# stack: scan third-barrier removed (double-buffered bonus slot), rotary table prefetch in odd in-proj epilogue, batched cumsum loads, redundant store waits removed in rwkv_prep
# speedup vs baseline: 1.0380x; 1.0099x over previous
.LBB0_549:
	v_lshl_add_u64 v[234:235], v[166:167], 0, s[44:45]
	global_load_dword v61, v[234:235], off
	s_waitcnt vmcnt(0)
	s_mov_b64 s[6:7], -1
	s_and_b64 vcc, exec, s[26:27]
	s_cbranch_vccz .LBB0_544

.LBB0_552:
	s_andn2_b64 vcc, exec, s[6:7]
	s_cbranch_vccnz .LBB0_554
	v_add_f32_e32 v63, v0, v61
	v_mul_f32_e32 v63, 0xbfb8aa3b, v63
	v_exp_f32_e32 v63, v63
	v_add_co_u32_e32 v234, vcc, 0x12c00000, v234
	v_add_f32_e32 v63, 1.0, v63
	v_rcp_f32_e32 v63, v63
	v_addc_co_u32_e32 v235, vcc, 0, v235, vcc
	v_cvt_pk_bf16_f32 v63, v63, s0
	global_store_short v[234:235], v63, off

.LBB0_555:
	s_nop 1
	v_add_f32_e32 v0, v0, v61
	v_mul_f32_e64 v63, |v0|, s52
	v_exp_f32_e32 v67, v63
	s_nop 0
	v_cmp_ngt_f32_e32 vcc, s55, v67
	s_and_saveexec_b64 s[0:1], vcc
	s_xor_b64 s[8:9], exec, s[0:1]
	s_cbranch_execz .LBB0_557
	v_add_f32_e32 v63, 1.0, v67
	v_cmp_gt_f32_e32 vcc, s56, v63
	s_nop 1
	v_cndmask_b32_e64 v67, 0, 32, vcc
	v_ldexp_f32 v63, v63, v67
	v_log_f32_e32 v63, v63
	s_nop 0
	v_mul_f32_e32 v67, 0x3f317217, v63
	v_fma_f32 v67, v63, s57, -v67
	v_fmac_f32_e32 v67, 0x3377d1cf, v63
	v_fmac_f32_e32 v67, 0x3f317217, v63
	v_cmp_lt_f32_e64 s[6:7], |v63|, s58
	s_nop 1
	v_cndmask_b32_e64 v63, v63, v67, s[6:7]
	v_cndmask_b32_e32 v67, 0, v238, vcc
	v_sub_f32_e32 v63, v63, v67

.LBB0_592:
	s_andn2_b64 vcc, exec, s[10:11]
	s_cbranch_vccnz .LBB0_594
	v_add_f32_e32 v0, v1, v61
	v_mul_f32_e32 v0, 0xbfb8aa3b, v0
	v_exp_f32_e32 v0, v0
	v_add_co_u32_e32 v234, vcc, 0x12c00000, v234
	v_add_f32_e32 v0, 1.0, v0
	v_rcp_f32_e32 v0, v0
	v_addc_co_u32_e32 v235, vcc, 0, v235, vcc
	v_cvt_pk_bf16_f32 v0, v0, s0
	global_store_short v[234:235], v0, off

.LBB0_595:
	v_add_f32_e32 v0, v1, v61
	v_mul_f32_e64 v1, |v0|, s52
	v_exp_f32_e32 v63, v1
	s_nop 0
	v_cmp_ngt_f32_e32 vcc, s55, v63
	s_and_saveexec_b64 s[0:1], vcc
	s_xor_b64 s[46:47], exec, s[0:1]
	s_cbranch_execz .LBB0_597
	v_add_f32_e32 v1, 1.0, v63
	v_cmp_gt_f32_e32 vcc, s56, v1
	s_nop 1
	v_cndmask_b32_e64 v63, 0, 32, vcc
	v_ldexp_f32 v1, v1, v63
	v_log_f32_e32 v1, v1
	s_nop 0
	v_mul_f32_e32 v63, 0x3f317217, v1
	v_fma_f32 v63, v1, s57, -v63
	v_fmac_f32_e32 v63, 0x3377d1cf, v1
	v_fmac_f32_e32 v63, 0x3f317217, v1
	v_cmp_lt_f32_e64 s[10:11], |v1|, s58
	s_nop 1
	v_cndmask_b32_e64 v1, v1, v63, s[10:11]
	v_cndmask_b32_e32 v63, 0, v238, vcc
	v_sub_f32_e32 v1, v1, v63

.LBB0_602:
	s_andn2_b64 vcc, exec, s[10:11]
	s_cbranch_vccnz .LBB0_604
	v_add_f32_e32 v63, v2, v61
	v_mul_f32_e32 v63, 0xbfb8aa3b, v63
	v_exp_f32_e32 v63, v63
	v_add_co_u32_e32 v0, vcc, 0x12c00000, v0
	v_add_f32_e32 v63, 1.0, v63
	v_rcp_f32_e32 v63, v63
	v_addc_co_u32_e32 v1, vcc, 0, v1, vcc
	v_cvt_pk_bf16_f32 v63, v63, s0
	global_store_short v[0:1], v63, off

.LBB0_605:
	v_add_f32_e32 v0, v2, v61
	v_mul_f32_e64 v1, |v0|, s52
	v_exp_f32_e32 v2, v1
	s_nop 0
	v_cmp_ngt_f32_e32 vcc, s55, v2
	s_and_saveexec_b64 s[0:1], vcc
	s_xor_b64 s[46:47], exec, s[0:1]
	s_cbranch_execz .LBB0_607
	v_add_f32_e32 v1, 1.0, v2
	v_cmp_gt_f32_e32 vcc, s56, v1
	s_nop 1
	v_cndmask_b32_e64 v2, 0, 32, vcc
	v_ldexp_f32 v1, v1, v2
	v_log_f32_e32 v1, v1
	s_nop 0
	v_mul_f32_e32 v2, 0x3f317217, v1
	v_fma_f32 v2, v1, s57, -v2
	v_fmac_f32_e32 v2, 0x3377d1cf, v1
	v_fmac_f32_e32 v2, 0x3f317217, v1
	v_cmp_lt_f32_e64 s[10:11], |v1|, s58
	s_nop 1
	v_cndmask_b32_e64 v1, v1, v2, s[10:11]
	v_cndmask_b32_e32 v2, 0, v238, vcc
	v_sub_f32_e32 v1, v1, v2

.LBB0_612:
	s_andn2_b64 vcc, exec, s[10:11]
	s_cbranch_vccnz .LBB0_614
	v_add_f32_e32 v2, v3, v61
	v_mul_f32_e32 v2, 0xbfb8aa3b, v2
	v_exp_f32_e32 v2, v2
	v_add_co_u32_e32 v0, vcc, 0x12c00000, v0
	v_add_f32_e32 v2, 1.0, v2
	v_rcp_f32_e32 v2, v2
	v_addc_co_u32_e32 v1, vcc, 0, v1, vcc
	v_cvt_pk_bf16_f32 v2, v2, s0
	global_store_short v[0:1], v2, off

.LBB0_615:
	v_add_f32_e32 v0, v3, v61
	v_mul_f32_e64 v1, |v0|, s52
	v_exp_f32_e32 v2, v1
	s_nop 0
	v_cmp_ngt_f32_e32 vcc, s55, v2
	s_and_saveexec_b64 s[0:1], vcc
	s_xor_b64 s[46:47], exec, s[0:1]
	s_cbranch_execz .LBB0_617
	v_add_f32_e32 v1, 1.0, v2
	v_cmp_gt_f32_e32 vcc, s56, v1
	s_nop 1
	v_cndmask_b32_e64 v2, 0, 32, vcc
	v_ldexp_f32 v1, v1, v2
	v_log_f32_e32 v1, v1
	s_nop 0
	v_mul_f32_e32 v2, 0x3f317217, v1
	v_fma_f32 v2, v1, s57, -v2
	v_fmac_f32_e32 v2, 0x3377d1cf, v1
	v_fmac_f32_e32 v2, 0x3f317217, v1
	v_cmp_lt_f32_e64 s[10:11], |v1|, s58
	s_nop 1
	v_cndmask_b32_e64 v1, v1, v2, s[10:11]
	v_cndmask_b32_e32 v2, 0, v238, vcc
	v_sub_f32_e32 v1, v1, v2

.LBB0_622:
	s_andn2_b64 vcc, exec, s[10:11]
	s_cbranch_vccnz .LBB0_624
	v_add_f32_e32 v2, v4, v61
	v_mul_f32_e32 v2, 0xbfb8aa3b, v2
	v_exp_f32_e32 v2, v2
	v_add_co_u32_e32 v0, vcc, 0x12c00000, v0
	v_add_f32_e32 v2, 1.0, v2
	v_rcp_f32_e32 v2, v2
	v_addc_co_u32_e32 v1, vcc, 0, v1, vcc
	v_cvt_pk_bf16_f32 v2, v2, s0
	global_store_short v[0:1], v2, off

.LBB0_625:
	v_add_f32_e32 v0, v4, v61
	v_mul_f32_e64 v1, |v0|, s52
	v_exp_f32_e32 v2, v1
	s_nop 0
	v_cmp_ngt_f32_e32 vcc, s55, v2
	s_and_saveexec_b64 s[0:1], vcc
	s_xor_b64 s[46:47], exec, s[0:1]
	s_cbranch_execz .LBB0_627
	v_add_f32_e32 v1, 1.0, v2
	v_cmp_gt_f32_e32 vcc, s56, v1
	s_nop 1
	v_cndmask_b32_e64 v2, 0, 32, vcc
	v_ldexp_f32 v1, v1, v2
	v_log_f32_e32 v1, v1
	s_nop 0
	v_mul_f32_e32 v2, 0x3f317217, v1
	v_fma_f32 v2, v1, s57, -v2
	v_fmac_f32_e32 v2, 0x3377d1cf, v1
	v_fmac_f32_e32 v2, 0x3f317217, v1
	v_cmp_lt_f32_e64 s[10:11], |v1|, s58
	s_nop 1
	v_cndmask_b32_e64 v1, v1, v2, s[10:11]
	v_cndmask_b32_e32 v2, 0, v238, vcc
	v_sub_f32_e32 v1, v1, v2

.LBB0_632:
	s_andn2_b64 vcc, exec, s[10:11]
	s_cbranch_vccnz .LBB0_634
	v_add_f32_e32 v2, v5, v61
	v_mul_f32_e32 v2, 0xbfb8aa3b, v2
	v_exp_f32_e32 v2, v2
	v_add_co_u32_e32 v0, vcc, 0x12c00000, v0
	v_add_f32_e32 v2, 1.0, v2
	v_rcp_f32_e32 v2, v2
	v_addc_co_u32_e32 v1, vcc, 0, v1, vcc
	v_cvt_pk_bf16_f32 v2, v2, s0
	global_store_short v[0:1], v2, off

.LBB0_635:
	v_add_f32_e32 v0, v5, v61
	v_mul_f32_e64 v1, |v0|, s52
	v_exp_f32_e32 v2, v1
	s_nop 0
	v_cmp_ngt_f32_e32 vcc, s55, v2
	s_and_saveexec_b64 s[0:1], vcc
	s_xor_b64 s[46:47], exec, s[0:1]
	s_cbranch_execz .LBB0_637
	v_add_f32_e32 v1, 1.0, v2
	v_cmp_gt_f32_e32 vcc, s56, v1
	s_nop 1
	v_cndmask_b32_e64 v2, 0, 32, vcc
	v_ldexp_f32 v1, v1, v2
	v_log_f32_e32 v1, v1
	s_nop 0
	v_mul_f32_e32 v2, 0x3f317217, v1
	v_fma_f32 v2, v1, s57, -v2
	v_fmac_f32_e32 v2, 0x3377d1cf, v1
	v_fmac_f32_e32 v2, 0x3f317217, v1
	v_cmp_lt_f32_e64 s[10:11], |v1|, s58
	s_nop 1
	v_cndmask_b32_e64 v1, v1, v2, s[10:11]
	v_cndmask_b32_e32 v2, 0, v238, vcc
	v_sub_f32_e32 v1, v1, v2

.LBB0_642:
	s_andn2_b64 vcc, exec, s[10:11]
	s_cbranch_vccnz .LBB0_644
	v_add_f32_e32 v2, v6, v61
	v_mul_f32_e32 v2, 0xbfb8aa3b, v2
	v_exp_f32_e32 v2, v2
	v_add_co_u32_e32 v0, vcc, 0x12c00000, v0
	v_add_f32_e32 v2, 1.0, v2
	v_rcp_f32_e32 v2, v2
	v_addc_co_u32_e32 v1, vcc, 0, v1, vcc
	v_cvt_pk_bf16_f32 v2, v2, s0
	global_store_short v[0:1], v2, off

.LBB0_645:
	v_add_f32_e32 v0, v6, v61
	v_mul_f32_e64 v1, |v0|, s52
	v_exp_f32_e32 v2, v1
	s_nop 0
	v_cmp_ngt_f32_e32 vcc, s55, v2
	s_and_saveexec_b64 s[0:1], vcc
	s_xor_b64 s[46:47], exec, s[0:1]
	s_cbranch_execz .LBB0_647
	v_add_f32_e32 v1, 1.0, v2
	v_cmp_gt_f32_e32 vcc, s56, v1
	s_nop 1
	v_cndmask_b32_e64 v2, 0, 32, vcc
	v_ldexp_f32 v1, v1, v2
	v_log_f32_e32 v1, v1
	s_nop 0
	v_mul_f32_e32 v2, 0x3f317217, v1
	v_fma_f32 v2, v1, s57, -v2
	v_fmac_f32_e32 v2, 0x3377d1cf, v1
	v_fmac_f32_e32 v2, 0x3f317217, v1
	v_cmp_lt_f32_e64 s[10:11], |v1|, s58
	s_nop 1
	v_cndmask_b32_e64 v1, v1, v2, s[10:11]
	v_cndmask_b32_e32 v2, 0, v238, vcc
	v_sub_f32_e32 v1, v1, v2

.LBB0_652:
	s_andn2_b64 vcc, exec, s[10:11]
	s_cbranch_vccnz .LBB0_654
	v_add_f32_e32 v2, v7, v61
	v_mul_f32_e32 v2, 0xbfb8aa3b, v2
	v_exp_f32_e32 v2, v2
	v_add_co_u32_e32 v0, vcc, 0x12c00000, v0
	v_add_f32_e32 v2, 1.0, v2
	v_rcp_f32_e32 v2, v2
	v_addc_co_u32_e32 v1, vcc, 0, v1, vcc
	v_cvt_pk_bf16_f32 v2, v2, s0
	global_store_short v[0:1], v2, off

.LBB0_655:
	v_add_f32_e32 v0, v7, v61
	v_mul_f32_e64 v1, |v0|, s52
	v_exp_f32_e32 v2, v1
	s_nop 0
	v_cmp_ngt_f32_e32 vcc, s55, v2
	s_and_saveexec_b64 s[0:1], vcc
	s_xor_b64 s[46:47], exec, s[0:1]
	s_cbranch_execz .LBB0_657
	v_add_f32_e32 v1, 1.0, v2
	v_cmp_gt_f32_e32 vcc, s56, v1
	s_nop 1
	v_cndmask_b32_e64 v2, 0, 32, vcc
	v_ldexp_f32 v1, v1, v2
	v_log_f32_e32 v1, v1
	s_nop 0
	v_mul_f32_e32 v2, 0x3f317217, v1
	v_fma_f32 v2, v1, s57, -v2
	v_fmac_f32_e32 v2, 0x3377d1cf, v1
	v_fmac_f32_e32 v2, 0x3f317217, v1
	v_cmp_lt_f32_e64 s[10:11], |v1|, s58
	s_nop 1
	v_cndmask_b32_e64 v1, v1, v2, s[10:11]
	v_cndmask_b32_e32 v2, 0, v238, vcc
	v_sub_f32_e32 v1, v1, v2

.LBB0_662:
	s_andn2_b64 vcc, exec, s[10:11]
	s_cbranch_vccnz .LBB0_664
	v_add_f32_e32 v2, v8, v61
	v_mul_f32_e32 v2, 0xbfb8aa3b, v2
	v_exp_f32_e32 v2, v2
	v_add_co_u32_e32 v0, vcc, 0x12c00000, v0
	v_add_f32_e32 v2, 1.0, v2
	v_rcp_f32_e32 v2, v2
	v_addc_co_u32_e32 v1, vcc, 0, v1, vcc
	v_cvt_pk_bf16_f32 v2, v2, s0
	global_store_short v[0:1], v2, off

.LBB0_665:
	v_add_f32_e32 v0, v8, v61
	v_mul_f32_e64 v1, |v0|, s52
	v_exp_f32_e32 v2, v1
	s_nop 0
	v_cmp_ngt_f32_e32 vcc, s55, v2
	s_and_saveexec_b64 s[0:1], vcc
	s_xor_b64 s[46:47], exec, s[0:1]
	s_cbranch_execz .LBB0_667
	v_add_f32_e32 v1, 1.0, v2
	v_cmp_gt_f32_e32 vcc, s56, v1
	s_nop 1
	v_cndmask_b32_e64 v2, 0, 32, vcc
	v_ldexp_f32 v1, v1, v2
	v_log_f32_e32 v1, v1
	s_nop 0
	v_mul_f32_e32 v2, 0x3f317217, v1
	v_fma_f32 v2, v1, s57, -v2
	v_fmac_f32_e32 v2, 0x3377d1cf, v1
	v_fmac_f32_e32 v2, 0x3f317217, v1
	v_cmp_lt_f32_e64 s[10:11], |v1|, s58
	s_nop 1
	v_cndmask_b32_e64 v1, v1, v2, s[10:11]
	v_cndmask_b32_e32 v2, 0, v238, vcc
	v_sub_f32_e32 v1, v1, v2

.LBB0_672:
	s_andn2_b64 vcc, exec, s[10:11]
	s_cbranch_vccnz .LBB0_674
	v_add_f32_e32 v2, v9, v61
	v_mul_f32_e32 v2, 0xbfb8aa3b, v2
	v_exp_f32_e32 v2, v2
	v_add_co_u32_e32 v0, vcc, 0x12c00000, v0
	v_add_f32_e32 v2, 1.0, v2
	v_rcp_f32_e32 v2, v2
	v_addc_co_u32_e32 v1, vcc, 0, v1, vcc
	v_cvt_pk_bf16_f32 v2, v2, s0
	global_store_short v[0:1], v2, off

.LBB0_675:
	v_add_f32_e32 v0, v9, v61
	v_mul_f32_e64 v1, |v0|, s52
	v_exp_f32_e32 v2, v1
	s_nop 0
	v_cmp_ngt_f32_e32 vcc, s55, v2
	s_and_saveexec_b64 s[0:1], vcc
	s_xor_b64 s[46:47], exec, s[0:1]
	s_cbranch_execz .LBB0_677
	v_add_f32_e32 v1, 1.0, v2
	v_cmp_gt_f32_e32 vcc, s56, v1
	s_nop 1
	v_cndmask_b32_e64 v2, 0, 32, vcc
	v_ldexp_f32 v1, v1, v2
	v_log_f32_e32 v1, v1
	s_nop 0
	v_mul_f32_e32 v2, 0x3f317217, v1
	v_fma_f32 v2, v1, s57, -v2
	v_fmac_f32_e32 v2, 0x3377d1cf, v1
	v_fmac_f32_e32 v2, 0x3f317217, v1
	v_cmp_lt_f32_e64 s[10:11], |v1|, s58
	s_nop 1
	v_cndmask_b32_e64 v1, v1, v2, s[10:11]
	v_cndmask_b32_e32 v2, 0, v238, vcc
	v_sub_f32_e32 v1, v1, v2

.LBB0_682:
	s_andn2_b64 vcc, exec, s[10:11]
	s_cbranch_vccnz .LBB0_684
	v_add_f32_e32 v2, v10, v61
	v_mul_f32_e32 v2, 0xbfb8aa3b, v2
	v_exp_f32_e32 v2, v2
	v_add_co_u32_e32 v0, vcc, 0x12c00000, v0
	v_add_f32_e32 v2, 1.0, v2
	v_rcp_f32_e32 v2, v2
	v_addc_co_u32_e32 v1, vcc, 0, v1, vcc
	v_cvt_pk_bf16_f32 v2, v2, s0
	global_store_short v[0:1], v2, off

.LBB0_685:
	v_add_f32_e32 v0, v10, v61
	v_mul_f32_e64 v1, |v0|, s52
	v_exp_f32_e32 v2, v1
	s_nop 0
	v_cmp_ngt_f32_e32 vcc, s55, v2
	s_and_saveexec_b64 s[0:1], vcc
	s_xor_b64 s[46:47], exec, s[0:1]
	s_cbranch_execz .LBB0_687
	v_add_f32_e32 v1, 1.0, v2
	v_cmp_gt_f32_e32 vcc, s56, v1
	s_nop 1
	v_cndmask_b32_e64 v2, 0, 32, vcc
	v_ldexp_f32 v1, v1, v2
	v_log_f32_e32 v1, v1
	s_nop 0
	v_mul_f32_e32 v2, 0x3f317217, v1
	v_fma_f32 v2, v1, s57, -v2
	v_fmac_f32_e32 v2, 0x3377d1cf, v1
	v_fmac_f32_e32 v2, 0x3f317217, v1
	v_cmp_lt_f32_e64 s[10:11], |v1|, s58
	s_nop 1
	v_cndmask_b32_e64 v1, v1, v2, s[10:11]
	v_cndmask_b32_e32 v2, 0, v238, vcc
	v_sub_f32_e32 v1, v1, v2

.LBB0_692:
	s_andn2_b64 vcc, exec, s[10:11]
	s_cbranch_vccnz .LBB0_694
	v_add_f32_e32 v2, v11, v61
	v_mul_f32_e32 v2, 0xbfb8aa3b, v2
	v_exp_f32_e32 v2, v2
	v_add_co_u32_e32 v0, vcc, 0x12c00000, v0
	v_add_f32_e32 v2, 1.0, v2
	v_rcp_f32_e32 v2, v2
	v_addc_co_u32_e32 v1, vcc, 0, v1, vcc
	v_cvt_pk_bf16_f32 v2, v2, s0
	global_store_short v[0:1], v2, off

.LBB0_695:
	v_add_f32_e32 v0, v11, v61
	v_mul_f32_e64 v1, |v0|, s52
	v_exp_f32_e32 v2, v1
	s_nop 0
	v_cmp_ngt_f32_e32 vcc, s55, v2
	s_and_saveexec_b64 s[0:1], vcc
	s_xor_b64 s[46:47], exec, s[0:1]
	s_cbranch_execz .LBB0_697
	v_add_f32_e32 v1, 1.0, v2
	v_cmp_gt_f32_e32 vcc, s56, v1
	s_nop 1
	v_cndmask_b32_e64 v2, 0, 32, vcc
	v_ldexp_f32 v1, v1, v2
	v_log_f32_e32 v1, v1
	s_nop 0
	v_mul_f32_e32 v2, 0x3f317217, v1
	v_fma_f32 v2, v1, s57, -v2
	v_fmac_f32_e32 v2, 0x3377d1cf, v1
	v_fmac_f32_e32 v2, 0x3f317217, v1
	v_cmp_lt_f32_e64 s[10:11], |v1|, s58
	s_nop 1
	v_cndmask_b32_e64 v1, v1, v2, s[10:11]
	v_cndmask_b32_e32 v2, 0, v238, vcc
	v_sub_f32_e32 v1, v1, v2

.LBB0_702:
	s_andn2_b64 vcc, exec, s[10:11]
	s_cbranch_vccnz .LBB0_704
	v_add_f32_e32 v2, v12, v61
	v_mul_f32_e32 v2, 0xbfb8aa3b, v2
	v_exp_f32_e32 v2, v2
	v_add_co_u32_e32 v0, vcc, 0x12c00000, v0
	v_add_f32_e32 v2, 1.0, v2
	v_rcp_f32_e32 v2, v2
	v_addc_co_u32_e32 v1, vcc, 0, v1, vcc
	v_cvt_pk_bf16_f32 v2, v2, s0
	global_store_short v[0:1], v2, off

.LBB0_705:
	v_add_f32_e32 v0, v12, v61
	v_mul_f32_e64 v1, |v0|, s52
	v_exp_f32_e32 v2, v1
	s_nop 0
	v_cmp_ngt_f32_e32 vcc, s55, v2
	s_and_saveexec_b64 s[0:1], vcc
	s_xor_b64 s[46:47], exec, s[0:1]
	s_cbranch_execz .LBB0_707
	v_add_f32_e32 v1, 1.0, v2
	v_cmp_gt_f32_e32 vcc, s56, v1
	s_nop 1
	v_cndmask_b32_e64 v2, 0, 32, vcc
	v_ldexp_f32 v1, v1, v2
	v_log_f32_e32 v1, v1
	s_nop 0
	v_mul_f32_e32 v2, 0x3f317217, v1
	v_fma_f32 v2, v1, s57, -v2
	v_fmac_f32_e32 v2, 0x3377d1cf, v1
	v_fmac_f32_e32 v2, 0x3f317217, v1
	v_cmp_lt_f32_e64 s[10:11], |v1|, s58
	s_nop 1
	v_cndmask_b32_e64 v1, v1, v2, s[10:11]
	v_cndmask_b32_e32 v2, 0, v238, vcc
	v_sub_f32_e32 v1, v1, v2

.LBB0_712:
	s_andn2_b64 vcc, exec, s[10:11]
	s_cbranch_vccnz .LBB0_714
	v_add_f32_e32 v2, v13, v61
	v_mul_f32_e32 v2, 0xbfb8aa3b, v2
	v_exp_f32_e32 v2, v2
	v_add_co_u32_e32 v0, vcc, 0x12c00000, v0
	v_add_f32_e32 v2, 1.0, v2
	v_rcp_f32_e32 v2, v2
	v_addc_co_u32_e32 v1, vcc, 0, v1, vcc
	v_cvt_pk_bf16_f32 v2, v2, s0
	global_store_short v[0:1], v2, off

.LBB0_715:
	v_add_f32_e32 v0, v13, v61
	v_mul_f32_e64 v1, |v0|, s52
	v_exp_f32_e32 v2, v1
	s_nop 0
	v_cmp_ngt_f32_e32 vcc, s55, v2
	s_and_saveexec_b64 s[0:1], vcc
	s_xor_b64 s[46:47], exec, s[0:1]
	s_cbranch_execz .LBB0_717
	v_add_f32_e32 v1, 1.0, v2
	v_cmp_gt_f32_e32 vcc, s56, v1
	s_nop 1
	v_cndmask_b32_e64 v2, 0, 32, vcc
	v_ldexp_f32 v1, v1, v2
	v_log_f32_e32 v1, v1
	s_nop 0
	v_mul_f32_e32 v2, 0x3f317217, v1
	v_fma_f32 v2, v1, s57, -v2
	v_fmac_f32_e32 v2, 0x3377d1cf, v1
	v_fmac_f32_e32 v2, 0x3f317217, v1
	v_cmp_lt_f32_e64 s[10:11], |v1|, s58
	s_nop 1
	v_cndmask_b32_e64 v1, v1, v2, s[10:11]
	v_cndmask_b32_e32 v2, 0, v238, vcc
	v_sub_f32_e32 v1, v1, v2

.LBB0_722:
	s_andn2_b64 vcc, exec, s[10:11]
	s_cbranch_vccnz .LBB0_724
	v_add_f32_e32 v2, v14, v61
	v_mul_f32_e32 v2, 0xbfb8aa3b, v2
	v_exp_f32_e32 v2, v2
	v_add_co_u32_e32 v0, vcc, 0x12c00000, v0
	v_add_f32_e32 v2, 1.0, v2
	v_rcp_f32_e32 v2, v2
	v_addc_co_u32_e32 v1, vcc, 0, v1, vcc
	v_cvt_pk_bf16_f32 v2, v2, s0
	global_store_short v[0:1], v2, off

.LBB0_725:
	v_add_f32_e32 v0, v14, v61
	v_mul_f32_e64 v1, |v0|, s52
	v_exp_f32_e32 v2, v1
	s_nop 0
	v_cmp_ngt_f32_e32 vcc, s55, v2
	s_and_saveexec_b64 s[0:1], vcc
	s_xor_b64 s[46:47], exec, s[0:1]
	s_cbranch_execz .LBB0_727
	v_add_f32_e32 v1, 1.0, v2
	v_cmp_gt_f32_e32 vcc, s56, v1
	s_nop 1
	v_cndmask_b32_e64 v2, 0, 32, vcc
	v_ldexp_f32 v1, v1, v2
	v_log_f32_e32 v1, v1
	s_nop 0
	v_mul_f32_e32 v2, 0x3f317217, v1
	v_fma_f32 v2, v1, s57, -v2
	v_fmac_f32_e32 v2, 0x3377d1cf, v1
	v_fmac_f32_e32 v2, 0x3f317217, v1
	v_cmp_lt_f32_e64 s[10:11], |v1|, s58
	s_nop 1
	v_cndmask_b32_e64 v1, v1, v2, s[10:11]
	v_cndmask_b32_e32 v2, 0, v238, vcc
	v_sub_f32_e32 v1, v1, v2

.LBB0_732:
	s_andn2_b64 vcc, exec, s[8:9]
	s_cbranch_vccnz .LBB0_734
	v_add_f32_e32 v2, v15, v61
	v_mul_f32_e32 v2, 0xbfb8aa3b, v2
	v_exp_f32_e32 v2, v2
	v_add_co_u32_e32 v0, vcc, 0x12c00000, v0
	v_add_f32_e32 v2, 1.0, v2
	v_rcp_f32_e32 v2, v2
	v_addc_co_u32_e32 v1, vcc, 0, v1, vcc
	v_cvt_pk_bf16_f32 v2, v2, s0
	global_store_short v[0:1], v2, off

.LBB0_735:
	v_add_f32_e32 v0, v15, v61
	v_mul_f32_e64 v1, |v0|, s52
	v_exp_f32_e32 v2, v1
	s_nop 0
	v_cmp_ngt_f32_e32 vcc, s55, v2
	s_and_saveexec_b64 s[0:1], vcc
	s_xor_b64 s[8:9], exec, s[0:1]
	s_cbranch_execz .LBB0_737
	v_add_f32_e32 v1, 1.0, v2
	v_cmp_gt_f32_e32 vcc, s56, v1
	s_nop 1
	v_cndmask_b32_e64 v2, 0, 32, vcc
	v_ldexp_f32 v1, v1, v2
	v_log_f32_e32 v1, v1
	s_nop 0
	v_mul_f32_e32 v2, 0x3f317217, v1
	v_fma_f32 v2, v1, s57, -v2
	v_fmac_f32_e32 v2, 0x3377d1cf, v1
	v_fmac_f32_e32 v2, 0x3f317217, v1
	v_cmp_lt_f32_e64 s[6:7], |v1|, s58
	s_nop 1
	v_cndmask_b32_e64 v1, v1, v2, s[6:7]
	v_cndmask_b32_e32 v2, 0, v238, vcc
	v_sub_f32_e32 v1, v1, v2

.LBB0_739:
	s_cmp_lt_i32 s2, 8
	s_cselect_b64 s[0:1], -1, 0
	v_writelane_b32 v248, s0, 6
	s_cmp_gt_i32 s2, 7
	s_nop 0
	v_writelane_b32 v248, s1, 7
	s_mul_hi_i32 s0, s2, 0x3440000
	v_writelane_b32 v248, s0, 8
	s_mul_i32 s0, s2, 0x3440000
	v_writelane_b32 v248, s0, 9
	s_cbranch_scc1 .LBB0_883
	s_load_dwordx2 s[0:1], s[18:19], 0x38
	v_mov_b32_e32 v20, 0
	s_ashr_i32 s3, s2, 31
	s_movk_i32 s4, 0x1a20
	s_mov_b64 s[6:7], 0
	s_waitcnt lgkmcnt(0)
	global_load_dwordx4 v[0:3], v20, s[0:1]
	global_load_dwordx4 v[4:7], v20, s[0:1] offset:16
	s_lshl_b32 s0, s35, 10
	v_lshl_add_u32 v18, v65, 4, s0
	v_readlane_b32 s0, v248, 9
	s_add_u32 s0, s16, s0
	v_readlane_b32 s1, v248, 8
	s_addc_u32 s1, s17, s1
	v_ashrrev_i32_e32 v19, 31, v18
	v_mov_b64_e32 v[8:9], s[0:1]
	v_mad_i64_i32 v[8:9], s[0:1], v18, s4, v[8:9]
	s_mov_b64 s[0:1], 0x22c01a00
	s_nop 0
	v_lshl_add_u64 v[16:17], v[8:9], 0, s[0:1]
	s_mov_b32 s0, 0xbfb8aa3b
	s_mov_b32 s1, 0x3c23d70a
	s_mov_b32 s10, 0x800000
	s_mov_b32 s11, 0x3f317217
	s_mov_b32 s12, 0x7f800000
	s_mov_b32 s13, 0xbeaaaaab
	v_mov_b32_e32 v12, 0x41b17218
	v_mov_b32_e32 v21, v20
	v_mov_b32_e32 v26, v20
	v_mov_b32_e32 v27, v20
	v_mov_b32_e32 v24, v20
	v_mov_b32_e32 v25, v20
	v_mov_b32_e32 v22, v20
	v_mov_b32_e32 v23, v20
	s_mov_b64 s[100:101], 0x1a20
	v_mov_b64_e32 v[164:165], v[16:17]
	global_load_dwordx4 v[100:103], v[164:165], off
	v_lshl_add_u64 v[164:165], v[164:165], 0, s[100:101]
	global_load_dwordx4 v[104:107], v[164:165], off
	v_lshl_add_u64 v[164:165], v[164:165], 0, s[100:101]
	global_load_dwordx4 v[108:111], v[164:165], off
	v_lshl_add_u64 v[164:165], v[164:165], 0, s[100:101]
	global_load_dwordx4 v[112:115], v[164:165], off
	v_lshl_add_u64 v[164:165], v[164:165], 0, s[100:101]
	global_load_dwordx4 v[116:119], v[164:165], off
	v_lshl_add_u64 v[164:165], v[164:165], 0, s[100:101]
	global_load_dwordx4 v[120:123], v[164:165], off
	v_lshl_add_u64 v[164:165], v[164:165], 0, s[100:101]
	global_load_dwordx4 v[124:127], v[164:165], off
	v_lshl_add_u64 v[164:165], v[164:165], 0, s[100:101]
	global_load_dwordx4 v[128:131], v[164:165], off
	v_lshl_add_u64 v[164:165], v[164:165], 0, s[100:101]
	global_load_dwordx4 v[132:135], v[164:165], off
	v_lshl_add_u64 v[164:165], v[164:165], 0, s[100:101]
	global_load_dwordx4 v[136:139], v[164:165], off
	v_lshl_add_u64 v[164:165], v[164:165], 0, s[100:101]
	global_load_dwordx4 v[140:143], v[164:165], off
	v_lshl_add_u64 v[164:165], v[164:165], 0, s[100:101]
	global_load_dwordx4 v[144:147], v[164:165], off
	v_lshl_add_u64 v[164:165], v[164:165], 0, s[100:101]
	global_load_dwordx4 v[148:151], v[164:165], off
	v_lshl_add_u64 v[164:165], v[164:165], 0, s[100:101]
	global_load_dwordx4 v[152:155], v[164:165], off
	v_lshl_add_u64 v[164:165], v[164:165], 0, s[100:101]
	global_load_dwordx4 v[156:159], v[164:165], off
	v_lshl_add_u64 v[164:165], v[164:165], 0, s[100:101]
	global_load_dwordx4 v[160:163], v[164:165], off
	s_waitcnt vmcnt(0)
	s_branch .LBB0_742

.LBB0_742:
	v_mov_b64_e32 v[8:9], v[100:101]
	v_mov_b64_e32 v[10:11], v[102:103]
	v_mov_b64_e32 v[164:165], v[100:101]
	v_mov_b64_e32 v[166:167], v[102:103]
	v_mov_b64_e32 v[100:101], v[104:105]
	v_mov_b64_e32 v[102:103], v[106:107]
	v_mov_b64_e32 v[104:105], v[108:109]
	v_mov_b64_e32 v[106:107], v[110:111]
	v_mov_b64_e32 v[108:109], v[112:113]
	v_mov_b64_e32 v[110:111], v[114:115]
	v_mov_b64_e32 v[112:113], v[116:117]
	v_mov_b64_e32 v[114:115], v[118:119]
	v_mov_b64_e32 v[116:117], v[120:121]
	v_mov_b64_e32 v[118:119], v[122:123]
	v_mov_b64_e32 v[120:121], v[124:125]
	v_mov_b64_e32 v[122:123], v[126:127]
	v_mov_b64_e32 v[124:125], v[128:129]
	v_mov_b64_e32 v[126:127], v[130:131]
	v_mov_b64_e32 v[128:129], v[132:133]
	v_mov_b64_e32 v[130:131], v[134:135]
	v_mov_b64_e32 v[132:133], v[136:137]
	v_mov_b64_e32 v[134:135], v[138:139]
	v_mov_b64_e32 v[136:137], v[140:141]
	v_mov_b64_e32 v[138:139], v[142:143]
	v_mov_b64_e32 v[140:141], v[144:145]
	v_mov_b64_e32 v[142:143], v[146:147]
	v_mov_b64_e32 v[144:145], v[148:149]
	v_mov_b64_e32 v[146:147], v[150:151]
	v_mov_b64_e32 v[148:149], v[152:153]
	v_mov_b64_e32 v[150:151], v[154:155]
	v_mov_b64_e32 v[152:153], v[156:157]
	v_mov_b64_e32 v[154:155], v[158:159]
	v_mov_b64_e32 v[156:157], v[160:161]
	v_mov_b64_e32 v[158:159], v[162:163]
	v_mov_b64_e32 v[160:161], v[164:165]
	v_mov_b64_e32 v[162:163], v[166:167]
	v_lshlrev_b32_e32 v13, 16, v8
	v_add_f32_e32 v13, v0, v13
	v_mul_f32_e64 v14, |v13|, s0
	v_exp_f32_e32 v15, v14
	s_nop 0
	v_cmp_ngt_f32_e32 vcc, s1, v15
	s_and_saveexec_b64 s[4:5], vcc
	s_xor_b64 s[8:9], exec, s[4:5]
	s_cbranch_execz .LBB0_744
	v_add_f32_e32 v14, 1.0, v15
	v_cmp_gt_f32_e32 vcc, s10, v14
	s_nop 1
	v_cndmask_b32_e64 v15, 0, 32, vcc
	v_ldexp_f32 v14, v14, v15
	v_log_f32_e32 v14, v14
	s_nop 0
	v_mul_f32_e32 v15, 0x3f317217, v14
	v_fma_f32 v15, v14, s11, -v15
	v_fmac_f32_e32 v15, 0x3377d1cf, v14
	v_fmac_f32_e32 v15, 0x3f317217, v14
	v_cmp_lt_f32_e64 s[4:5], |v14|, s12
	s_nop 1
	v_cndmask_b32_e64 v14, v14, v15, s[4:5]
	v_cndmask_b32_e32 v15, 0, v12, vcc
	v_sub_f32_e32 v14, v14, v15

.LBB0_850:
	v_mov_b64_e32 v[8:9], v[100:101]
	v_mov_b64_e32 v[10:11], v[102:103]
	v_mov_b64_e32 v[164:165], v[100:101]
	v_mov_b64_e32 v[166:167], v[102:103]
	v_mov_b64_e32 v[100:101], v[104:105]
	v_mov_b64_e32 v[102:103], v[106:107]
	v_mov_b64_e32 v[104:105], v[108:109]
	v_mov_b64_e32 v[106:107], v[110:111]
	v_mov_b64_e32 v[108:109], v[112:113]
	v_mov_b64_e32 v[110:111], v[114:115]
	v_mov_b64_e32 v[112:113], v[116:117]
	v_mov_b64_e32 v[114:115], v[118:119]
	v_mov_b64_e32 v[116:117], v[120:121]
	v_mov_b64_e32 v[118:119], v[122:123]
	v_mov_b64_e32 v[120:121], v[124:125]
	v_mov_b64_e32 v[122:123], v[126:127]
	v_mov_b64_e32 v[124:125], v[128:129]
	v_mov_b64_e32 v[126:127], v[130:131]
	v_mov_b64_e32 v[128:129], v[132:133]
	v_mov_b64_e32 v[130:131], v[134:135]
	v_mov_b64_e32 v[132:133], v[136:137]
	v_mov_b64_e32 v[134:135], v[138:139]
	v_mov_b64_e32 v[136:137], v[140:141]
	v_mov_b64_e32 v[138:139], v[142:143]
	v_mov_b64_e32 v[140:141], v[144:145]
	v_mov_b64_e32 v[142:143], v[146:147]
	v_mov_b64_e32 v[144:145], v[148:149]
	v_mov_b64_e32 v[146:147], v[150:151]
	v_mov_b64_e32 v[148:149], v[152:153]
	v_mov_b64_e32 v[150:151], v[154:155]
	v_mov_b64_e32 v[152:153], v[156:157]
	v_mov_b64_e32 v[154:155], v[158:159]
	v_mov_b64_e32 v[156:157], v[160:161]
	v_mov_b64_e32 v[158:159], v[162:163]
	v_mov_b64_e32 v[160:161], v[164:165]
	v_mov_b64_e32 v[162:163], v[166:167]
	v_lshlrev_b32_e32 v25, 16, v8
	v_add_f32_e32 v25, v0, v25
	v_mul_f32_e64 v26, |v25|, s0
	v_exp_f32_e32 v27, v26
	s_nop 0
	v_cmp_ngt_f32_e32 vcc, s1, v27
	s_and_saveexec_b64 s[4:5], vcc
	s_xor_b64 s[10:11], exec, s[4:5]
	s_cbranch_execz .LBB0_852
	v_add_f32_e32 v26, 1.0, v27
	v_cmp_gt_f32_e32 vcc, s3, v26
	s_nop 1
	v_cndmask_b32_e64 v27, 0, 32, vcc
	v_ldexp_f32 v26, v26, v27
	v_log_f32_e32 v26, v26
	s_nop 0
	v_mul_f32_e32 v27, 0x3f317217, v26
	v_fma_f32 v27, v26, s9, -v27
	v_fmac_f32_e32 v27, 0x3377d1cf, v26
	v_fmac_f32_e32 v27, 0x3f317217, v26
	v_cmp_lt_f32_e64 s[4:5], |v26|, s12
	s_nop 1
	v_cndmask_b32_e64 v26, v26, v27, s[4:5]
	v_cndmask_b32_e32 v27, 0, v24, vcc
	v_sub_f32_e32 v26, v26, v27

.LBB0_978:
	s_or_b64 exec, exec, s[24:25]
	s_cmpk_eq_i32 s49, 0x100
	s_mov_b32 s48, s49
	s_cbranch_scc1 .LBB0_938
.LBB0_979:
	s_waitcnt vmcnt(4)
	v_lshlrev_b32_e32 v30, 16, v50
	v_and_b32_e32 v31, 0xffff0000, v50
	v_lshlrev_b32_e32 v32, 16, v51
	v_and_b32_e32 v33, 0xffff0000, v51
	v_lshlrev_b32_e32 v1, 16, v56
	v_and_b32_e32 v34, 0xffff0000, v56
	v_lshlrev_b32_e32 v46, 16, v57
	v_and_b32_e32 v35, 0xffff0000, v57
	s_waitcnt vmcnt(3)
	v_lshlrev_b32_e32 v36, 16, v52
	v_and_b32_e32 v37, 0xffff0000, v52
	v_lshlrev_b32_e32 v38, 16, v53
	v_and_b32_e32 v39, 0xffff0000, v53
	v_lshlrev_b32_e32 v47, 16, v58
	v_and_b32_e32 v84, 0xffff0000, v58
	v_lshlrev_b32_e32 v85, 16, v59
	v_and_b32_e32 v86, 0xffff0000, v59
	v_sub_f32_e32 v45, v34, v31
	v_sub_f32_e32 v44, v1, v30
	v_sub_f32_e32 v35, v35, v33
	v_sub_f32_e32 v34, v46, v32
	v_pk_fma_f32 v[34:35], v[4:5], v[34:35], v[32:33]
	v_pk_fma_f32 v[32:33], v[2:3], v[44:45], v[30:31]
	v_sub_f32_e32 v31, v84, v37
	v_sub_f32_e32 v30, v47, v36
	v_sub_f32_e32 v45, v86, v39
	v_sub_f32_e32 v44, v85, v38
	s_waitcnt vmcnt(2)
	v_lshlrev_b32_e32 v40, 16, v54
	v_and_b32_e32 v41, 0xffff0000, v54
	v_lshlrev_b32_e32 v42, 16, v55
	v_and_b32_e32 v43, 0xffff0000, v55
	v_lshlrev_b32_e32 v87, 16, v60
	v_and_b32_e32 v88, 0xffff0000, v60
	v_lshlrev_b32_e32 v89, 16, v61
	v_and_b32_e32 v90, 0xffff0000, v61
	v_pk_fma_f32 v[44:45], v[8:9], v[44:45], v[38:39]
	v_pk_fma_f32 v[30:31], v[6:7], v[30:31], v[36:37]
	v_sub_f32_e32 v37, v88, v41
	v_sub_f32_e32 v36, v87, v40
	v_sub_f32_e32 v39, v90, v43
	v_sub_f32_e32 v38, v89, v42
	v_pk_mul_f32 v[84:85], v[14:15], v[30:31]
	v_pk_mul_f32 v[86:87], v[16:17], v[44:45]
	v_pk_fma_f32 v[38:39], v[12:13], v[38:39], v[42:43]
	v_pk_fma_f32 v[36:37], v[10:11], v[36:37], v[40:41]
	v_pk_mul_f32 v[40:41], v[86:87], v[86:87]
	v_pk_mul_f32 v[42:43], v[84:85], v[84:85]
	s_waitcnt vmcnt(1)
	v_lshlrev_b32_e32 v48, 16, v70
	v_pk_mov_b32 v[46:47], v[42:43], v[40:41] op_sel:[1,0]
	v_mov_b32_e32 v43, v41
	v_pk_add_f32 v[40:41], v[46:47], v[42:43]
	v_and_b32_e32 v49, 0xffff0000, v70
	v_lshlrev_b32_e32 v80, 16, v71
	v_and_b32_e32 v81, 0xffff0000, v71
	v_add_f32_e32 v1, v40, v41
	v_pk_add_f32 v[40:41], v[80:81], -1.0 op_sel_hi:[1,0]
	v_pk_add_f32 v[42:43], v[48:49], -1.0 op_sel_hi:[1,0]
	v_add_f32_dpp v1, v1, v1 quad_perm:[1,0,3,2] row_mask:0xf bank_mask:0xf bound_ctrl:1
	v_pk_fma_f32 v[46:47], v[18:19], v[42:43], 1.0 op_sel_hi:[1,1,0]
	v_pk_fma_f32 v[40:41], v[20:21], v[40:41], 1.0 op_sel_hi:[1,1,0]
	v_add_f32_dpp v1, v1, v1 quad_perm:[2,3,0,1] row_mask:0xf bank_mask:0xf bound_ctrl:1
	v_pk_mul_f32 v[42:43], v[44:45], v[40:41]
	v_pk_mul_f32 v[40:41], v[30:31], v[46:47]
	v_add_f32_dpp v1, v1, v1 row_half_mirror row_mask:0xf bank_mask:0xf bound_ctrl:1
	v_pk_mul_f32 v[30:31], v[32:33], v[40:41]
	v_pk_mul_f32 v[44:45], v[34:35], v[42:43]
	v_add_f32_dpp v1, v1, v1 row_ror:8 row_mask:0xf bank_mask:0xf bound_ctrl:1
	v_max_f32_e32 v1, 0x179abe15, v1
	v_pk_mul_f32 v[44:45], v[24:25], v[44:45]
	v_pk_mul_f32 v[30:31], v[22:23], v[30:31]
	v_rsq_f32_e32 v88, v1
	v_add_f32_e32 v1, v30, v31
	v_add_f32_e32 v30, v44, v45
	s_waitcnt vmcnt(0)
	v_exp_f32_e32 v44, v26
	v_exp_f32_e32 v45, v27
	v_exp_f32_e32 v46, v28
	v_exp_f32_e32 v47, v29
	v_add_f32_e32 v1, v1, v30
	ds_write_b128 v155, v[44:47]
	s_nop 0
	v_add_f32_dpp v1, v1, v1 quad_perm:[1,0,3,2] row_mask:0xf bank_mask:0xf bound_ctrl:1
	v_pk_mul_f32 v[46:47], v[86:87], v[88:89] op_sel_hi:[1,0] neg_lo:[0,1] neg_hi:[0,1]
	v_pk_mul_f32 v[44:45], v[84:85], v[88:89] op_sel_hi:[1,0] neg_lo:[0,1] neg_hi:[0,1]
	v_add_f32_dpp v1, v1, v1 quad_perm:[2,3,0,1] row_mask:0xf bank_mask:0xf bound_ctrl:1
	ds_write_b128 v155, v[44:47] offset:8192
	v_pk_mul_f32 v[46:47], v[46:47], v[80:81] neg_lo:[1,0] neg_hi:[1,0]
	v_add_f32_dpp v1, v1, v1 row_half_mirror row_mask:0xf bank_mask:0xf bound_ctrl:1
	v_pk_mul_f32 v[44:45], v[44:45], v[48:49] neg_lo:[1,0] neg_hi:[1,0]
	ds_write_b128 v155, v[44:47] offset:16384
	ds_write_b128 v155, v[40:43] offset:24576
	ds_write_b128 v155, v[32:35] offset:32768
	ds_write_b128 v155, v[36:39] offset:40960
	v_mov_b32_dpp v30, v1 row_ror:8 row_mask:0xf bank_mask:0xf bound_ctrl:1
	s_and_saveexec_b64 s[24:25], s[14:15]
	v_add_f32_e32 v1, v1, v30
	s_bitcmp1_b32 s48, 0
	s_cselect_b32 s100, 0x10100, 0
	v_add_u32_e32 v111, s100, v160
	ds_write_b32 v111, v1 offset:49152
	s_or_b64 exec, exec, s[24:25]
	s_add_i32 s49, s48, 1
	s_cmpk_eq_i32 s48, 0xff
	s_waitcnt lgkmcnt(0)
	s_barrier
	s_cbranch_scc1 .LBB0_985
	v_lshl_add_u32 v26, s49, 5, v154
	v_mad_i64_i32 v[28:29], s[24:25], v26, s59, v[68:69]
	v_add_co_u32_e32 v30, vcc, 0x1000, v28
	v_mov_b32_e32 v1, v0
	s_nop 0
	v_addc_co_u32_e32 v31, vcc, 0, v29, vcc
	global_load_dwordx2 v[50:51], v[28:29], off offset:3072
	global_load_dwordx2 v[52:53], v[30:31], off
	global_load_dwordx2 v[54:55], v[30:31], off offset:1024
	v_cmp_lt_i32_e32 vcc, 0, v26
	v_mov_b64_e32 v[60:61], v[0:1]
	v_mov_b64_e32 v[58:59], v[0:1]
	v_mov_b64_e32 v[56:57], v[0:1]
	s_and_saveexec_b64 s[24:25], vcc
	s_cbranch_execz .LBB0_984
	global_load_dwordx2 v[56:57], v[28:29], off offset:-3616
	global_load_dwordx2 v[58:59], v[28:29], off offset:-2592
	global_load_dwordx2 v[60:61], v[28:29], off offset:-1568

.LBB0_988:
	s_or_b64 exec, exec, s[24:25]
	s_waitcnt lgkmcnt(0)
	s_barrier
	ds_read_b128 v[30:33], v190 offset:49408
	ds_read_b128 v[34:37], v190 offset:49424
	ds_read_b128 v[38:41], v190 offset:49440
	ds_read_b128 v[42:45], v190 offset:49456
	s_waitcnt lgkmcnt(2)
	v_pk_add_f32 v[32:33], v[32:33], v[36:37]
	v_pk_add_f32 v[34:35], v[30:31], v[34:35]
	s_waitcnt lgkmcnt(1)
	v_pk_add_f32 v[36:37], v[32:33], v[40:41]
	ds_read_b128 v[30:33], v190 offset:49472
	v_pk_add_f32 v[34:35], v[34:35], v[38:39]
	s_waitcnt lgkmcnt(1)
	v_pk_add_f32 v[38:39], v[36:37], v[44:45]
	v_pk_add_f32 v[42:43], v[34:35], v[42:43]
	ds_read_b128 v[34:37], v190 offset:49488
	s_waitcnt lgkmcnt(1)
	v_pk_add_f32 v[44:45], v[38:39], v[32:33]
	ds_read_b128 v[38:41], v190 offset:49504
	v_pk_add_f32 v[42:43], v[42:43], v[30:31]
	ds_read_b128 v[30:33], v190 offset:49520
	s_waitcnt lgkmcnt(2)
	v_pk_add_f32 v[36:37], v[44:45], v[36:37]
	v_pk_add_f32 v[34:35], v[42:43], v[34:35]
	s_waitcnt lgkmcnt(1)
	v_pk_add_f32 v[36:37], v[36:37], v[40:41]
	v_pk_add_f32 v[34:35], v[34:35], v[38:39]
	s_waitcnt lgkmcnt(0)
	v_pk_add_f32 v[32:33], v[36:37], v[32:33]
	v_pk_add_f32 v[34:35], v[34:35], v[30:31]
	v_lshl_add_u32 v30, s48, 5, v154
	v_pk_add_f32 v[32:33], v[34:35], v[32:33]
	v_ashrrev_i32_e32 v31, 31, v30
	v_cvt_pk_bf16_f32 v1, v32, v33
	v_lshlrev_b64 v[32:33], 11, v[30:31]
	v_lshl_add_u64 v[32:33], v[66:67], 0, v[32:33]
	global_store_dword v[32:33], v1, off
	s_and_saveexec_b64 s[24:25], s[22:23]
	s_cbranch_execz .LBB0_978
	s_bitcmp1_b32 s48, 0
	s_cselect_b32 s100, 0x10100, 0
	v_add_u32_e32 v111, s100, v160
	ds_read_b32 v1, v111 offset:49152
	v_lshlrev_b64 v[30:31], 5, v[30:31]
	v_lshl_add_u64 v[30:31], s[20:21], 0, v[30:31]
	s_waitcnt lgkmcnt(0)
	global_store_dword v[30:31], v1, off
	s_branch .LBB0_978

.LBB0_1587:
	v_lshl_add_u32 v148, s38, 8, v150
	v_lshl_or_b32 v146, s30, 8, v152
	v_cmp_gt_i32_e32 vcc, s51, v146
	v_ashrrev_i32_e32 v149, 31, v148
	s_and_saveexec_b64 s[30:31], vcc
	s_cbranch_execz .LBB0_1605
	v_cmp_gt_i32_e32 vcc, s52, v146
	s_and_b64 s[38:39], s[10:11], vcc
	s_and_saveexec_b64 s[100:101], s[38:39]
	s_cbranch_execz .Lrotpf_0
	v_mov_b32_e32 v238, v148
	v_ashrrev_i32_e32 v239, 31, v238
	v_lshlrev_b64 v[238:239], 6, v[238:239]
	v_lshl_add_u64 v[238:239], v[136:137], 0, v[238:239]
	global_load_dwordx4 v[180:183], v[238:239], off offset:32
	global_load_dwordx4 v[184:187], v[238:239], off
	v_or_b32_e32 v238, 16, v148
	v_ashrrev_i32_e32 v239, 31, v238
	v_lshlrev_b64 v[238:239], 6, v[238:239]
	v_lshl_add_u64 v[238:239], v[136:137], 0, v[238:239]
	global_load_dwordx4 v[188:191], v[238:239], off offset:32
	global_load_dwordx4 v[192:195], v[238:239], off
	v_or_b32_e32 v238, 32, v148
	v_ashrrev_i32_e32 v239, 31, v238
	v_lshlrev_b64 v[238:239], 6, v[238:239]
	v_lshl_add_u64 v[238:239], v[136:137], 0, v[238:239]
	global_load_dwordx4 v[196:199], v[238:239], off offset:32
	global_load_dwordx4 v[200:203], v[238:239], off
	v_or_b32_e32 v238, 48, v148
	v_ashrrev_i32_e32 v239, 31, v238
	v_lshlrev_b64 v[238:239], 6, v[238:239]
	v_lshl_add_u64 v[238:239], v[136:137], 0, v[238:239]
	global_load_dwordx4 v[204:207], v[238:239], off offset:32
	global_load_dwordx4 v[208:211], v[238:239], off
	v_or_b32_e32 v238, 128, v148
	v_ashrrev_i32_e32 v239, 31, v238
	v_lshlrev_b64 v[238:239], 6, v[238:239]
	v_lshl_add_u64 v[238:239], v[136:137], 0, v[238:239]
	global_load_dwordx4 v[212:215], v[238:239], off offset:32
	global_load_dwordx4 v[216:219], v[238:239], off
	v_or_b32_e32 v238, 144, v148
	v_ashrrev_i32_e32 v239, 31, v238
	v_lshlrev_b64 v[238:239], 6, v[238:239]
	v_lshl_add_u64 v[238:239], v[136:137], 0, v[238:239]
	global_load_dwordx4 v[220:223], v[238:239], off offset:32
	global_load_dwordx4 v[224:227], v[238:239], off
	v_or_b32_e32 v238, 160, v148
	v_ashrrev_i32_e32 v239, 31, v238
	v_lshlrev_b64 v[238:239], 6, v[238:239]
	v_lshl_add_u64 v[238:239], v[136:137], 0, v[238:239]
	global_load_dwordx4 v[228:231], v[238:239], off offset:32
	global_load_dwordx4 v[232:235], v[238:239], off
	v_or_b32_e32 v238, 176, v148
	v_ashrrev_i32_e32 v239, 31, v238
	v_lshlrev_b64 v[238:239], 6, v[238:239]
	v_lshl_add_u64 v[238:239], v[136:137], 0, v[238:239]
	global_load_dwordx4 v[240:243], v[238:239], off offset:32
	global_load_dwordx4 v[244:247], v[238:239], off
	s_waitcnt vmcnt(0)
.Lrotpf_0:
	s_or_b64 exec, exec, s[100:101]
	s_and_saveexec_b64 s[44:45], s[38:39]
	s_cbranch_execz .LBB0_1590
	v_lshlrev_b64 v[156:157], 6, v[148:149]
	v_lshl_add_u64 v[160:161], v[136:137], 0, v[156:157]
	v_mov_b64_e32 v[156:157], v[180:181]
	v_mov_b64_e32 v[158:159], v[182:183]
	v_mov_b64_e32 v[160:161], v[184:185]
	v_mov_b64_e32 v[162:163], v[186:187]
	v_pk_mul_f32 v[164:165], v[124:125], v[156:157] op_sel:[1,0] op_sel_hi:[0,0]
	v_pk_mul_f32 v[172:173], v[120:121], v[158:159] op_sel:[1,0] op_sel_hi:[0,0]
	v_pk_mul_f32 v[166:167], v[124:125], v[160:161]
	v_mov_b32_e32 v156, v161
	v_mul_f32_e32 v168, v127, v157
	v_mul_f32_e32 v170, v127, v161
	v_pk_mul_f32 v[174:175], v[120:121], v[162:163]
	v_mov_b32_e32 v158, v163
	v_mul_f32_e32 v176, v123, v159
	v_mul_f32_e32 v178, v123, v163
	v_pk_fma_f32 v[124:125], v[124:125], v[160:161], v[164:165] op_sel_hi:[1,0,1]
	v_mov_b32_e32 v160, v157
	v_pk_fma_f32 v[120:121], v[120:121], v[162:163], v[172:173] op_sel_hi:[1,0,1]
	v_mov_b32_e32 v162, v159
	v_pk_fma_f32 v[168:169], v[126:127], v[156:157], v[168:169] op_sel_hi:[1,1,0] neg_lo:[0,0,1] neg_hi:[0,0,1]
	v_pk_fma_f32 v[156:157], v[122:123], v[158:159], v[176:177] op_sel_hi:[1,1,0] neg_lo:[0,0,1] neg_hi:[0,0,1]
	v_pk_fma_f32 v[158:159], v[126:127], v[160:161], v[170:171] op_sel_hi:[1,1,0]
	v_pk_fma_f32 v[160:161], v[122:123], v[162:163], v[178:179] op_sel_hi:[1,1,0]
	v_sub_f32_e32 v124, v166, v164
	v_sub_f32_e32 v120, v174, v172
	v_mov_b32_e32 v126, v168
	v_mov_b32_e32 v122, v156
	v_mov_b32_e32 v127, v158
	v_mov_b32_e32 v123, v160
.LBB0_1590:
	s_or_b64 exec, exec, s[44:45]
	v_cvt_pk_bf16_f32 v124, v124, v125
	v_cvt_pk_bf16_f32 v125, v126, v127
	v_cvt_pk_bf16_f32 v126, v120, v121
	v_mov_b64_e32 v[120:121], s[16:17]
	v_ashrrev_i32_e32 v147, 31, v146
	v_mad_i64_i32 v[120:121], s[44:45], v148, s53, v[120:121]
	v_cvt_pk_bf16_f32 v127, v122, v123
	v_lshl_add_u64 v[120:121], v[146:147], 1, v[120:121]
	global_store_dwordx4 v[120:121], v[124:127], off
	v_or_b32_e32 v120, 16, v148
	v_ashrrev_i32_e32 v121, 31, v120
	s_and_saveexec_b64 s[44:45], s[38:39]
	s_cbranch_execz .LBB0_1592
	v_lshlrev_b64 v[122:123], 6, v[120:121]
	v_lshl_add_u64 v[126:127], v[136:137], 0, v[122:123]
	v_mov_b64_e32 v[122:123], v[188:189]
	v_mov_b64_e32 v[124:125], v[190:191]
	v_mov_b64_e32 v[156:157], v[192:193]
	v_mov_b64_e32 v[158:159], v[194:195]
	v_pk_mul_f32 v[126:127], v[116:117], v[122:123] op_sel:[1,0] op_sel_hi:[0,0]
	v_pk_mul_f32 v[166:167], v[112:113], v[124:125] op_sel:[1,0] op_sel_hi:[0,0]
	v_pk_mul_f32 v[160:161], v[116:117], v[156:157]
	v_mov_b32_e32 v122, v157
	v_mul_f32_e32 v162, v119, v123
	v_mul_f32_e32 v164, v119, v157
	v_pk_mul_f32 v[168:169], v[112:113], v[158:159]
	v_mov_b32_e32 v124, v159
	v_mul_f32_e32 v170, v115, v125
	v_mul_f32_e32 v172, v115, v159
	v_pk_fma_f32 v[116:117], v[116:117], v[156:157], v[126:127] op_sel_hi:[1,0,1]
	v_mov_b32_e32 v156, v123
	v_pk_fma_f32 v[112:113], v[112:113], v[158:159], v[166:167] op_sel_hi:[1,0,1]
	v_mov_b32_e32 v158, v125
	v_pk_fma_f32 v[162:163], v[118:119], v[122:123], v[162:163] op_sel_hi:[1,1,0] neg_lo:[0,0,1] neg_hi:[0,0,1]
	v_pk_fma_f32 v[122:123], v[114:115], v[124:125], v[170:171] op_sel_hi:[1,1,0] neg_lo:[0,0,1] neg_hi:[0,0,1]
	v_pk_fma_f32 v[124:125], v[118:119], v[156:157], v[164:165] op_sel_hi:[1,1,0]
	v_pk_fma_f32 v[156:157], v[114:115], v[158:159], v[172:173] op_sel_hi:[1,1,0]
	v_sub_f32_e32 v116, v160, v126
	v_sub_f32_e32 v112, v168, v166
	v_mov_b32_e32 v118, v162
	v_mov_b32_e32 v114, v122
	v_mov_b32_e32 v119, v124
	v_mov_b32_e32 v115, v156
.LBB0_1592:
	s_or_b64 exec, exec, s[44:45]
	v_cvt_pk_bf16_f32 v116, v116, v117
	v_cvt_pk_bf16_f32 v117, v118, v119
	v_cvt_pk_bf16_f32 v118, v112, v113
	v_mov_b64_e32 v[112:113], s[16:17]
	v_mad_i64_i32 v[112:113], s[44:45], v120, s53, v[112:113]
	v_cvt_pk_bf16_f32 v119, v114, v115
	v_lshl_add_u64 v[112:113], v[146:147], 1, v[112:113]
	global_store_dwordx4 v[112:113], v[116:119], off
	v_or_b32_e32 v112, 32, v148
	v_ashrrev_i32_e32 v113, 31, v112
	s_and_saveexec_b64 s[44:45], s[38:39]
	s_cbranch_execz .LBB0_1594
	v_lshlrev_b64 v[114:115], 6, v[112:113]
	v_lshl_add_u64 v[118:119], v[136:137], 0, v[114:115]
	v_mov_b64_e32 v[114:115], v[196:197]
	v_mov_b64_e32 v[116:117], v[198:199]
	v_mov_b64_e32 v[118:119], v[200:201]
	v_mov_b64_e32 v[120:121], v[202:203]
	v_pk_mul_f32 v[122:123], v[108:109], v[114:115] op_sel:[1,0] op_sel_hi:[0,0]
	v_pk_mul_f32 v[158:159], v[104:105], v[116:117] op_sel:[1,0] op_sel_hi:[0,0]
	v_pk_mul_f32 v[124:125], v[108:109], v[118:119]
	v_mov_b32_e32 v114, v119
	v_mul_f32_e32 v126, v111, v115
	v_mul_f32_e32 v156, v111, v119
	v_pk_mul_f32 v[160:161], v[104:105], v[120:121]
	v_mov_b32_e32 v116, v121
	v_mul_f32_e32 v162, v107, v117
	v_mul_f32_e32 v164, v107, v121
	v_pk_fma_f32 v[108:109], v[108:109], v[118:119], v[122:123] op_sel_hi:[1,0,1]
	v_mov_b32_e32 v118, v115
	v_pk_fma_f32 v[104:105], v[104:105], v[120:121], v[158:159] op_sel_hi:[1,0,1]
	v_mov_b32_e32 v120, v117
	v_pk_fma_f32 v[126:127], v[110:111], v[114:115], v[126:127] op_sel_hi:[1,1,0] neg_lo:[0,0,1] neg_hi:[0,0,1]
	v_pk_fma_f32 v[114:115], v[106:107], v[116:117], v[162:163] op_sel_hi:[1,1,0] neg_lo:[0,0,1] neg_hi:[0,0,1]
	v_pk_fma_f32 v[116:117], v[110:111], v[118:119], v[156:157] op_sel_hi:[1,1,0]
	v_pk_fma_f32 v[118:119], v[106:107], v[120:121], v[164:165] op_sel_hi:[1,1,0]
	v_sub_f32_e32 v108, v124, v122
	v_sub_f32_e32 v104, v160, v158
	v_mov_b32_e32 v110, v126
	v_mov_b32_e32 v106, v114
	v_mov_b32_e32 v111, v116
	v_mov_b32_e32 v107, v118
.LBB0_1594:
	s_or_b64 exec, exec, s[44:45]
	v_cvt_pk_bf16_f32 v108, v108, v109
	v_cvt_pk_bf16_f32 v109, v110, v111
	v_cvt_pk_bf16_f32 v110, v104, v105
	v_mov_b64_e32 v[104:105], s[16:17]
	v_mad_i64_i32 v[104:105], s[44:45], v112, s53, v[104:105]
	v_cvt_pk_bf16_f32 v111, v106, v107
	v_lshl_add_u64 v[104:105], v[146:147], 1, v[104:105]
	global_store_dwordx4 v[104:105], v[108:111], off
	v_or_b32_e32 v104, 48, v148
	v_ashrrev_i32_e32 v105, 31, v104
	s_and_saveexec_b64 s[44:45], s[38:39]
	s_cbranch_execz .LBB0_1596
	v_lshlrev_b64 v[106:107], 6, v[104:105]
	v_lshl_add_u64 v[110:111], v[136:137], 0, v[106:107]
	v_mov_b64_e32 v[106:107], v[204:205]
	v_mov_b64_e32 v[108:109], v[206:207]
	v_mov_b64_e32 v[110:111], v[208:209]
	v_mov_b64_e32 v[112:113], v[210:211]
	v_pk_mul_f32 v[114:115], v[100:101], v[106:107] op_sel:[1,0] op_sel_hi:[0,0]
	v_pk_mul_f32 v[122:123], v[96:97], v[108:109] op_sel:[1,0] op_sel_hi:[0,0]
	v_pk_mul_f32 v[116:117], v[100:101], v[110:111]
	v_mov_b32_e32 v106, v111
	v_mul_f32_e32 v118, v103, v107
	v_mul_f32_e32 v120, v103, v111
	v_pk_mul_f32 v[124:125], v[96:97], v[112:113]
	v_mov_b32_e32 v108, v113
	v_mul_f32_e32 v126, v99, v109
	v_mul_f32_e32 v156, v99, v113
	v_pk_fma_f32 v[100:101], v[100:101], v[110:111], v[114:115] op_sel_hi:[1,0,1]
	v_mov_b32_e32 v110, v107
	v_pk_fma_f32 v[96:97], v[96:97], v[112:113], v[122:123] op_sel_hi:[1,0,1]
	v_mov_b32_e32 v112, v109
	v_pk_fma_f32 v[118:119], v[102:103], v[106:107], v[118:119] op_sel_hi:[1,1,0] neg_lo:[0,0,1] neg_hi:[0,0,1]
	v_pk_fma_f32 v[106:107], v[98:99], v[108:109], v[126:127] op_sel_hi:[1,1,0] neg_lo:[0,0,1] neg_hi:[0,0,1]
	v_pk_fma_f32 v[108:109], v[102:103], v[110:111], v[120:121] op_sel_hi:[1,1,0]
	v_pk_fma_f32 v[110:111], v[98:99], v[112:113], v[156:157] op_sel_hi:[1,1,0]
	v_sub_f32_e32 v100, v116, v114
	v_sub_f32_e32 v96, v124, v122
	v_mov_b32_e32 v102, v118
	v_mov_b32_e32 v98, v106
	v_mov_b32_e32 v103, v108
	v_mov_b32_e32 v99, v110
.LBB0_1596:
	s_or_b64 exec, exec, s[44:45]
	v_cvt_pk_bf16_f32 v100, v100, v101
	v_cvt_pk_bf16_f32 v101, v102, v103
	v_cvt_pk_bf16_f32 v102, v96, v97
	v_mov_b64_e32 v[96:97], s[16:17]
	v_mad_i64_i32 v[96:97], s[44:45], v104, s53, v[96:97]
	v_cvt_pk_bf16_f32 v103, v98, v99
	v_lshl_add_u64 v[96:97], v[146:147], 1, v[96:97]
	global_store_dwordx4 v[96:97], v[100:103], off
	v_add_u32_e32 v96, 0x80, v148
	v_ashrrev_i32_e32 v97, 31, v96
	s_and_saveexec_b64 s[44:45], s[38:39]
	s_cbranch_execz .LBB0_1598
	v_lshlrev_b64 v[98:99], 6, v[96:97]
	v_lshl_add_u64 v[102:103], v[136:137], 0, v[98:99]
	v_mov_b64_e32 v[98:99], v[212:213]
	v_mov_b64_e32 v[100:101], v[214:215]
	v_mov_b64_e32 v[102:103], v[216:217]
	v_mov_b64_e32 v[104:105], v[218:219]
	v_pk_mul_f32 v[106:107], v[92:93], v[98:99] op_sel:[1,0] op_sel_hi:[0,0]
	v_pk_mul_f32 v[114:115], v[88:89], v[100:101] op_sel:[1,0] op_sel_hi:[0,0]
	v_pk_mul_f32 v[108:109], v[92:93], v[102:103]
	v_mov_b32_e32 v98, v103
	v_mul_f32_e32 v110, v95, v99
	v_mul_f32_e32 v112, v95, v103
	v_pk_mul_f32 v[116:117], v[88:89], v[104:105]
	v_mov_b32_e32 v100, v105
	v_mul_f32_e32 v118, v91, v101
	v_mul_f32_e32 v120, v91, v105
	v_pk_fma_f32 v[92:93], v[92:93], v[102:103], v[106:107] op_sel_hi:[1,0,1]
	v_mov_b32_e32 v102, v99
	v_pk_fma_f32 v[88:89], v[88:89], v[104:105], v[114:115] op_sel_hi:[1,0,1]
	v_mov_b32_e32 v104, v101
	v_pk_fma_f32 v[110:111], v[94:95], v[98:99], v[110:111] op_sel_hi:[1,1,0] neg_lo:[0,0,1] neg_hi:[0,0,1]
	v_pk_fma_f32 v[98:99], v[90:91], v[100:101], v[118:119] op_sel_hi:[1,1,0] neg_lo:[0,0,1] neg_hi:[0,0,1]
	v_pk_fma_f32 v[100:101], v[94:95], v[102:103], v[112:113] op_sel_hi:[1,1,0]
	v_pk_fma_f32 v[102:103], v[90:91], v[104:105], v[120:121] op_sel_hi:[1,1,0]
	v_sub_f32_e32 v92, v108, v106
	v_sub_f32_e32 v88, v116, v114
	v_mov_b32_e32 v94, v110
	v_mov_b32_e32 v90, v98
	v_mov_b32_e32 v95, v100
	v_mov_b32_e32 v91, v102
.LBB0_1598:
	s_or_b64 exec, exec, s[44:45]
	v_cvt_pk_bf16_f32 v92, v92, v93
	v_cvt_pk_bf16_f32 v93, v94, v95
	v_cvt_pk_bf16_f32 v94, v88, v89
	v_mov_b64_e32 v[88:89], s[16:17]
	v_mad_i64_i32 v[88:89], s[44:45], v96, s53, v[88:89]
	v_cvt_pk_bf16_f32 v95, v90, v91
	v_lshl_add_u64 v[88:89], v[146:147], 1, v[88:89]
	global_store_dwordx4 v[88:89], v[92:95], off
	v_add_u32_e32 v88, 0x90, v148
	v_ashrrev_i32_e32 v89, 31, v88
	s_and_saveexec_b64 s[44:45], s[38:39]
	s_cbranch_execz .LBB0_1600
	v_lshlrev_b64 v[90:91], 6, v[88:89]
	v_lshl_add_u64 v[94:95], v[136:137], 0, v[90:91]
	v_mov_b64_e32 v[90:91], v[220:221]
	v_mov_b64_e32 v[92:93], v[222:223]
	v_mov_b64_e32 v[94:95], v[224:225]
	v_mov_b64_e32 v[96:97], v[226:227]
	v_pk_mul_f32 v[98:99], v[84:85], v[90:91] op_sel:[1,0] op_sel_hi:[0,0]
	v_pk_mul_f32 v[106:107], v[80:81], v[92:93] op_sel:[1,0] op_sel_hi:[0,0]
	v_pk_mul_f32 v[100:101], v[84:85], v[94:95]
	v_mov_b32_e32 v90, v95
	v_mul_f32_e32 v102, v87, v91
	v_mul_f32_e32 v104, v87, v95
	v_pk_mul_f32 v[108:109], v[80:81], v[96:97]
	v_mov_b32_e32 v92, v97
	v_mul_f32_e32 v110, v83, v93
	v_mul_f32_e32 v112, v83, v97
	v_pk_fma_f32 v[84:85], v[84:85], v[94:95], v[98:99] op_sel_hi:[1,0,1]
	v_mov_b32_e32 v94, v91
	v_pk_fma_f32 v[80:81], v[80:81], v[96:97], v[106:107] op_sel_hi:[1,0,1]
	v_mov_b32_e32 v96, v93
	v_pk_fma_f32 v[102:103], v[86:87], v[90:91], v[102:103] op_sel_hi:[1,1,0] neg_lo:[0,0,1] neg_hi:[0,0,1]
	v_pk_fma_f32 v[90:91], v[82:83], v[92:93], v[110:111] op_sel_hi:[1,1,0] neg_lo:[0,0,1] neg_hi:[0,0,1]
	v_pk_fma_f32 v[92:93], v[86:87], v[94:95], v[104:105] op_sel_hi:[1,1,0]
	v_pk_fma_f32 v[94:95], v[82:83], v[96:97], v[112:113] op_sel_hi:[1,1,0]
	v_sub_f32_e32 v84, v100, v98
	v_sub_f32_e32 v80, v108, v106
	v_mov_b32_e32 v86, v102
	v_mov_b32_e32 v82, v90
	v_mov_b32_e32 v87, v92
	v_mov_b32_e32 v83, v94
.LBB0_1600:
	s_or_b64 exec, exec, s[44:45]
	v_cvt_pk_bf16_f32 v84, v84, v85
	v_cvt_pk_bf16_f32 v85, v86, v87
	v_cvt_pk_bf16_f32 v86, v80, v81
	v_mov_b64_e32 v[80:81], s[16:17]
	v_mad_i64_i32 v[80:81], s[44:45], v88, s53, v[80:81]
	v_cvt_pk_bf16_f32 v87, v82, v83
	v_lshl_add_u64 v[80:81], v[146:147], 1, v[80:81]
	global_store_dwordx4 v[80:81], v[84:87], off
	v_add_u32_e32 v80, 0xa0, v148
	v_ashrrev_i32_e32 v81, 31, v80
	s_and_saveexec_b64 s[44:45], s[38:39]
	s_cbranch_execz .LBB0_1602
	v_lshlrev_b64 v[82:83], 6, v[80:81]
	v_lshl_add_u64 v[86:87], v[136:137], 0, v[82:83]
	v_mov_b64_e32 v[82:83], v[228:229]
	v_mov_b64_e32 v[84:85], v[230:231]
	v_mov_b64_e32 v[86:87], v[232:233]
	v_mov_b64_e32 v[88:89], v[234:235]
	v_pk_mul_f32 v[90:91], v[76:77], v[82:83] op_sel:[1,0] op_sel_hi:[0,0]
	v_pk_mul_f32 v[98:99], v[72:73], v[84:85] op_sel:[1,0] op_sel_hi:[0,0]
	v_pk_mul_f32 v[92:93], v[76:77], v[86:87]
	v_mov_b32_e32 v82, v87
	v_mul_f32_e32 v94, v79, v83
	v_mul_f32_e32 v96, v79, v87
	v_pk_mul_f32 v[100:101], v[72:73], v[88:89]
	v_mov_b32_e32 v84, v89
	v_mul_f32_e32 v102, v75, v85
	v_mul_f32_e32 v104, v75, v89
	v_pk_fma_f32 v[76:77], v[76:77], v[86:87], v[90:91] op_sel_hi:[1,0,1]
	v_mov_b32_e32 v86, v83
	v_pk_fma_f32 v[72:73], v[72:73], v[88:89], v[98:99] op_sel_hi:[1,0,1]
	v_mov_b32_e32 v88, v85
	v_pk_fma_f32 v[94:95], v[78:79], v[82:83], v[94:95] op_sel_hi:[1,1,0] neg_lo:[0,0,1] neg_hi:[0,0,1]
	v_pk_fma_f32 v[82:83], v[74:75], v[84:85], v[102:103] op_sel_hi:[1,1,0] neg_lo:[0,0,1] neg_hi:[0,0,1]
	v_pk_fma_f32 v[84:85], v[78:79], v[86:87], v[96:97] op_sel_hi:[1,1,0]
	v_pk_fma_f32 v[86:87], v[74:75], v[88:89], v[104:105] op_sel_hi:[1,1,0]
	v_sub_f32_e32 v76, v92, v90
	v_sub_f32_e32 v72, v100, v98
	v_mov_b32_e32 v78, v94
	v_mov_b32_e32 v74, v82
	v_mov_b32_e32 v79, v84
	v_mov_b32_e32 v75, v86
.LBB0_1602:
	s_or_b64 exec, exec, s[44:45]
	v_cvt_pk_bf16_f32 v76, v76, v77
	v_cvt_pk_bf16_f32 v77, v78, v79
	v_cvt_pk_bf16_f32 v78, v72, v73
	v_mov_b64_e32 v[72:73], s[16:17]
	v_mad_i64_i32 v[72:73], s[44:45], v80, s53, v[72:73]
	v_cvt_pk_bf16_f32 v79, v74, v75
	v_lshl_add_u64 v[72:73], v[146:147], 1, v[72:73]
	global_store_dwordx4 v[72:73], v[76:79], off
	v_add_u32_e32 v72, 0xb0, v148
	v_ashrrev_i32_e32 v73, 31, v72
	s_and_saveexec_b64 s[44:45], s[38:39]
	s_cbranch_execz .LBB0_1604
	v_lshlrev_b64 v[74:75], 6, v[72:73]
	v_lshl_add_u64 v[78:79], v[136:137], 0, v[74:75]
	v_mov_b64_e32 v[74:75], v[240:241]
	v_mov_b64_e32 v[76:77], v[242:243]
	v_mov_b64_e32 v[78:79], v[244:245]
	v_mov_b64_e32 v[80:81], v[246:247]
	v_pk_mul_f32 v[82:83], v[68:69], v[74:75] op_sel:[1,0] op_sel_hi:[0,0]
	v_pk_mul_f32 v[90:91], v[64:65], v[76:77] op_sel:[1,0] op_sel_hi:[0,0]
	v_pk_mul_f32 v[84:85], v[68:69], v[78:79]
	v_mov_b32_e32 v74, v79
	v_mul_f32_e32 v86, v71, v75
	v_mul_f32_e32 v88, v71, v79
	v_pk_mul_f32 v[92:93], v[64:65], v[80:81]
	v_mov_b32_e32 v76, v81
	v_mul_f32_e32 v94, v67, v77
	v_mul_f32_e32 v96, v67, v81
	v_pk_fma_f32 v[68:69], v[68:69], v[78:79], v[82:83] op_sel_hi:[1,0,1]
	v_mov_b32_e32 v78, v75
	v_pk_fma_f32 v[64:65], v[64:65], v[80:81], v[90:91] op_sel_hi:[1,0,1]
	v_mov_b32_e32 v80, v77
	v_pk_fma_f32 v[86:87], v[70:71], v[74:75], v[86:87] op_sel_hi:[1,1,0] neg_lo:[0,0,1] neg_hi:[0,0,1]
	v_pk_fma_f32 v[74:75], v[66:67], v[76:77], v[94:95] op_sel_hi:[1,1,0] neg_lo:[0,0,1] neg_hi:[0,0,1]
	v_pk_fma_f32 v[76:77], v[70:71], v[78:79], v[88:89] op_sel_hi:[1,1,0]
	v_pk_fma_f32 v[78:79], v[66:67], v[80:81], v[96:97] op_sel_hi:[1,1,0]
	v_sub_f32_e32 v68, v84, v82
	v_sub_f32_e32 v64, v92, v90
	v_mov_b32_e32 v70, v86
	v_mov_b32_e32 v66, v74
	v_mov_b32_e32 v71, v76
	v_mov_b32_e32 v67, v78

.LBB0_1605:
	s_or_b64 exec, exec, s[30:31]
	v_or_b32_e32 v64, 0x80, v146
	v_cmp_gt_i32_e32 vcc, s51, v64
	s_and_saveexec_b64 s[30:31], vcc
	s_cbranch_execz .LBB0_1623
	v_cmp_gt_i32_e32 vcc, s52, v64
	s_and_b64 s[38:39], s[10:11], vcc
	s_and_saveexec_b64 s[44:45], s[38:39]
	s_cbranch_execz .LBB0_1608
	v_lshlrev_b64 v[64:65], 6, v[148:149]
	v_lshl_add_u64 v[68:69], v[136:137], 0, v[64:65]
	v_mov_b64_e32 v[64:65], v[180:181]
	v_mov_b64_e32 v[66:67], v[182:183]
	v_mov_b64_e32 v[68:69], v[184:185]
	v_mov_b64_e32 v[70:71], v[186:187]
	v_pk_mul_f32 v[72:73], v[60:61], v[64:65] op_sel:[1,0] op_sel_hi:[0,0]
	v_pk_mul_f32 v[80:81], v[56:57], v[66:67] op_sel:[1,0] op_sel_hi:[0,0]
	v_pk_mul_f32 v[74:75], v[60:61], v[68:69]
	v_mov_b32_e32 v64, v69
	v_mul_f32_e32 v76, v63, v65
	v_mul_f32_e32 v78, v63, v69
	v_pk_mul_f32 v[82:83], v[56:57], v[70:71]
	v_mov_b32_e32 v66, v71
	v_mul_f32_e32 v84, v59, v67
	v_mul_f32_e32 v86, v59, v71
	v_pk_fma_f32 v[60:61], v[60:61], v[68:69], v[72:73] op_sel_hi:[1,0,1]
	v_mov_b32_e32 v68, v65
	v_pk_fma_f32 v[56:57], v[56:57], v[70:71], v[80:81] op_sel_hi:[1,0,1]
	v_mov_b32_e32 v70, v67
	v_pk_fma_f32 v[76:77], v[62:63], v[64:65], v[76:77] op_sel_hi:[1,1,0] neg_lo:[0,0,1] neg_hi:[0,0,1]
	v_pk_fma_f32 v[64:65], v[58:59], v[66:67], v[84:85] op_sel_hi:[1,1,0] neg_lo:[0,0,1] neg_hi:[0,0,1]
	v_pk_fma_f32 v[66:67], v[62:63], v[68:69], v[78:79] op_sel_hi:[1,1,0]
	v_pk_fma_f32 v[68:69], v[58:59], v[70:71], v[86:87] op_sel_hi:[1,1,0]
	v_sub_f32_e32 v60, v74, v72
	v_sub_f32_e32 v56, v82, v80
	v_mov_b32_e32 v62, v76
	v_mov_b32_e32 v58, v64
	v_mov_b32_e32 v63, v66
	v_mov_b32_e32 v59, v68
.LBB0_1608:
	s_or_b64 exec, exec, s[44:45]
	v_cvt_pk_bf16_f32 v60, v60, v61
	v_cvt_pk_bf16_f32 v61, v62, v63
	v_cvt_pk_bf16_f32 v62, v56, v57
	v_mov_b64_e32 v[56:57], s[16:17]
	v_mad_i64_i32 v[56:57], s[44:45], v148, s53, v[56:57]
	v_ashrrev_i32_e32 v147, 31, v146
	v_cvt_pk_bf16_f32 v63, v58, v59
	v_lshl_add_u64 v[56:57], v[146:147], 1, v[56:57]
	global_store_dwordx4 v[56:57], v[60:63], off offset:256
	v_or_b32_e32 v56, 16, v148
	v_ashrrev_i32_e32 v57, 31, v56
	s_and_saveexec_b64 s[44:45], s[38:39]
	s_cbranch_execz .LBB0_1610
	v_lshlrev_b64 v[58:59], 6, v[56:57]
	v_lshl_add_u64 v[62:63], v[136:137], 0, v[58:59]
	v_mov_b64_e32 v[58:59], v[188:189]
	v_mov_b64_e32 v[60:61], v[190:191]
	v_mov_b64_e32 v[62:63], v[192:193]
	v_mov_b64_e32 v[64:65], v[194:195]
	v_pk_mul_f32 v[66:67], v[52:53], v[58:59] op_sel:[1,0] op_sel_hi:[0,0]
	v_pk_mul_f32 v[74:75], v[48:49], v[60:61] op_sel:[1,0] op_sel_hi:[0,0]
	v_pk_mul_f32 v[68:69], v[52:53], v[62:63]
	v_mov_b32_e32 v58, v63
	v_mul_f32_e32 v70, v55, v59
	v_mul_f32_e32 v72, v55, v63
	v_pk_mul_f32 v[76:77], v[48:49], v[64:65]
	v_mov_b32_e32 v60, v65
	v_mul_f32_e32 v78, v51, v61
	v_mul_f32_e32 v80, v51, v65
	v_pk_fma_f32 v[52:53], v[52:53], v[62:63], v[66:67] op_sel_hi:[1,0,1]
	v_mov_b32_e32 v62, v59
	v_pk_fma_f32 v[48:49], v[48:49], v[64:65], v[74:75] op_sel_hi:[1,0,1]
	v_mov_b32_e32 v64, v61
	v_pk_fma_f32 v[70:71], v[54:55], v[58:59], v[70:71] op_sel_hi:[1,1,0] neg_lo:[0,0,1] neg_hi:[0,0,1]
	v_pk_fma_f32 v[58:59], v[50:51], v[60:61], v[78:79] op_sel_hi:[1,1,0] neg_lo:[0,0,1] neg_hi:[0,0,1]
	v_pk_fma_f32 v[60:61], v[54:55], v[62:63], v[72:73] op_sel_hi:[1,1,0]
	v_pk_fma_f32 v[62:63], v[50:51], v[64:65], v[80:81] op_sel_hi:[1,1,0]
	v_sub_f32_e32 v52, v68, v66
	v_sub_f32_e32 v48, v76, v74
	v_mov_b32_e32 v54, v70
	v_mov_b32_e32 v50, v58
	v_mov_b32_e32 v55, v60
	v_mov_b32_e32 v51, v62
.LBB0_1610:
	s_or_b64 exec, exec, s[44:45]
	v_cvt_pk_bf16_f32 v52, v52, v53
	v_cvt_pk_bf16_f32 v53, v54, v55
	v_cvt_pk_bf16_f32 v54, v48, v49
	v_mov_b64_e32 v[48:49], s[16:17]
	v_mad_i64_i32 v[48:49], s[44:45], v56, s53, v[48:49]
	v_cvt_pk_bf16_f32 v55, v50, v51
	v_lshl_add_u64 v[48:49], v[146:147], 1, v[48:49]
	global_store_dwordx4 v[48:49], v[52:55], off offset:256
	v_or_b32_e32 v48, 32, v148
	v_ashrrev_i32_e32 v49, 31, v48
	s_and_saveexec_b64 s[44:45], s[38:39]
	s_cbranch_execz .LBB0_1612
	v_lshlrev_b64 v[50:51], 6, v[48:49]
	v_lshl_add_u64 v[54:55], v[136:137], 0, v[50:51]
	v_mov_b64_e32 v[50:51], v[196:197]
	v_mov_b64_e32 v[52:53], v[198:199]
	v_mov_b64_e32 v[54:55], v[200:201]
	v_mov_b64_e32 v[56:57], v[202:203]
	v_pk_mul_f32 v[58:59], v[44:45], v[50:51] op_sel:[1,0] op_sel_hi:[0,0]
	v_pk_mul_f32 v[66:67], v[40:41], v[52:53] op_sel:[1,0] op_sel_hi:[0,0]
	v_pk_mul_f32 v[60:61], v[44:45], v[54:55]
	v_mov_b32_e32 v50, v55
	v_mul_f32_e32 v62, v47, v51
	v_mul_f32_e32 v64, v47, v55
	v_pk_mul_f32 v[68:69], v[40:41], v[56:57]
	v_mov_b32_e32 v52, v57
	v_mul_f32_e32 v70, v43, v53
	v_mul_f32_e32 v72, v43, v57
	v_pk_fma_f32 v[44:45], v[44:45], v[54:55], v[58:59] op_sel_hi:[1,0,1]
	v_mov_b32_e32 v54, v51
	v_pk_fma_f32 v[40:41], v[40:41], v[56:57], v[66:67] op_sel_hi:[1,0,1]
	v_mov_b32_e32 v56, v53
	v_pk_fma_f32 v[62:63], v[46:47], v[50:51], v[62:63] op_sel_hi:[1,1,0] neg_lo:[0,0,1] neg_hi:[0,0,1]
	v_pk_fma_f32 v[50:51], v[42:43], v[52:53], v[70:71] op_sel_hi:[1,1,0] neg_lo:[0,0,1] neg_hi:[0,0,1]
	v_pk_fma_f32 v[52:53], v[46:47], v[54:55], v[64:65] op_sel_hi:[1,1,0]
	v_pk_fma_f32 v[54:55], v[42:43], v[56:57], v[72:73] op_sel_hi:[1,1,0]
	v_sub_f32_e32 v44, v60, v58
	v_sub_f32_e32 v40, v68, v66
	v_mov_b32_e32 v46, v62
	v_mov_b32_e32 v42, v50
	v_mov_b32_e32 v47, v52
	v_mov_b32_e32 v43, v54
.LBB0_1612:
	s_or_b64 exec, exec, s[44:45]
	v_cvt_pk_bf16_f32 v44, v44, v45
	v_cvt_pk_bf16_f32 v45, v46, v47
	v_cvt_pk_bf16_f32 v46, v40, v41
	v_mov_b64_e32 v[40:41], s[16:17]
	v_mad_i64_i32 v[40:41], s[44:45], v48, s53, v[40:41]
	v_cvt_pk_bf16_f32 v47, v42, v43
	v_lshl_add_u64 v[40:41], v[146:147], 1, v[40:41]
	global_store_dwordx4 v[40:41], v[44:47], off offset:256
	v_or_b32_e32 v40, 48, v148
	v_ashrrev_i32_e32 v41, 31, v40
	s_and_saveexec_b64 s[44:45], s[38:39]
	s_cbranch_execz .LBB0_1614
	v_lshlrev_b64 v[42:43], 6, v[40:41]
	v_lshl_add_u64 v[46:47], v[136:137], 0, v[42:43]
	v_mov_b64_e32 v[42:43], v[204:205]
	v_mov_b64_e32 v[44:45], v[206:207]
	v_mov_b64_e32 v[46:47], v[208:209]
	v_mov_b64_e32 v[48:49], v[210:211]
	v_pk_mul_f32 v[50:51], v[36:37], v[42:43] op_sel:[1,0] op_sel_hi:[0,0]
	v_pk_mul_f32 v[58:59], v[32:33], v[44:45] op_sel:[1,0] op_sel_hi:[0,0]
	v_pk_mul_f32 v[52:53], v[36:37], v[46:47]
	v_mov_b32_e32 v42, v47
	v_mul_f32_e32 v54, v39, v43
	v_mul_f32_e32 v56, v39, v47
	v_pk_mul_f32 v[60:61], v[32:33], v[48:49]
	v_mov_b32_e32 v44, v49
	v_mul_f32_e32 v62, v35, v45
	v_mul_f32_e32 v64, v35, v49
	v_pk_fma_f32 v[36:37], v[36:37], v[46:47], v[50:51] op_sel_hi:[1,0,1]
	v_mov_b32_e32 v46, v43
	v_pk_fma_f32 v[32:33], v[32:33], v[48:49], v[58:59] op_sel_hi:[1,0,1]
	v_mov_b32_e32 v48, v45
	v_pk_fma_f32 v[54:55], v[38:39], v[42:43], v[54:55] op_sel_hi:[1,1,0] neg_lo:[0,0,1] neg_hi:[0,0,1]
	v_pk_fma_f32 v[42:43], v[34:35], v[44:45], v[62:63] op_sel_hi:[1,1,0] neg_lo:[0,0,1] neg_hi:[0,0,1]
	v_pk_fma_f32 v[44:45], v[38:39], v[46:47], v[56:57] op_sel_hi:[1,1,0]
	v_pk_fma_f32 v[46:47], v[34:35], v[48:49], v[64:65] op_sel_hi:[1,1,0]
	v_sub_f32_e32 v36, v52, v50
	v_sub_f32_e32 v32, v60, v58
	v_mov_b32_e32 v38, v54
	v_mov_b32_e32 v34, v42
	v_mov_b32_e32 v39, v44
	v_mov_b32_e32 v35, v46
.LBB0_1614:
	s_or_b64 exec, exec, s[44:45]
	v_cvt_pk_bf16_f32 v36, v36, v37
	v_cvt_pk_bf16_f32 v37, v38, v39
	v_cvt_pk_bf16_f32 v38, v32, v33
	v_mov_b64_e32 v[32:33], s[16:17]
	v_mad_i64_i32 v[32:33], s[44:45], v40, s53, v[32:33]
	v_cvt_pk_bf16_f32 v39, v34, v35
	v_lshl_add_u64 v[32:33], v[146:147], 1, v[32:33]
	global_store_dwordx4 v[32:33], v[36:39], off offset:256
	v_add_u32_e32 v32, 0x80, v148
	v_ashrrev_i32_e32 v33, 31, v32
	s_and_saveexec_b64 s[44:45], s[38:39]
	s_cbranch_execz .LBB0_1616
	v_lshlrev_b64 v[34:35], 6, v[32:33]
	v_lshl_add_u64 v[38:39], v[136:137], 0, v[34:35]
	v_mov_b64_e32 v[34:35], v[212:213]
	v_mov_b64_e32 v[36:37], v[214:215]
	v_mov_b64_e32 v[38:39], v[216:217]
	v_mov_b64_e32 v[40:41], v[218:219]
	v_pk_mul_f32 v[42:43], v[28:29], v[34:35] op_sel:[1,0] op_sel_hi:[0,0]
	v_pk_mul_f32 v[50:51], v[24:25], v[36:37] op_sel:[1,0] op_sel_hi:[0,0]
	v_pk_mul_f32 v[44:45], v[28:29], v[38:39]
	v_mov_b32_e32 v34, v39
	v_mul_f32_e32 v46, v31, v35
	v_mul_f32_e32 v48, v31, v39
	v_pk_mul_f32 v[52:53], v[24:25], v[40:41]
	v_mov_b32_e32 v36, v41
	v_mul_f32_e32 v54, v27, v37
	v_mul_f32_e32 v56, v27, v41
	v_pk_fma_f32 v[28:29], v[28:29], v[38:39], v[42:43] op_sel_hi:[1,0,1]
	v_mov_b32_e32 v38, v35
	v_pk_fma_f32 v[24:25], v[24:25], v[40:41], v[50:51] op_sel_hi:[1,0,1]
	v_mov_b32_e32 v40, v37
	v_pk_fma_f32 v[46:47], v[30:31], v[34:35], v[46:47] op_sel_hi:[1,1,0] neg_lo:[0,0,1] neg_hi:[0,0,1]
	v_pk_fma_f32 v[34:35], v[26:27], v[36:37], v[54:55] op_sel_hi:[1,1,0] neg_lo:[0,0,1] neg_hi:[0,0,1]
	v_pk_fma_f32 v[36:37], v[30:31], v[38:39], v[48:49] op_sel_hi:[1,1,0]
	v_pk_fma_f32 v[38:39], v[26:27], v[40:41], v[56:57] op_sel_hi:[1,1,0]
	v_sub_f32_e32 v28, v44, v42
	v_sub_f32_e32 v24, v52, v50
	v_mov_b32_e32 v30, v46
	v_mov_b32_e32 v26, v34
	v_mov_b32_e32 v31, v36
	v_mov_b32_e32 v27, v38
.LBB0_1616:
	s_or_b64 exec, exec, s[44:45]
	v_cvt_pk_bf16_f32 v28, v28, v29
	v_cvt_pk_bf16_f32 v29, v30, v31
	v_cvt_pk_bf16_f32 v30, v24, v25
	v_mov_b64_e32 v[24:25], s[16:17]
	v_mad_i64_i32 v[24:25], s[44:45], v32, s53, v[24:25]
	v_cvt_pk_bf16_f32 v31, v26, v27
	v_lshl_add_u64 v[24:25], v[146:147], 1, v[24:25]
	global_store_dwordx4 v[24:25], v[28:31], off offset:256
	v_add_u32_e32 v24, 0x90, v148
	v_ashrrev_i32_e32 v25, 31, v24
	s_and_saveexec_b64 s[44:45], s[38:39]
	s_cbranch_execz .LBB0_1618
	v_lshlrev_b64 v[26:27], 6, v[24:25]
	v_lshl_add_u64 v[30:31], v[136:137], 0, v[26:27]
	v_mov_b64_e32 v[26:27], v[220:221]
	v_mov_b64_e32 v[28:29], v[222:223]
	v_mov_b64_e32 v[30:31], v[224:225]
	v_mov_b64_e32 v[32:33], v[226:227]
	v_pk_mul_f32 v[34:35], v[20:21], v[26:27] op_sel:[1,0] op_sel_hi:[0,0]
	v_pk_mul_f32 v[42:43], v[16:17], v[28:29] op_sel:[1,0] op_sel_hi:[0,0]
	v_pk_mul_f32 v[36:37], v[20:21], v[30:31]
	v_mov_b32_e32 v26, v31
	v_mul_f32_e32 v38, v23, v27
	v_mul_f32_e32 v40, v23, v31
	v_pk_mul_f32 v[44:45], v[16:17], v[32:33]
	v_mov_b32_e32 v28, v33
	v_mul_f32_e32 v46, v19, v29
	v_mul_f32_e32 v48, v19, v33
	v_pk_fma_f32 v[20:21], v[20:21], v[30:31], v[34:35] op_sel_hi:[1,0,1]
	v_mov_b32_e32 v30, v27
	v_pk_fma_f32 v[16:17], v[16:17], v[32:33], v[42:43] op_sel_hi:[1,0,1]
	v_mov_b32_e32 v32, v29
	v_pk_fma_f32 v[38:39], v[22:23], v[26:27], v[38:39] op_sel_hi:[1,1,0] neg_lo:[0,0,1] neg_hi:[0,0,1]
	v_pk_fma_f32 v[26:27], v[18:19], v[28:29], v[46:47] op_sel_hi:[1,1,0] neg_lo:[0,0,1] neg_hi:[0,0,1]
	v_pk_fma_f32 v[28:29], v[22:23], v[30:31], v[40:41] op_sel_hi:[1,1,0]
	v_pk_fma_f32 v[30:31], v[18:19], v[32:33], v[48:49] op_sel_hi:[1,1,0]
	v_sub_f32_e32 v20, v36, v34
	v_sub_f32_e32 v16, v44, v42
	v_mov_b32_e32 v22, v38
	v_mov_b32_e32 v18, v26
	v_mov_b32_e32 v23, v28
	v_mov_b32_e32 v19, v30
.LBB0_1618:
	s_or_b64 exec, exec, s[44:45]
	v_cvt_pk_bf16_f32 v20, v20, v21
	v_cvt_pk_bf16_f32 v21, v22, v23
	v_cvt_pk_bf16_f32 v22, v16, v17
	v_mov_b64_e32 v[16:17], s[16:17]
	v_mad_i64_i32 v[16:17], s[44:45], v24, s53, v[16:17]
	v_cvt_pk_bf16_f32 v23, v18, v19
	v_lshl_add_u64 v[16:17], v[146:147], 1, v[16:17]
	global_store_dwordx4 v[16:17], v[20:23], off offset:256
	v_add_u32_e32 v16, 0xa0, v148
	v_ashrrev_i32_e32 v17, 31, v16
	s_and_saveexec_b64 s[44:45], s[38:39]
	s_cbranch_execz .LBB0_1620
	v_lshlrev_b64 v[18:19], 6, v[16:17]
	v_lshl_add_u64 v[22:23], v[136:137], 0, v[18:19]
	v_mov_b64_e32 v[18:19], v[228:229]
	v_mov_b64_e32 v[20:21], v[230:231]
	v_mov_b64_e32 v[22:23], v[232:233]
	v_mov_b64_e32 v[24:25], v[234:235]
	v_pk_mul_f32 v[26:27], v[12:13], v[18:19] op_sel:[1,0] op_sel_hi:[0,0]
	v_pk_mul_f32 v[34:35], v[8:9], v[20:21] op_sel:[1,0] op_sel_hi:[0,0]
	v_pk_mul_f32 v[28:29], v[12:13], v[22:23]
	v_mov_b32_e32 v18, v23
	v_mul_f32_e32 v30, v15, v19
	v_mul_f32_e32 v32, v15, v23
	v_pk_mul_f32 v[36:37], v[8:9], v[24:25]
	v_mov_b32_e32 v20, v25
	v_mul_f32_e32 v38, v11, v21
	v_mul_f32_e32 v40, v11, v25
	v_pk_fma_f32 v[12:13], v[12:13], v[22:23], v[26:27] op_sel_hi:[1,0,1]
	v_mov_b32_e32 v22, v19
	v_pk_fma_f32 v[8:9], v[8:9], v[24:25], v[34:35] op_sel_hi:[1,0,1]
	v_mov_b32_e32 v24, v21
	v_pk_fma_f32 v[30:31], v[14:15], v[18:19], v[30:31] op_sel_hi:[1,1,0] neg_lo:[0,0,1] neg_hi:[0,0,1]
	v_pk_fma_f32 v[18:19], v[10:11], v[20:21], v[38:39] op_sel_hi:[1,1,0] neg_lo:[0,0,1] neg_hi:[0,0,1]
	v_pk_fma_f32 v[20:21], v[14:15], v[22:23], v[32:33] op_sel_hi:[1,1,0]
	v_pk_fma_f32 v[22:23], v[10:11], v[24:25], v[40:41] op_sel_hi:[1,1,0]
	v_sub_f32_e32 v12, v28, v26
	v_sub_f32_e32 v8, v36, v34
	v_mov_b32_e32 v14, v30
	v_mov_b32_e32 v10, v18
	v_mov_b32_e32 v15, v20
	v_mov_b32_e32 v11, v22
.LBB0_1620:
	s_or_b64 exec, exec, s[44:45]
	v_cvt_pk_bf16_f32 v12, v12, v13
	v_cvt_pk_bf16_f32 v13, v14, v15
	v_cvt_pk_bf16_f32 v14, v8, v9
	v_mov_b64_e32 v[8:9], s[16:17]
	v_mad_i64_i32 v[8:9], s[44:45], v16, s53, v[8:9]
	v_cvt_pk_bf16_f32 v15, v10, v11
	v_lshl_add_u64 v[8:9], v[146:147], 1, v[8:9]
	global_store_dwordx4 v[8:9], v[12:15], off offset:256
	v_add_u32_e32 v8, 0xb0, v148
	v_ashrrev_i32_e32 v9, 31, v8
	s_and_saveexec_b64 s[44:45], s[38:39]
	s_cbranch_execz .LBB0_1622
	v_lshlrev_b64 v[10:11], 6, v[8:9]
	v_lshl_add_u64 v[14:15], v[136:137], 0, v[10:11]
	v_mov_b64_e32 v[10:11], v[240:241]
	v_mov_b64_e32 v[12:13], v[242:243]
	v_mov_b64_e32 v[14:15], v[244:245]
	v_mov_b64_e32 v[16:17], v[246:247]
	v_pk_mul_f32 v[18:19], v[4:5], v[10:11] op_sel:[1,0] op_sel_hi:[0,0]
	v_pk_mul_f32 v[26:27], v[0:1], v[12:13] op_sel:[1,0] op_sel_hi:[0,0]
	v_pk_mul_f32 v[20:21], v[4:5], v[14:15]
	v_mov_b32_e32 v10, v15
	v_mul_f32_e32 v22, v7, v11
	v_mul_f32_e32 v24, v7, v15
	v_pk_mul_f32 v[28:29], v[0:1], v[16:17]
	v_mov_b32_e32 v12, v17
	v_mul_f32_e32 v30, v3, v13
	v_mul_f32_e32 v32, v3, v17
	v_pk_fma_f32 v[4:5], v[4:5], v[14:15], v[18:19] op_sel_hi:[1,0,1]
	v_mov_b32_e32 v14, v11
	v_pk_fma_f32 v[0:1], v[0:1], v[16:17], v[26:27] op_sel_hi:[1,0,1]
	v_mov_b32_e32 v16, v13
	v_pk_fma_f32 v[22:23], v[6:7], v[10:11], v[22:23] op_sel_hi:[1,1,0] neg_lo:[0,0,1] neg_hi:[0,0,1]
	v_pk_fma_f32 v[10:11], v[2:3], v[12:13], v[30:31] op_sel_hi:[1,1,0] neg_lo:[0,0,1] neg_hi:[0,0,1]
	v_pk_fma_f32 v[12:13], v[6:7], v[14:15], v[24:25] op_sel_hi:[1,1,0]
	v_pk_fma_f32 v[14:15], v[2:3], v[16:17], v[32:33] op_sel_hi:[1,1,0]
	v_sub_f32_e32 v4, v20, v18
	v_sub_f32_e32 v0, v28, v26
	v_mov_b32_e32 v6, v22
	v_mov_b32_e32 v2, v10
	v_mov_b32_e32 v7, v12
	v_mov_b32_e32 v3, v14

.LBB0_2650:
	v_lshl_add_u64 v[234:235], v[166:167], 0, s[52:53]
	global_load_dword v61, v[234:235], off
	s_waitcnt vmcnt(0)
	s_mov_b64 s[12:13], -1
	s_and_b64 vcc, exec, s[42:43]
	s_cbranch_vccz .LBB0_2645

.LBB0_2653:
	s_andn2_b64 vcc, exec, s[12:13]
	s_cbranch_vccnz .LBB0_2655
	v_add_f32_e32 v63, v0, v61
	v_mul_f32_e32 v63, 0xbfb8aa3b, v63
	v_exp_f32_e32 v63, v63
	v_add_co_u32_e32 v234, vcc, 0x12c00000, v234
	v_add_f32_e32 v63, 1.0, v63
	v_rcp_f32_e32 v63, v63
	v_addc_co_u32_e32 v235, vcc, 0, v235, vcc
	v_cvt_pk_bf16_f32 v63, v63, s0
	global_store_short v[234:235], v63, off

.LBB0_2656:
	s_nop 1
	v_add_f32_e32 v0, v0, v61
	v_mul_f32_e64 v63, |v0|, s60
	v_exp_f32_e32 v67, v63
	s_nop 0
	v_cmp_ngt_f32_e32 vcc, s63, v67
	s_and_saveexec_b64 s[0:1], vcc
	s_xor_b64 s[14:15], exec, s[0:1]
	s_cbranch_execz .LBB0_2658
	v_add_f32_e32 v63, 1.0, v67
	v_cmp_gt_f32_e32 vcc, s64, v63
	s_nop 1
	v_cndmask_b32_e64 v67, 0, 32, vcc
	v_ldexp_f32 v63, v63, v67
	v_log_f32_e32 v63, v63
	s_nop 0
	v_mul_f32_e32 v67, 0x3f317217, v63
	v_fma_f32 v67, v63, s65, -v67
	v_fmac_f32_e32 v67, 0x3377d1cf, v63
	v_fmac_f32_e32 v67, 0x3f317217, v63
	v_cmp_lt_f32_e64 s[12:13], |v63|, s66
	s_nop 1
	v_cndmask_b32_e64 v63, v63, v67, s[12:13]
	v_cndmask_b32_e32 v67, 0, v238, vcc
	v_sub_f32_e32 v63, v63, v67

.LBB0_2693:
	s_andn2_b64 vcc, exec, s[16:17]
	s_cbranch_vccnz .LBB0_2695
	v_add_f32_e32 v0, v1, v61
	v_mul_f32_e32 v0, 0xbfb8aa3b, v0
	v_exp_f32_e32 v0, v0
	v_add_co_u32_e32 v234, vcc, 0x12c00000, v234
	v_add_f32_e32 v0, 1.0, v0
	v_rcp_f32_e32 v0, v0
	v_addc_co_u32_e32 v235, vcc, 0, v235, vcc
	v_cvt_pk_bf16_f32 v0, v0, s0
	global_store_short v[234:235], v0, off

.LBB0_2696:
	v_add_f32_e32 v0, v1, v61
	v_mul_f32_e64 v1, |v0|, s60
	v_exp_f32_e32 v63, v1
	s_nop 0
	v_cmp_ngt_f32_e32 vcc, s63, v63
	s_and_saveexec_b64 s[0:1], vcc
	s_xor_b64 s[54:55], exec, s[0:1]
	s_cbranch_execz .LBB0_2698
	v_add_f32_e32 v1, 1.0, v63
	v_cmp_gt_f32_e32 vcc, s64, v1
	s_nop 1
	v_cndmask_b32_e64 v63, 0, 32, vcc
	v_ldexp_f32 v1, v1, v63
	v_log_f32_e32 v1, v1
	s_nop 0
	v_mul_f32_e32 v63, 0x3f317217, v1
	v_fma_f32 v63, v1, s65, -v63
	v_fmac_f32_e32 v63, 0x3377d1cf, v1
	v_fmac_f32_e32 v63, 0x3f317217, v1
	v_cmp_lt_f32_e64 s[16:17], |v1|, s66
	s_nop 1
	v_cndmask_b32_e64 v1, v1, v63, s[16:17]
	v_cndmask_b32_e32 v63, 0, v238, vcc
	v_sub_f32_e32 v1, v1, v63

.LBB0_2703:
	s_andn2_b64 vcc, exec, s[16:17]
	s_cbranch_vccnz .LBB0_2705
	v_add_f32_e32 v63, v2, v61
	v_mul_f32_e32 v63, 0xbfb8aa3b, v63
	v_exp_f32_e32 v63, v63
	v_add_co_u32_e32 v0, vcc, 0x12c00000, v0
	v_add_f32_e32 v63, 1.0, v63
	v_rcp_f32_e32 v63, v63
	v_addc_co_u32_e32 v1, vcc, 0, v1, vcc
	v_cvt_pk_bf16_f32 v63, v63, s0
	global_store_short v[0:1], v63, off

.LBB0_2706:
	v_add_f32_e32 v0, v2, v61
	v_mul_f32_e64 v1, |v0|, s60
	v_exp_f32_e32 v2, v1
	s_nop 0
	v_cmp_ngt_f32_e32 vcc, s63, v2
	s_and_saveexec_b64 s[0:1], vcc
	s_xor_b64 s[54:55], exec, s[0:1]
	s_cbranch_execz .LBB0_2708
	v_add_f32_e32 v1, 1.0, v2
	v_cmp_gt_f32_e32 vcc, s64, v1
	s_nop 1
	v_cndmask_b32_e64 v2, 0, 32, vcc
	v_ldexp_f32 v1, v1, v2
	v_log_f32_e32 v1, v1
	s_nop 0
	v_mul_f32_e32 v2, 0x3f317217, v1
	v_fma_f32 v2, v1, s65, -v2
	v_fmac_f32_e32 v2, 0x3377d1cf, v1
	v_fmac_f32_e32 v2, 0x3f317217, v1
	v_cmp_lt_f32_e64 s[16:17], |v1|, s66
	s_nop 1
	v_cndmask_b32_e64 v1, v1, v2, s[16:17]
	v_cndmask_b32_e32 v2, 0, v238, vcc
	v_sub_f32_e32 v1, v1, v2

.LBB0_2713:
	s_andn2_b64 vcc, exec, s[16:17]
	s_cbranch_vccnz .LBB0_2715
	v_add_f32_e32 v2, v3, v61
	v_mul_f32_e32 v2, 0xbfb8aa3b, v2
	v_exp_f32_e32 v2, v2
	v_add_co_u32_e32 v0, vcc, 0x12c00000, v0
	v_add_f32_e32 v2, 1.0, v2
	v_rcp_f32_e32 v2, v2
	v_addc_co_u32_e32 v1, vcc, 0, v1, vcc
	v_cvt_pk_bf16_f32 v2, v2, s0
	global_store_short v[0:1], v2, off

.LBB0_2716:
	v_add_f32_e32 v0, v3, v61
	v_mul_f32_e64 v1, |v0|, s60
	v_exp_f32_e32 v2, v1
	s_nop 0
	v_cmp_ngt_f32_e32 vcc, s63, v2
	s_and_saveexec_b64 s[0:1], vcc
	s_xor_b64 s[54:55], exec, s[0:1]
	s_cbranch_execz .LBB0_2718
	v_add_f32_e32 v1, 1.0, v2
	v_cmp_gt_f32_e32 vcc, s64, v1
	s_nop 1
	v_cndmask_b32_e64 v2, 0, 32, vcc
	v_ldexp_f32 v1, v1, v2
	v_log_f32_e32 v1, v1
	s_nop 0
	v_mul_f32_e32 v2, 0x3f317217, v1
	v_fma_f32 v2, v1, s65, -v2
	v_fmac_f32_e32 v2, 0x3377d1cf, v1
	v_fmac_f32_e32 v2, 0x3f317217, v1
	v_cmp_lt_f32_e64 s[16:17], |v1|, s66
	s_nop 1
	v_cndmask_b32_e64 v1, v1, v2, s[16:17]
	v_cndmask_b32_e32 v2, 0, v238, vcc
	v_sub_f32_e32 v1, v1, v2

.LBB0_2723:
	s_andn2_b64 vcc, exec, s[16:17]
	s_cbranch_vccnz .LBB0_2725
	v_add_f32_e32 v2, v4, v61
	v_mul_f32_e32 v2, 0xbfb8aa3b, v2
	v_exp_f32_e32 v2, v2
	v_add_co_u32_e32 v0, vcc, 0x12c00000, v0
	v_add_f32_e32 v2, 1.0, v2
	v_rcp_f32_e32 v2, v2
	v_addc_co_u32_e32 v1, vcc, 0, v1, vcc
	v_cvt_pk_bf16_f32 v2, v2, s0
	global_store_short v[0:1], v2, off

.LBB0_2726:
	v_add_f32_e32 v0, v4, v61
	v_mul_f32_e64 v1, |v0|, s60
	v_exp_f32_e32 v2, v1
	s_nop 0
	v_cmp_ngt_f32_e32 vcc, s63, v2
	s_and_saveexec_b64 s[0:1], vcc
	s_xor_b64 s[54:55], exec, s[0:1]
	s_cbranch_execz .LBB0_2728
	v_add_f32_e32 v1, 1.0, v2
	v_cmp_gt_f32_e32 vcc, s64, v1
	s_nop 1
	v_cndmask_b32_e64 v2, 0, 32, vcc
	v_ldexp_f32 v1, v1, v2
	v_log_f32_e32 v1, v1
	s_nop 0
	v_mul_f32_e32 v2, 0x3f317217, v1
	v_fma_f32 v2, v1, s65, -v2
	v_fmac_f32_e32 v2, 0x3377d1cf, v1
	v_fmac_f32_e32 v2, 0x3f317217, v1
	v_cmp_lt_f32_e64 s[16:17], |v1|, s66
	s_nop 1
	v_cndmask_b32_e64 v1, v1, v2, s[16:17]
	v_cndmask_b32_e32 v2, 0, v238, vcc
	v_sub_f32_e32 v1, v1, v2

.LBB0_2733:
	s_andn2_b64 vcc, exec, s[16:17]
	s_cbranch_vccnz .LBB0_2735
	v_add_f32_e32 v2, v5, v61
	v_mul_f32_e32 v2, 0xbfb8aa3b, v2
	v_exp_f32_e32 v2, v2
	v_add_co_u32_e32 v0, vcc, 0x12c00000, v0
	v_add_f32_e32 v2, 1.0, v2
	v_rcp_f32_e32 v2, v2
	v_addc_co_u32_e32 v1, vcc, 0, v1, vcc
	v_cvt_pk_bf16_f32 v2, v2, s0
	global_store_short v[0:1], v2, off

.LBB0_2736:
	v_add_f32_e32 v0, v5, v61
	v_mul_f32_e64 v1, |v0|, s60
	v_exp_f32_e32 v2, v1
	s_nop 0
	v_cmp_ngt_f32_e32 vcc, s63, v2
	s_and_saveexec_b64 s[0:1], vcc
	s_xor_b64 s[54:55], exec, s[0:1]
	s_cbranch_execz .LBB0_2738
	v_add_f32_e32 v1, 1.0, v2
	v_cmp_gt_f32_e32 vcc, s64, v1
	s_nop 1
	v_cndmask_b32_e64 v2, 0, 32, vcc
	v_ldexp_f32 v1, v1, v2
	v_log_f32_e32 v1, v1
	s_nop 0
	v_mul_f32_e32 v2, 0x3f317217, v1
	v_fma_f32 v2, v1, s65, -v2
	v_fmac_f32_e32 v2, 0x3377d1cf, v1
	v_fmac_f32_e32 v2, 0x3f317217, v1
	v_cmp_lt_f32_e64 s[16:17], |v1|, s66
	s_nop 1
	v_cndmask_b32_e64 v1, v1, v2, s[16:17]
	v_cndmask_b32_e32 v2, 0, v238, vcc
	v_sub_f32_e32 v1, v1, v2

.LBB0_2743:
	s_andn2_b64 vcc, exec, s[16:17]
	s_cbranch_vccnz .LBB0_2745
	v_add_f32_e32 v2, v6, v61
	v_mul_f32_e32 v2, 0xbfb8aa3b, v2
	v_exp_f32_e32 v2, v2
	v_add_co_u32_e32 v0, vcc, 0x12c00000, v0
	v_add_f32_e32 v2, 1.0, v2
	v_rcp_f32_e32 v2, v2
	v_addc_co_u32_e32 v1, vcc, 0, v1, vcc
	v_cvt_pk_bf16_f32 v2, v2, s0
	global_store_short v[0:1], v2, off

.LBB0_2746:
	v_add_f32_e32 v0, v6, v61
	v_mul_f32_e64 v1, |v0|, s60
	v_exp_f32_e32 v2, v1
	s_nop 0
	v_cmp_ngt_f32_e32 vcc, s63, v2
	s_and_saveexec_b64 s[0:1], vcc
	s_xor_b64 s[54:55], exec, s[0:1]
	s_cbranch_execz .LBB0_2748
	v_add_f32_e32 v1, 1.0, v2
	v_cmp_gt_f32_e32 vcc, s64, v1
	s_nop 1
	v_cndmask_b32_e64 v2, 0, 32, vcc
	v_ldexp_f32 v1, v1, v2
	v_log_f32_e32 v1, v1
	s_nop 0
	v_mul_f32_e32 v2, 0x3f317217, v1
	v_fma_f32 v2, v1, s65, -v2
	v_fmac_f32_e32 v2, 0x3377d1cf, v1
	v_fmac_f32_e32 v2, 0x3f317217, v1
	v_cmp_lt_f32_e64 s[16:17], |v1|, s66
	s_nop 1
	v_cndmask_b32_e64 v1, v1, v2, s[16:17]
	v_cndmask_b32_e32 v2, 0, v238, vcc
	v_sub_f32_e32 v1, v1, v2

.LBB0_2753:
	s_andn2_b64 vcc, exec, s[16:17]
	s_cbranch_vccnz .LBB0_2755
	v_add_f32_e32 v2, v7, v61
	v_mul_f32_e32 v2, 0xbfb8aa3b, v2
	v_exp_f32_e32 v2, v2
	v_add_co_u32_e32 v0, vcc, 0x12c00000, v0
	v_add_f32_e32 v2, 1.0, v2
	v_rcp_f32_e32 v2, v2
	v_addc_co_u32_e32 v1, vcc, 0, v1, vcc
	v_cvt_pk_bf16_f32 v2, v2, s0
	global_store_short v[0:1], v2, off

.LBB0_2756:
	v_add_f32_e32 v0, v7, v61
	v_mul_f32_e64 v1, |v0|, s60
	v_exp_f32_e32 v2, v1
	s_nop 0
	v_cmp_ngt_f32_e32 vcc, s63, v2
	s_and_saveexec_b64 s[0:1], vcc
	s_xor_b64 s[54:55], exec, s[0:1]
	s_cbranch_execz .LBB0_2758
	v_add_f32_e32 v1, 1.0, v2
	v_cmp_gt_f32_e32 vcc, s64, v1
	s_nop 1
	v_cndmask_b32_e64 v2, 0, 32, vcc
	v_ldexp_f32 v1, v1, v2
	v_log_f32_e32 v1, v1
	s_nop 0
	v_mul_f32_e32 v2, 0x3f317217, v1
	v_fma_f32 v2, v1, s65, -v2
	v_fmac_f32_e32 v2, 0x3377d1cf, v1
	v_fmac_f32_e32 v2, 0x3f317217, v1
	v_cmp_lt_f32_e64 s[16:17], |v1|, s66
	s_nop 1
	v_cndmask_b32_e64 v1, v1, v2, s[16:17]
	v_cndmask_b32_e32 v2, 0, v238, vcc
	v_sub_f32_e32 v1, v1, v2

.LBB0_2763:
	s_andn2_b64 vcc, exec, s[16:17]
	s_cbranch_vccnz .LBB0_2765
	v_add_f32_e32 v2, v8, v61
	v_mul_f32_e32 v2, 0xbfb8aa3b, v2
	v_exp_f32_e32 v2, v2
	v_add_co_u32_e32 v0, vcc, 0x12c00000, v0
	v_add_f32_e32 v2, 1.0, v2
	v_rcp_f32_e32 v2, v2
	v_addc_co_u32_e32 v1, vcc, 0, v1, vcc
	v_cvt_pk_bf16_f32 v2, v2, s0
	global_store_short v[0:1], v2, off

.LBB0_2766:
	v_add_f32_e32 v0, v8, v61
	v_mul_f32_e64 v1, |v0|, s60
	v_exp_f32_e32 v2, v1
	s_nop 0
	v_cmp_ngt_f32_e32 vcc, s63, v2
	s_and_saveexec_b64 s[0:1], vcc
	s_xor_b64 s[54:55], exec, s[0:1]
	s_cbranch_execz .LBB0_2768
	v_add_f32_e32 v1, 1.0, v2
	v_cmp_gt_f32_e32 vcc, s64, v1
	s_nop 1
	v_cndmask_b32_e64 v2, 0, 32, vcc
	v_ldexp_f32 v1, v1, v2
	v_log_f32_e32 v1, v1
	s_nop 0
	v_mul_f32_e32 v2, 0x3f317217, v1
	v_fma_f32 v2, v1, s65, -v2
	v_fmac_f32_e32 v2, 0x3377d1cf, v1
	v_fmac_f32_e32 v2, 0x3f317217, v1
	v_cmp_lt_f32_e64 s[16:17], |v1|, s66
	s_nop 1
	v_cndmask_b32_e64 v1, v1, v2, s[16:17]
	v_cndmask_b32_e32 v2, 0, v238, vcc
	v_sub_f32_e32 v1, v1, v2

.LBB0_2773:
	s_andn2_b64 vcc, exec, s[16:17]
	s_cbranch_vccnz .LBB0_2775
	v_add_f32_e32 v2, v9, v61
	v_mul_f32_e32 v2, 0xbfb8aa3b, v2
	v_exp_f32_e32 v2, v2
	v_add_co_u32_e32 v0, vcc, 0x12c00000, v0
	v_add_f32_e32 v2, 1.0, v2
	v_rcp_f32_e32 v2, v2
	v_addc_co_u32_e32 v1, vcc, 0, v1, vcc
	v_cvt_pk_bf16_f32 v2, v2, s0
	global_store_short v[0:1], v2, off

.LBB0_2776:
	v_add_f32_e32 v0, v9, v61
	v_mul_f32_e64 v1, |v0|, s60
	v_exp_f32_e32 v2, v1
	s_nop 0
	v_cmp_ngt_f32_e32 vcc, s63, v2
	s_and_saveexec_b64 s[0:1], vcc
	s_xor_b64 s[54:55], exec, s[0:1]
	s_cbranch_execz .LBB0_2778
	v_add_f32_e32 v1, 1.0, v2
	v_cmp_gt_f32_e32 vcc, s64, v1
	s_nop 1
	v_cndmask_b32_e64 v2, 0, 32, vcc
	v_ldexp_f32 v1, v1, v2
	v_log_f32_e32 v1, v1
	s_nop 0
	v_mul_f32_e32 v2, 0x3f317217, v1
	v_fma_f32 v2, v1, s65, -v2
	v_fmac_f32_e32 v2, 0x3377d1cf, v1
	v_fmac_f32_e32 v2, 0x3f317217, v1
	v_cmp_lt_f32_e64 s[16:17], |v1|, s66
	s_nop 1
	v_cndmask_b32_e64 v1, v1, v2, s[16:17]
	v_cndmask_b32_e32 v2, 0, v238, vcc
	v_sub_f32_e32 v1, v1, v2

.LBB0_2783:
	s_andn2_b64 vcc, exec, s[16:17]
	s_cbranch_vccnz .LBB0_2785
	v_add_f32_e32 v2, v10, v61
	v_mul_f32_e32 v2, 0xbfb8aa3b, v2
	v_exp_f32_e32 v2, v2
	v_add_co_u32_e32 v0, vcc, 0x12c00000, v0
	v_add_f32_e32 v2, 1.0, v2
	v_rcp_f32_e32 v2, v2
	v_addc_co_u32_e32 v1, vcc, 0, v1, vcc
	v_cvt_pk_bf16_f32 v2, v2, s0
	global_store_short v[0:1], v2, off

.LBB0_2786:
	v_add_f32_e32 v0, v10, v61
	v_mul_f32_e64 v1, |v0|, s60
	v_exp_f32_e32 v2, v1
	s_nop 0
	v_cmp_ngt_f32_e32 vcc, s63, v2
	s_and_saveexec_b64 s[0:1], vcc
	s_xor_b64 s[54:55], exec, s[0:1]
	s_cbranch_execz .LBB0_2788
	v_add_f32_e32 v1, 1.0, v2
	v_cmp_gt_f32_e32 vcc, s64, v1
	s_nop 1
	v_cndmask_b32_e64 v2, 0, 32, vcc
	v_ldexp_f32 v1, v1, v2
	v_log_f32_e32 v1, v1
	s_nop 0
	v_mul_f32_e32 v2, 0x3f317217, v1
	v_fma_f32 v2, v1, s65, -v2
	v_fmac_f32_e32 v2, 0x3377d1cf, v1
	v_fmac_f32_e32 v2, 0x3f317217, v1
	v_cmp_lt_f32_e64 s[16:17], |v1|, s66
	s_nop 1
	v_cndmask_b32_e64 v1, v1, v2, s[16:17]
	v_cndmask_b32_e32 v2, 0, v238, vcc
	v_sub_f32_e32 v1, v1, v2

.LBB0_2793:
	s_andn2_b64 vcc, exec, s[16:17]
	s_cbranch_vccnz .LBB0_2795
	v_add_f32_e32 v2, v11, v61
	v_mul_f32_e32 v2, 0xbfb8aa3b, v2
	v_exp_f32_e32 v2, v2
	v_add_co_u32_e32 v0, vcc, 0x12c00000, v0
	v_add_f32_e32 v2, 1.0, v2
	v_rcp_f32_e32 v2, v2
	v_addc_co_u32_e32 v1, vcc, 0, v1, vcc
	v_cvt_pk_bf16_f32 v2, v2, s0
	global_store_short v[0:1], v2, off

.LBB0_2796:
	v_add_f32_e32 v0, v11, v61
	v_mul_f32_e64 v1, |v0|, s60
	v_exp_f32_e32 v2, v1
	s_nop 0
	v_cmp_ngt_f32_e32 vcc, s63, v2
	s_and_saveexec_b64 s[0:1], vcc
	s_xor_b64 s[54:55], exec, s[0:1]
	s_cbranch_execz .LBB0_2798
	v_add_f32_e32 v1, 1.0, v2
	v_cmp_gt_f32_e32 vcc, s64, v1
	s_nop 1
	v_cndmask_b32_e64 v2, 0, 32, vcc
	v_ldexp_f32 v1, v1, v2
	v_log_f32_e32 v1, v1
	s_nop 0
	v_mul_f32_e32 v2, 0x3f317217, v1
	v_fma_f32 v2, v1, s65, -v2
	v_fmac_f32_e32 v2, 0x3377d1cf, v1
	v_fmac_f32_e32 v2, 0x3f317217, v1
	v_cmp_lt_f32_e64 s[16:17], |v1|, s66
	s_nop 1
	v_cndmask_b32_e64 v1, v1, v2, s[16:17]
	v_cndmask_b32_e32 v2, 0, v238, vcc
	v_sub_f32_e32 v1, v1, v2

.LBB0_2803:
	s_andn2_b64 vcc, exec, s[16:17]
	s_cbranch_vccnz .LBB0_2805
	v_add_f32_e32 v2, v12, v61
	v_mul_f32_e32 v2, 0xbfb8aa3b, v2
	v_exp_f32_e32 v2, v2
	v_add_co_u32_e32 v0, vcc, 0x12c00000, v0
	v_add_f32_e32 v2, 1.0, v2
	v_rcp_f32_e32 v2, v2
	v_addc_co_u32_e32 v1, vcc, 0, v1, vcc
	v_cvt_pk_bf16_f32 v2, v2, s0
	global_store_short v[0:1], v2, off

.LBB0_2806:
	v_add_f32_e32 v0, v12, v61
	v_mul_f32_e64 v1, |v0|, s60
	v_exp_f32_e32 v2, v1
	s_nop 0
	v_cmp_ngt_f32_e32 vcc, s63, v2
	s_and_saveexec_b64 s[0:1], vcc
	s_xor_b64 s[54:55], exec, s[0:1]
	s_cbranch_execz .LBB0_2808
	v_add_f32_e32 v1, 1.0, v2
	v_cmp_gt_f32_e32 vcc, s64, v1
	s_nop 1
	v_cndmask_b32_e64 v2, 0, 32, vcc
	v_ldexp_f32 v1, v1, v2
	v_log_f32_e32 v1, v1
	s_nop 0
	v_mul_f32_e32 v2, 0x3f317217, v1
	v_fma_f32 v2, v1, s65, -v2
	v_fmac_f32_e32 v2, 0x3377d1cf, v1
	v_fmac_f32_e32 v2, 0x3f317217, v1
	v_cmp_lt_f32_e64 s[16:17], |v1|, s66
	s_nop 1
	v_cndmask_b32_e64 v1, v1, v2, s[16:17]
	v_cndmask_b32_e32 v2, 0, v238, vcc
	v_sub_f32_e32 v1, v1, v2

.LBB0_2813:
	s_andn2_b64 vcc, exec, s[16:17]
	s_cbranch_vccnz .LBB0_2815
	v_add_f32_e32 v2, v13, v61
	v_mul_f32_e32 v2, 0xbfb8aa3b, v2
	v_exp_f32_e32 v2, v2
	v_add_co_u32_e32 v0, vcc, 0x12c00000, v0
	v_add_f32_e32 v2, 1.0, v2
	v_rcp_f32_e32 v2, v2
	v_addc_co_u32_e32 v1, vcc, 0, v1, vcc
	v_cvt_pk_bf16_f32 v2, v2, s0
	global_store_short v[0:1], v2, off

.LBB0_2816:
	v_add_f32_e32 v0, v13, v61
	v_mul_f32_e64 v1, |v0|, s60
	v_exp_f32_e32 v2, v1
	s_nop 0
	v_cmp_ngt_f32_e32 vcc, s63, v2
	s_and_saveexec_b64 s[0:1], vcc
	s_xor_b64 s[54:55], exec, s[0:1]
	s_cbranch_execz .LBB0_2818
	v_add_f32_e32 v1, 1.0, v2
	v_cmp_gt_f32_e32 vcc, s64, v1
	s_nop 1
	v_cndmask_b32_e64 v2, 0, 32, vcc
	v_ldexp_f32 v1, v1, v2
	v_log_f32_e32 v1, v1
	s_nop 0
	v_mul_f32_e32 v2, 0x3f317217, v1
	v_fma_f32 v2, v1, s65, -v2
	v_fmac_f32_e32 v2, 0x3377d1cf, v1
	v_fmac_f32_e32 v2, 0x3f317217, v1
	v_cmp_lt_f32_e64 s[16:17], |v1|, s66
	s_nop 1
	v_cndmask_b32_e64 v1, v1, v2, s[16:17]
	v_cndmask_b32_e32 v2, 0, v238, vcc
	v_sub_f32_e32 v1, v1, v2

.LBB0_2823:
	s_andn2_b64 vcc, exec, s[16:17]
	s_cbranch_vccnz .LBB0_2825
	v_add_f32_e32 v2, v14, v61
	v_mul_f32_e32 v2, 0xbfb8aa3b, v2
	v_exp_f32_e32 v2, v2
	v_add_co_u32_e32 v0, vcc, 0x12c00000, v0
	v_add_f32_e32 v2, 1.0, v2
	v_rcp_f32_e32 v2, v2
	v_addc_co_u32_e32 v1, vcc, 0, v1, vcc
	v_cvt_pk_bf16_f32 v2, v2, s0
	global_store_short v[0:1], v2, off

.LBB0_2826:
	v_add_f32_e32 v0, v14, v61
	v_mul_f32_e64 v1, |v0|, s60
	v_exp_f32_e32 v2, v1
	s_nop 0
	v_cmp_ngt_f32_e32 vcc, s63, v2
	s_and_saveexec_b64 s[0:1], vcc
	s_xor_b64 s[54:55], exec, s[0:1]
	s_cbranch_execz .LBB0_2828
	v_add_f32_e32 v1, 1.0, v2
	v_cmp_gt_f32_e32 vcc, s64, v1
	s_nop 1
	v_cndmask_b32_e64 v2, 0, 32, vcc
	v_ldexp_f32 v1, v1, v2
	v_log_f32_e32 v1, v1
	s_nop 0
	v_mul_f32_e32 v2, 0x3f317217, v1
	v_fma_f32 v2, v1, s65, -v2
	v_fmac_f32_e32 v2, 0x3377d1cf, v1
	v_fmac_f32_e32 v2, 0x3f317217, v1
	v_cmp_lt_f32_e64 s[16:17], |v1|, s66
	s_nop 1
	v_cndmask_b32_e64 v1, v1, v2, s[16:17]
	v_cndmask_b32_e32 v2, 0, v238, vcc
	v_sub_f32_e32 v1, v1, v2

.LBB0_2833:
	s_andn2_b64 vcc, exec, s[14:15]
	s_cbranch_vccnz .LBB0_2835
	v_add_f32_e32 v2, v15, v61
	v_mul_f32_e32 v2, 0xbfb8aa3b, v2
	v_exp_f32_e32 v2, v2
	v_add_co_u32_e32 v0, vcc, 0x12c00000, v0
	v_add_f32_e32 v2, 1.0, v2
	v_rcp_f32_e32 v2, v2
	v_addc_co_u32_e32 v1, vcc, 0, v1, vcc
	v_cvt_pk_bf16_f32 v2, v2, s0
	global_store_short v[0:1], v2, off

.LBB0_2836:
	v_add_f32_e32 v0, v15, v61
	v_mul_f32_e64 v1, |v0|, s60
	v_exp_f32_e32 v2, v1
	s_nop 0
	v_cmp_ngt_f32_e32 vcc, s63, v2
	s_and_saveexec_b64 s[0:1], vcc
	s_xor_b64 s[14:15], exec, s[0:1]
	s_cbranch_execz .LBB0_2838
	v_add_f32_e32 v1, 1.0, v2
	v_cmp_gt_f32_e32 vcc, s64, v1
	s_nop 1
	v_cndmask_b32_e64 v2, 0, 32, vcc
	v_ldexp_f32 v1, v1, v2
	v_log_f32_e32 v1, v1
	s_nop 0
	v_mul_f32_e32 v2, 0x3f317217, v1
	v_fma_f32 v2, v1, s65, -v2
	v_fmac_f32_e32 v2, 0x3377d1cf, v1
	v_fmac_f32_e32 v2, 0x3f317217, v1
	v_cmp_lt_f32_e64 s[12:13], |v1|, s66
	s_nop 1
	v_cndmask_b32_e64 v1, v1, v2, s[12:13]
	v_cndmask_b32_e32 v2, 0, v238, vcc
	v_sub_f32_e32 v1, v1, v2

.LBB0_2840:
	v_readlane_b32 s0, v248, 6
	v_readlane_b32 s1, v248, 7
	s_andn2_b64 vcc, exec, s[0:1]
	s_cbranch_vccnz .LBB0_2984
	s_load_dwordx2 s[0:1], s[22:23], 0x38
	v_mov_b32_e32 v20, 0
	s_ashr_i32 s3, s2, 31
	s_movk_i32 s4, 0x1a20
	s_mov_b64 s[12:13], 0
	s_waitcnt lgkmcnt(0)
	global_load_dwordx4 v[0:3], v20, s[0:1] offset:32
	global_load_dwordx4 v[4:7], v20, s[0:1] offset:48
	s_lshl_b32 s0, s35, 10
	v_lshl_add_u32 v18, v65, 4, s0
	v_readlane_b32 s0, v248, 9
	s_add_u32 s0, s20, s0
	v_readlane_b32 s1, v248, 8
	s_addc_u32 s1, s21, s1
	v_ashrrev_i32_e32 v19, 31, v18
	v_mov_b64_e32 v[8:9], s[0:1]
	v_mad_i64_i32 v[8:9], s[0:1], v18, s4, v[8:9]
	s_mov_b64 s[0:1], 0x22c01a00
	s_nop 0
	v_lshl_add_u64 v[16:17], v[8:9], 0, s[0:1]
	s_mov_b32 s0, 0xbfb8aa3b
	s_mov_b32 s1, 0x3c23d70a
	s_mov_b32 s4, 0x800000
	s_mov_b32 s5, 0x3f317217
	s_mov_b32 s6, 0x7f800000
	s_mov_b32 s7, 0xbeaaaaab
	v_mov_b32_e32 v12, 0x41b17218
	v_mov_b32_e32 v21, v20
	v_mov_b32_e32 v26, v20
	v_mov_b32_e32 v27, v20
	v_mov_b32_e32 v24, v20
	v_mov_b32_e32 v25, v20
	v_mov_b32_e32 v22, v20
	v_mov_b32_e32 v23, v20
	s_mov_b64 s[100:101], 0x1a20
	v_mov_b64_e32 v[164:165], v[16:17]
	global_load_dwordx4 v[100:103], v[164:165], off
	v_lshl_add_u64 v[164:165], v[164:165], 0, s[100:101]
	global_load_dwordx4 v[104:107], v[164:165], off
	v_lshl_add_u64 v[164:165], v[164:165], 0, s[100:101]
	global_load_dwordx4 v[108:111], v[164:165], off
	v_lshl_add_u64 v[164:165], v[164:165], 0, s[100:101]
	global_load_dwordx4 v[112:115], v[164:165], off
	v_lshl_add_u64 v[164:165], v[164:165], 0, s[100:101]
	global_load_dwordx4 v[116:119], v[164:165], off
	v_lshl_add_u64 v[164:165], v[164:165], 0, s[100:101]
	global_load_dwordx4 v[120:123], v[164:165], off
	v_lshl_add_u64 v[164:165], v[164:165], 0, s[100:101]
	global_load_dwordx4 v[124:127], v[164:165], off
	v_lshl_add_u64 v[164:165], v[164:165], 0, s[100:101]
	global_load_dwordx4 v[128:131], v[164:165], off
	v_lshl_add_u64 v[164:165], v[164:165], 0, s[100:101]
	global_load_dwordx4 v[132:135], v[164:165], off
	v_lshl_add_u64 v[164:165], v[164:165], 0, s[100:101]
	global_load_dwordx4 v[136:139], v[164:165], off
	v_lshl_add_u64 v[164:165], v[164:165], 0, s[100:101]
	global_load_dwordx4 v[140:143], v[164:165], off
	v_lshl_add_u64 v[164:165], v[164:165], 0, s[100:101]
	global_load_dwordx4 v[144:147], v[164:165], off
	v_lshl_add_u64 v[164:165], v[164:165], 0, s[100:101]
	global_load_dwordx4 v[148:151], v[164:165], off
	v_lshl_add_u64 v[164:165], v[164:165], 0, s[100:101]
	global_load_dwordx4 v[152:155], v[164:165], off
	v_lshl_add_u64 v[164:165], v[164:165], 0, s[100:101]
	global_load_dwordx4 v[156:159], v[164:165], off
	v_lshl_add_u64 v[164:165], v[164:165], 0, s[100:101]
	global_load_dwordx4 v[160:163], v[164:165], off
	s_waitcnt vmcnt(0)
	s_branch .LBB0_2843

.LBB0_2843:
	v_mov_b64_e32 v[8:9], v[100:101]
	v_mov_b64_e32 v[10:11], v[102:103]
	v_mov_b64_e32 v[164:165], v[100:101]
	v_mov_b64_e32 v[166:167], v[102:103]
	v_mov_b64_e32 v[100:101], v[104:105]
	v_mov_b64_e32 v[102:103], v[106:107]
	v_mov_b64_e32 v[104:105], v[108:109]
	v_mov_b64_e32 v[106:107], v[110:111]
	v_mov_b64_e32 v[108:109], v[112:113]
	v_mov_b64_e32 v[110:111], v[114:115]
	v_mov_b64_e32 v[112:113], v[116:117]
	v_mov_b64_e32 v[114:115], v[118:119]
	v_mov_b64_e32 v[116:117], v[120:121]
	v_mov_b64_e32 v[118:119], v[122:123]
	v_mov_b64_e32 v[120:121], v[124:125]
	v_mov_b64_e32 v[122:123], v[126:127]
	v_mov_b64_e32 v[124:125], v[128:129]
	v_mov_b64_e32 v[126:127], v[130:131]
	v_mov_b64_e32 v[128:129], v[132:133]
	v_mov_b64_e32 v[130:131], v[134:135]
	v_mov_b64_e32 v[132:133], v[136:137]
	v_mov_b64_e32 v[134:135], v[138:139]
	v_mov_b64_e32 v[136:137], v[140:141]
	v_mov_b64_e32 v[138:139], v[142:143]
	v_mov_b64_e32 v[140:141], v[144:145]
	v_mov_b64_e32 v[142:143], v[146:147]
	v_mov_b64_e32 v[144:145], v[148:149]
	v_mov_b64_e32 v[146:147], v[150:151]
	v_mov_b64_e32 v[148:149], v[152:153]
	v_mov_b64_e32 v[150:151], v[154:155]
	v_mov_b64_e32 v[152:153], v[156:157]
	v_mov_b64_e32 v[154:155], v[158:159]
	v_mov_b64_e32 v[156:157], v[160:161]
	v_mov_b64_e32 v[158:159], v[162:163]
	v_mov_b64_e32 v[160:161], v[164:165]
	v_mov_b64_e32 v[162:163], v[166:167]
	v_lshlrev_b32_e32 v13, 16, v8
	v_add_f32_e32 v13, v0, v13
	v_mul_f32_e64 v14, |v13|, s0
	v_exp_f32_e32 v15, v14
	s_nop 0
	v_cmp_ngt_f32_e32 vcc, s1, v15
	s_and_saveexec_b64 s[8:9], vcc
	s_xor_b64 s[14:15], exec, s[8:9]
	s_cbranch_execz .LBB0_2845
	v_add_f32_e32 v14, 1.0, v15
	v_cmp_gt_f32_e32 vcc, s4, v14
	s_nop 1
	v_cndmask_b32_e64 v15, 0, 32, vcc
	v_ldexp_f32 v14, v14, v15
	v_log_f32_e32 v14, v14
	s_nop 0
	v_mul_f32_e32 v15, 0x3f317217, v14
	v_fma_f32 v15, v14, s5, -v15
	v_fmac_f32_e32 v15, 0x3377d1cf, v14
	v_fmac_f32_e32 v15, 0x3f317217, v14
	v_cmp_lt_f32_e64 s[10:11], |v14|, s6
	s_nop 1
	v_cndmask_b32_e64 v14, v14, v15, s[10:11]
	v_cndmask_b32_e32 v15, 0, v12, vcc
	v_sub_f32_e32 v14, v14, v15

.LBB0_2951:
	v_mov_b64_e32 v[8:9], v[100:101]
	v_mov_b64_e32 v[10:11], v[102:103]
	v_mov_b64_e32 v[164:165], v[100:101]
	v_mov_b64_e32 v[166:167], v[102:103]
	v_mov_b64_e32 v[100:101], v[104:105]
	v_mov_b64_e32 v[102:103], v[106:107]
	v_mov_b64_e32 v[104:105], v[108:109]
	v_mov_b64_e32 v[106:107], v[110:111]
	v_mov_b64_e32 v[108:109], v[112:113]
	v_mov_b64_e32 v[110:111], v[114:115]
	v_mov_b64_e32 v[112:113], v[116:117]
	v_mov_b64_e32 v[114:115], v[118:119]
	v_mov_b64_e32 v[116:117], v[120:121]
	v_mov_b64_e32 v[118:119], v[122:123]
	v_mov_b64_e32 v[120:121], v[124:125]
	v_mov_b64_e32 v[122:123], v[126:127]
	v_mov_b64_e32 v[124:125], v[128:129]
	v_mov_b64_e32 v[126:127], v[130:131]
	v_mov_b64_e32 v[128:129], v[132:133]
	v_mov_b64_e32 v[130:131], v[134:135]
	v_mov_b64_e32 v[132:133], v[136:137]
	v_mov_b64_e32 v[134:135], v[138:139]
	v_mov_b64_e32 v[136:137], v[140:141]
	v_mov_b64_e32 v[138:139], v[142:143]
	v_mov_b64_e32 v[140:141], v[144:145]
	v_mov_b64_e32 v[142:143], v[146:147]
	v_mov_b64_e32 v[144:145], v[148:149]
	v_mov_b64_e32 v[146:147], v[150:151]
	v_mov_b64_e32 v[148:149], v[152:153]
	v_mov_b64_e32 v[150:151], v[154:155]
	v_mov_b64_e32 v[152:153], v[156:157]
	v_mov_b64_e32 v[154:155], v[158:159]
	v_mov_b64_e32 v[156:157], v[160:161]
	v_mov_b64_e32 v[158:159], v[162:163]
	v_mov_b64_e32 v[160:161], v[164:165]
	v_mov_b64_e32 v[162:163], v[166:167]
	v_lshlrev_b32_e32 v25, 16, v8
	v_add_f32_e32 v25, v0, v25
	v_mul_f32_e64 v26, |v25|, s0
	v_exp_f32_e32 v27, v26
	s_nop 0
	v_cmp_ngt_f32_e32 vcc, s1, v27
	s_and_saveexec_b64 s[8:9], vcc
	s_xor_b64 s[16:17], exec, s[8:9]
	s_cbranch_execz .LBB0_2953
	v_add_f32_e32 v26, 1.0, v27
	v_cmp_gt_f32_e32 vcc, s3, v26
	s_nop 1
	v_cndmask_b32_e64 v27, 0, 32, vcc
	v_ldexp_f32 v26, v26, v27
	v_log_f32_e32 v26, v26
	s_nop 0
	v_mul_f32_e32 v27, 0x3f317217, v26
	v_fma_f32 v27, v26, s4, -v27
	v_fmac_f32_e32 v27, 0x3377d1cf, v26
	v_fmac_f32_e32 v27, 0x3f317217, v26
	v_cmp_lt_f32_e64 s[10:11], |v26|, s5
	s_nop 1
	v_cndmask_b32_e64 v26, v26, v27, s[10:11]
	v_cndmask_b32_e32 v27, 0, v24, vcc
	v_sub_f32_e32 v26, v26, v27

.LBB0_3079:
	s_or_b64 exec, exec, s[30:31]
	s_cmpk_eq_i32 s1, 0x100
	s_mov_b32 s0, s1
	s_cbranch_scc1 .LBB0_3039
.LBB0_3080:
	s_waitcnt vmcnt(4)
	v_lshlrev_b32_e32 v30, 16, v50
	v_and_b32_e32 v31, 0xffff0000, v50
	v_lshlrev_b32_e32 v32, 16, v51
	v_and_b32_e32 v33, 0xffff0000, v51
	v_lshlrev_b32_e32 v1, 16, v56
	v_and_b32_e32 v34, 0xffff0000, v56
	v_lshlrev_b32_e32 v46, 16, v57
	v_and_b32_e32 v35, 0xffff0000, v57
	s_waitcnt vmcnt(3)
	v_lshlrev_b32_e32 v36, 16, v52
	v_and_b32_e32 v37, 0xffff0000, v52
	v_lshlrev_b32_e32 v38, 16, v53
	v_and_b32_e32 v39, 0xffff0000, v53
	v_lshlrev_b32_e32 v47, 16, v58
	v_and_b32_e32 v84, 0xffff0000, v58
	v_lshlrev_b32_e32 v85, 16, v59
	v_and_b32_e32 v86, 0xffff0000, v59
	v_sub_f32_e32 v45, v34, v31
	v_sub_f32_e32 v44, v1, v30
	v_sub_f32_e32 v35, v35, v33
	v_sub_f32_e32 v34, v46, v32
	v_pk_fma_f32 v[34:35], v[4:5], v[34:35], v[32:33]
	v_pk_fma_f32 v[32:33], v[2:3], v[44:45], v[30:31]
	v_sub_f32_e32 v31, v84, v37
	v_sub_f32_e32 v30, v47, v36
	v_sub_f32_e32 v45, v86, v39
	v_sub_f32_e32 v44, v85, v38
	s_waitcnt vmcnt(2)
	v_lshlrev_b32_e32 v40, 16, v54
	v_and_b32_e32 v41, 0xffff0000, v54
	v_lshlrev_b32_e32 v42, 16, v55
	v_and_b32_e32 v43, 0xffff0000, v55
	v_lshlrev_b32_e32 v87, 16, v60
	v_and_b32_e32 v88, 0xffff0000, v60
	v_lshlrev_b32_e32 v89, 16, v61
	v_and_b32_e32 v90, 0xffff0000, v61
	v_pk_fma_f32 v[44:45], v[8:9], v[44:45], v[38:39]
	v_pk_fma_f32 v[30:31], v[6:7], v[30:31], v[36:37]
	v_sub_f32_e32 v37, v88, v41
	v_sub_f32_e32 v36, v87, v40
	v_sub_f32_e32 v39, v90, v43
	v_sub_f32_e32 v38, v89, v42
	v_pk_mul_f32 v[84:85], v[14:15], v[30:31]
	v_pk_mul_f32 v[86:87], v[16:17], v[44:45]
	v_pk_fma_f32 v[38:39], v[12:13], v[38:39], v[42:43]
	v_pk_fma_f32 v[36:37], v[10:11], v[36:37], v[40:41]
	v_pk_mul_f32 v[40:41], v[86:87], v[86:87]
	v_pk_mul_f32 v[42:43], v[84:85], v[84:85]
	s_waitcnt vmcnt(1)
	v_lshlrev_b32_e32 v48, 16, v70
	v_pk_mov_b32 v[46:47], v[42:43], v[40:41] op_sel:[1,0]
	v_mov_b32_e32 v43, v41
	v_pk_add_f32 v[40:41], v[46:47], v[42:43]
	v_and_b32_e32 v49, 0xffff0000, v70
	v_lshlrev_b32_e32 v80, 16, v71
	v_and_b32_e32 v81, 0xffff0000, v71
	v_add_f32_e32 v1, v40, v41
	v_pk_add_f32 v[40:41], v[80:81], -1.0 op_sel_hi:[1,0]
	v_pk_add_f32 v[42:43], v[48:49], -1.0 op_sel_hi:[1,0]
	v_add_f32_dpp v1, v1, v1 quad_perm:[1,0,3,2] row_mask:0xf bank_mask:0xf bound_ctrl:1
	v_pk_fma_f32 v[46:47], v[18:19], v[42:43], 1.0 op_sel_hi:[1,1,0]
	v_pk_fma_f32 v[40:41], v[20:21], v[40:41], 1.0 op_sel_hi:[1,1,0]
	v_add_f32_dpp v1, v1, v1 quad_perm:[2,3,0,1] row_mask:0xf bank_mask:0xf bound_ctrl:1
	v_pk_mul_f32 v[42:43], v[44:45], v[40:41]
	v_pk_mul_f32 v[40:41], v[30:31], v[46:47]
	v_add_f32_dpp v1, v1, v1 row_half_mirror row_mask:0xf bank_mask:0xf bound_ctrl:1
	v_pk_mul_f32 v[30:31], v[32:33], v[40:41]
	v_pk_mul_f32 v[44:45], v[34:35], v[42:43]
	v_add_f32_dpp v1, v1, v1 row_ror:8 row_mask:0xf bank_mask:0xf bound_ctrl:1
	v_max_f32_e32 v1, 0x179abe15, v1
	v_pk_mul_f32 v[44:45], v[24:25], v[44:45]
	v_pk_mul_f32 v[30:31], v[22:23], v[30:31]
	v_rsq_f32_e32 v88, v1
	v_add_f32_e32 v1, v30, v31
	v_add_f32_e32 v30, v44, v45
	s_waitcnt vmcnt(0)
	v_exp_f32_e32 v44, v26
	v_exp_f32_e32 v45, v27
	v_exp_f32_e32 v46, v28
	v_exp_f32_e32 v47, v29
	v_add_f32_e32 v1, v1, v30
	ds_write_b128 v155, v[44:47]
	s_nop 0
	v_add_f32_dpp v1, v1, v1 quad_perm:[1,0,3,2] row_mask:0xf bank_mask:0xf bound_ctrl:1
	v_pk_mul_f32 v[46:47], v[86:87], v[88:89] op_sel_hi:[1,0] neg_lo:[0,1] neg_hi:[0,1]
	v_pk_mul_f32 v[44:45], v[84:85], v[88:89] op_sel_hi:[1,0] neg_lo:[0,1] neg_hi:[0,1]
	v_add_f32_dpp v1, v1, v1 quad_perm:[2,3,0,1] row_mask:0xf bank_mask:0xf bound_ctrl:1
	ds_write_b128 v155, v[44:47] offset:8192
	v_pk_mul_f32 v[46:47], v[46:47], v[80:81] neg_lo:[1,0] neg_hi:[1,0]
	v_add_f32_dpp v1, v1, v1 row_half_mirror row_mask:0xf bank_mask:0xf bound_ctrl:1
	v_pk_mul_f32 v[44:45], v[44:45], v[48:49] neg_lo:[1,0] neg_hi:[1,0]
	ds_write_b128 v155, v[44:47] offset:16384
	ds_write_b128 v155, v[40:43] offset:24576
	ds_write_b128 v155, v[32:35] offset:32768
	ds_write_b128 v155, v[36:39] offset:40960
	v_mov_b32_dpp v30, v1 row_ror:8 row_mask:0xf bank_mask:0xf bound_ctrl:1
	s_and_saveexec_b64 s[30:31], s[20:21]
	v_add_f32_e32 v1, v1, v30
	s_bitcmp1_b32 s0, 0
	s_cselect_b32 s100, 0x10100, 0
	v_add_u32_e32 v111, s100, v160
	ds_write_b32 v111, v1 offset:49152
	s_or_b64 exec, exec, s[30:31]
	s_add_i32 s1, s0, 1
	s_cmpk_eq_i32 s0, 0xff
	s_waitcnt lgkmcnt(0)
	s_barrier
	s_cbranch_scc1 .LBB0_3086
	v_lshl_add_u32 v26, s1, 5, v154
	v_mad_i64_i32 v[28:29], s[4:5], v26, s72, v[68:69]
	v_add_co_u32_e32 v30, vcc, 0x1000, v28
	v_mov_b32_e32 v1, v0
	s_nop 0
	v_addc_co_u32_e32 v31, vcc, 0, v29, vcc
	global_load_dwordx2 v[50:51], v[28:29], off offset:3072
	global_load_dwordx2 v[52:53], v[30:31], off
	global_load_dwordx2 v[54:55], v[30:31], off offset:1024
	v_cmp_lt_i32_e32 vcc, 0, v26
	v_mov_b64_e32 v[60:61], v[0:1]
	v_mov_b64_e32 v[58:59], v[0:1]
	v_mov_b64_e32 v[56:57], v[0:1]
	s_and_saveexec_b64 s[30:31], vcc
	s_cbranch_execz .LBB0_3085
	global_load_dwordx2 v[56:57], v[28:29], off offset:-3616
	global_load_dwordx2 v[58:59], v[28:29], off offset:-2592
	global_load_dwordx2 v[60:61], v[28:29], off offset:-1568

.LBB0_3089:
	s_or_b64 exec, exec, s[30:31]
	s_waitcnt lgkmcnt(0)
	s_barrier
	ds_read_b128 v[30:33], v190 offset:49408
	ds_read_b128 v[34:37], v190 offset:49424
	ds_read_b128 v[38:41], v190 offset:49440
	ds_read_b128 v[42:45], v190 offset:49456
	s_waitcnt lgkmcnt(2)
	v_pk_add_f32 v[32:33], v[32:33], v[36:37]
	v_pk_add_f32 v[34:35], v[30:31], v[34:35]
	s_waitcnt lgkmcnt(1)
	v_pk_add_f32 v[36:37], v[32:33], v[40:41]
	ds_read_b128 v[30:33], v190 offset:49472
	v_pk_add_f32 v[34:35], v[34:35], v[38:39]
	s_waitcnt lgkmcnt(1)
	v_pk_add_f32 v[38:39], v[36:37], v[44:45]
	v_pk_add_f32 v[42:43], v[34:35], v[42:43]
	ds_read_b128 v[34:37], v190 offset:49488
	s_waitcnt lgkmcnt(1)
	v_pk_add_f32 v[44:45], v[38:39], v[32:33]
	ds_read_b128 v[38:41], v190 offset:49504
	v_pk_add_f32 v[42:43], v[42:43], v[30:31]
	ds_read_b128 v[30:33], v190 offset:49520
	s_waitcnt lgkmcnt(2)
	v_pk_add_f32 v[36:37], v[44:45], v[36:37]
	v_pk_add_f32 v[34:35], v[42:43], v[34:35]
	s_waitcnt lgkmcnt(1)
	v_pk_add_f32 v[36:37], v[36:37], v[40:41]
	v_pk_add_f32 v[34:35], v[34:35], v[38:39]
	s_waitcnt lgkmcnt(0)
	v_pk_add_f32 v[32:33], v[36:37], v[32:33]
	v_pk_add_f32 v[34:35], v[34:35], v[30:31]
	v_lshl_add_u32 v30, s0, 5, v154
	v_pk_add_f32 v[32:33], v[34:35], v[32:33]
	v_ashrrev_i32_e32 v31, 31, v30
	v_cvt_pk_bf16_f32 v1, v32, v33
	v_lshlrev_b64 v[32:33], 11, v[30:31]
	v_lshl_add_u64 v[32:33], v[66:67], 0, v[32:33]
	global_store_dword v[32:33], v1, off
	s_and_saveexec_b64 s[30:31], s[28:29]
	s_cbranch_execz .LBB0_3079
	s_bitcmp1_b32 s0, 0
	s_cselect_b32 s100, 0x10100, 0
	v_add_u32_e32 v111, s100, v160
	ds_read_b32 v1, v111 offset:49152
	v_lshlrev_b64 v[30:31], 5, v[30:31]
	v_lshl_add_u64 v[30:31], s[26:27], 0, v[30:31]
	s_waitcnt lgkmcnt(0)
	global_store_dword v[30:31], v1, off
	s_branch .LBB0_3079

.LBB0_3688:
	v_lshl_add_u32 v148, s30, 8, v150
	v_lshl_or_b32 v146, s28, 8, v152
	v_cmp_gt_i32_e32 vcc, s51, v146
	v_ashrrev_i32_e32 v149, 31, v148
	s_and_saveexec_b64 s[28:29], vcc
	s_cbranch_execz .LBB0_3706
	v_cmp_gt_i32_e32 vcc, s52, v146
	s_and_b64 s[30:31], s[8:9], vcc
	s_and_saveexec_b64 s[100:101], s[30:31]
	s_cbranch_execz .Lrotpf_1
	v_mov_b32_e32 v238, v148
	v_ashrrev_i32_e32 v239, 31, v238
	v_lshlrev_b64 v[238:239], 6, v[238:239]
	v_lshl_add_u64 v[238:239], v[136:137], 0, v[238:239]
	global_load_dwordx4 v[180:183], v[238:239], off offset:32
	global_load_dwordx4 v[184:187], v[238:239], off
	v_or_b32_e32 v238, 16, v148
	v_ashrrev_i32_e32 v239, 31, v238
	v_lshlrev_b64 v[238:239], 6, v[238:239]
	v_lshl_add_u64 v[238:239], v[136:137], 0, v[238:239]
	global_load_dwordx4 v[188:191], v[238:239], off offset:32
	global_load_dwordx4 v[192:195], v[238:239], off
	v_or_b32_e32 v238, 32, v148
	v_ashrrev_i32_e32 v239, 31, v238
	v_lshlrev_b64 v[238:239], 6, v[238:239]
	v_lshl_add_u64 v[238:239], v[136:137], 0, v[238:239]
	global_load_dwordx4 v[196:199], v[238:239], off offset:32
	global_load_dwordx4 v[200:203], v[238:239], off
	v_or_b32_e32 v238, 48, v148
	v_ashrrev_i32_e32 v239, 31, v238
	v_lshlrev_b64 v[238:239], 6, v[238:239]
	v_lshl_add_u64 v[238:239], v[136:137], 0, v[238:239]
	global_load_dwordx4 v[204:207], v[238:239], off offset:32
	global_load_dwordx4 v[208:211], v[238:239], off
	v_or_b32_e32 v238, 128, v148
	v_ashrrev_i32_e32 v239, 31, v238
	v_lshlrev_b64 v[238:239], 6, v[238:239]
	v_lshl_add_u64 v[238:239], v[136:137], 0, v[238:239]
	global_load_dwordx4 v[212:215], v[238:239], off offset:32
	global_load_dwordx4 v[216:219], v[238:239], off
	v_or_b32_e32 v238, 144, v148
	v_ashrrev_i32_e32 v239, 31, v238
	v_lshlrev_b64 v[238:239], 6, v[238:239]
	v_lshl_add_u64 v[238:239], v[136:137], 0, v[238:239]
	global_load_dwordx4 v[220:223], v[238:239], off offset:32
	global_load_dwordx4 v[224:227], v[238:239], off
	v_or_b32_e32 v238, 160, v148
	v_ashrrev_i32_e32 v239, 31, v238
	v_lshlrev_b64 v[238:239], 6, v[238:239]
	v_lshl_add_u64 v[238:239], v[136:137], 0, v[238:239]
	global_load_dwordx4 v[228:231], v[238:239], off offset:32
	global_load_dwordx4 v[232:235], v[238:239], off
	v_or_b32_e32 v238, 176, v148
	v_ashrrev_i32_e32 v239, 31, v238
	v_lshlrev_b64 v[238:239], 6, v[238:239]
	v_lshl_add_u64 v[238:239], v[136:137], 0, v[238:239]
	global_load_dwordx4 v[240:243], v[238:239], off offset:32
	global_load_dwordx4 v[244:247], v[238:239], off
	s_waitcnt vmcnt(0)
.Lrotpf_1:
	s_or_b64 exec, exec, s[100:101]
	s_and_saveexec_b64 s[40:41], s[30:31]
	s_cbranch_execz .LBB0_3691
	v_lshlrev_b64 v[156:157], 6, v[148:149]
	v_lshl_add_u64 v[160:161], v[136:137], 0, v[156:157]
	v_mov_b64_e32 v[156:157], v[180:181]
	v_mov_b64_e32 v[158:159], v[182:183]
	v_mov_b64_e32 v[160:161], v[184:185]
	v_mov_b64_e32 v[162:163], v[186:187]
	v_pk_mul_f32 v[164:165], v[124:125], v[156:157] op_sel:[1,0] op_sel_hi:[0,0]
	v_pk_mul_f32 v[172:173], v[120:121], v[158:159] op_sel:[1,0] op_sel_hi:[0,0]
	v_pk_mul_f32 v[166:167], v[124:125], v[160:161]
	v_mov_b32_e32 v156, v161
	v_mul_f32_e32 v168, v127, v157
	v_mul_f32_e32 v170, v127, v161
	v_pk_mul_f32 v[174:175], v[120:121], v[162:163]
	v_mov_b32_e32 v158, v163
	v_mul_f32_e32 v176, v123, v159
	v_mul_f32_e32 v178, v123, v163
	v_pk_fma_f32 v[124:125], v[124:125], v[160:161], v[164:165] op_sel_hi:[1,0,1]
	v_mov_b32_e32 v160, v157
	v_pk_fma_f32 v[120:121], v[120:121], v[162:163], v[172:173] op_sel_hi:[1,0,1]
	v_mov_b32_e32 v162, v159
	v_pk_fma_f32 v[168:169], v[126:127], v[156:157], v[168:169] op_sel_hi:[1,1,0] neg_lo:[0,0,1] neg_hi:[0,0,1]
	v_pk_fma_f32 v[156:157], v[122:123], v[158:159], v[176:177] op_sel_hi:[1,1,0] neg_lo:[0,0,1] neg_hi:[0,0,1]
	v_pk_fma_f32 v[158:159], v[126:127], v[160:161], v[170:171] op_sel_hi:[1,1,0]
	v_pk_fma_f32 v[160:161], v[122:123], v[162:163], v[178:179] op_sel_hi:[1,1,0]
	v_sub_f32_e32 v124, v166, v164
	v_sub_f32_e32 v120, v174, v172
	v_mov_b32_e32 v126, v168
	v_mov_b32_e32 v122, v156
	v_mov_b32_e32 v127, v158
	v_mov_b32_e32 v123, v160
.LBB0_3691:
	s_or_b64 exec, exec, s[40:41]
	v_cvt_pk_bf16_f32 v124, v124, v125
	v_cvt_pk_bf16_f32 v125, v126, v127
	v_cvt_pk_bf16_f32 v126, v120, v121
	v_mov_b64_e32 v[120:121], s[14:15]
	v_ashrrev_i32_e32 v147, 31, v146
	v_mad_i64_i32 v[120:121], s[40:41], v148, s53, v[120:121]
	v_cvt_pk_bf16_f32 v127, v122, v123
	v_lshl_add_u64 v[120:121], v[146:147], 1, v[120:121]
	global_store_dwordx4 v[120:121], v[124:127], off
	v_or_b32_e32 v120, 16, v148
	v_ashrrev_i32_e32 v121, 31, v120
	s_and_saveexec_b64 s[40:41], s[30:31]
	s_cbranch_execz .LBB0_3693
	v_lshlrev_b64 v[122:123], 6, v[120:121]
	v_lshl_add_u64 v[126:127], v[136:137], 0, v[122:123]
	v_mov_b64_e32 v[122:123], v[188:189]
	v_mov_b64_e32 v[124:125], v[190:191]
	v_mov_b64_e32 v[156:157], v[192:193]
	v_mov_b64_e32 v[158:159], v[194:195]
	v_pk_mul_f32 v[126:127], v[116:117], v[122:123] op_sel:[1,0] op_sel_hi:[0,0]
	v_pk_mul_f32 v[166:167], v[112:113], v[124:125] op_sel:[1,0] op_sel_hi:[0,0]
	v_pk_mul_f32 v[160:161], v[116:117], v[156:157]
	v_mov_b32_e32 v122, v157
	v_mul_f32_e32 v162, v119, v123
	v_mul_f32_e32 v164, v119, v157
	v_pk_mul_f32 v[168:169], v[112:113], v[158:159]
	v_mov_b32_e32 v124, v159
	v_mul_f32_e32 v170, v115, v125
	v_mul_f32_e32 v172, v115, v159
	v_pk_fma_f32 v[116:117], v[116:117], v[156:157], v[126:127] op_sel_hi:[1,0,1]
	v_mov_b32_e32 v156, v123
	v_pk_fma_f32 v[112:113], v[112:113], v[158:159], v[166:167] op_sel_hi:[1,0,1]
	v_mov_b32_e32 v158, v125
	v_pk_fma_f32 v[162:163], v[118:119], v[122:123], v[162:163] op_sel_hi:[1,1,0] neg_lo:[0,0,1] neg_hi:[0,0,1]
	v_pk_fma_f32 v[122:123], v[114:115], v[124:125], v[170:171] op_sel_hi:[1,1,0] neg_lo:[0,0,1] neg_hi:[0,0,1]
	v_pk_fma_f32 v[124:125], v[118:119], v[156:157], v[164:165] op_sel_hi:[1,1,0]
	v_pk_fma_f32 v[156:157], v[114:115], v[158:159], v[172:173] op_sel_hi:[1,1,0]
	v_sub_f32_e32 v116, v160, v126
	v_sub_f32_e32 v112, v168, v166
	v_mov_b32_e32 v118, v162
	v_mov_b32_e32 v114, v122
	v_mov_b32_e32 v119, v124
	v_mov_b32_e32 v115, v156
.LBB0_3693:
	s_or_b64 exec, exec, s[40:41]
	v_cvt_pk_bf16_f32 v116, v116, v117
	v_cvt_pk_bf16_f32 v117, v118, v119
	v_cvt_pk_bf16_f32 v118, v112, v113
	v_mov_b64_e32 v[112:113], s[14:15]
	v_mad_i64_i32 v[112:113], s[40:41], v120, s53, v[112:113]
	v_cvt_pk_bf16_f32 v119, v114, v115
	v_lshl_add_u64 v[112:113], v[146:147], 1, v[112:113]
	global_store_dwordx4 v[112:113], v[116:119], off
	v_or_b32_e32 v112, 32, v148
	v_ashrrev_i32_e32 v113, 31, v112
	s_and_saveexec_b64 s[40:41], s[30:31]
	s_cbranch_execz .LBB0_3695
	v_lshlrev_b64 v[114:115], 6, v[112:113]
	v_lshl_add_u64 v[118:119], v[136:137], 0, v[114:115]
	v_mov_b64_e32 v[114:115], v[196:197]
	v_mov_b64_e32 v[116:117], v[198:199]
	v_mov_b64_e32 v[118:119], v[200:201]
	v_mov_b64_e32 v[120:121], v[202:203]
	v_pk_mul_f32 v[122:123], v[108:109], v[114:115] op_sel:[1,0] op_sel_hi:[0,0]
	v_pk_mul_f32 v[158:159], v[104:105], v[116:117] op_sel:[1,0] op_sel_hi:[0,0]
	v_pk_mul_f32 v[124:125], v[108:109], v[118:119]
	v_mov_b32_e32 v114, v119
	v_mul_f32_e32 v126, v111, v115
	v_mul_f32_e32 v156, v111, v119
	v_pk_mul_f32 v[160:161], v[104:105], v[120:121]
	v_mov_b32_e32 v116, v121
	v_mul_f32_e32 v162, v107, v117
	v_mul_f32_e32 v164, v107, v121
	v_pk_fma_f32 v[108:109], v[108:109], v[118:119], v[122:123] op_sel_hi:[1,0,1]
	v_mov_b32_e32 v118, v115
	v_pk_fma_f32 v[104:105], v[104:105], v[120:121], v[158:159] op_sel_hi:[1,0,1]
	v_mov_b32_e32 v120, v117
	v_pk_fma_f32 v[126:127], v[110:111], v[114:115], v[126:127] op_sel_hi:[1,1,0] neg_lo:[0,0,1] neg_hi:[0,0,1]
	v_pk_fma_f32 v[114:115], v[106:107], v[116:117], v[162:163] op_sel_hi:[1,1,0] neg_lo:[0,0,1] neg_hi:[0,0,1]
	v_pk_fma_f32 v[116:117], v[110:111], v[118:119], v[156:157] op_sel_hi:[1,1,0]
	v_pk_fma_f32 v[118:119], v[106:107], v[120:121], v[164:165] op_sel_hi:[1,1,0]
	v_sub_f32_e32 v108, v124, v122
	v_sub_f32_e32 v104, v160, v158
	v_mov_b32_e32 v110, v126
	v_mov_b32_e32 v106, v114
	v_mov_b32_e32 v111, v116
	v_mov_b32_e32 v107, v118
.LBB0_3695:
	s_or_b64 exec, exec, s[40:41]
	v_cvt_pk_bf16_f32 v108, v108, v109
	v_cvt_pk_bf16_f32 v109, v110, v111
	v_cvt_pk_bf16_f32 v110, v104, v105
	v_mov_b64_e32 v[104:105], s[14:15]
	v_mad_i64_i32 v[104:105], s[40:41], v112, s53, v[104:105]
	v_cvt_pk_bf16_f32 v111, v106, v107
	v_lshl_add_u64 v[104:105], v[146:147], 1, v[104:105]
	global_store_dwordx4 v[104:105], v[108:111], off
	v_or_b32_e32 v104, 48, v148
	v_ashrrev_i32_e32 v105, 31, v104
	s_and_saveexec_b64 s[40:41], s[30:31]
	s_cbranch_execz .LBB0_3697
	v_lshlrev_b64 v[106:107], 6, v[104:105]
	v_lshl_add_u64 v[110:111], v[136:137], 0, v[106:107]
	v_mov_b64_e32 v[106:107], v[204:205]
	v_mov_b64_e32 v[108:109], v[206:207]
	v_mov_b64_e32 v[110:111], v[208:209]
	v_mov_b64_e32 v[112:113], v[210:211]
	v_pk_mul_f32 v[114:115], v[100:101], v[106:107] op_sel:[1,0] op_sel_hi:[0,0]
	v_pk_mul_f32 v[122:123], v[96:97], v[108:109] op_sel:[1,0] op_sel_hi:[0,0]
	v_pk_mul_f32 v[116:117], v[100:101], v[110:111]
	v_mov_b32_e32 v106, v111
	v_mul_f32_e32 v118, v103, v107
	v_mul_f32_e32 v120, v103, v111
	v_pk_mul_f32 v[124:125], v[96:97], v[112:113]
	v_mov_b32_e32 v108, v113
	v_mul_f32_e32 v126, v99, v109
	v_mul_f32_e32 v156, v99, v113
	v_pk_fma_f32 v[100:101], v[100:101], v[110:111], v[114:115] op_sel_hi:[1,0,1]
	v_mov_b32_e32 v110, v107
	v_pk_fma_f32 v[96:97], v[96:97], v[112:113], v[122:123] op_sel_hi:[1,0,1]
	v_mov_b32_e32 v112, v109
	v_pk_fma_f32 v[118:119], v[102:103], v[106:107], v[118:119] op_sel_hi:[1,1,0] neg_lo:[0,0,1] neg_hi:[0,0,1]
	v_pk_fma_f32 v[106:107], v[98:99], v[108:109], v[126:127] op_sel_hi:[1,1,0] neg_lo:[0,0,1] neg_hi:[0,0,1]
	v_pk_fma_f32 v[108:109], v[102:103], v[110:111], v[120:121] op_sel_hi:[1,1,0]
	v_pk_fma_f32 v[110:111], v[98:99], v[112:113], v[156:157] op_sel_hi:[1,1,0]
	v_sub_f32_e32 v100, v116, v114
	v_sub_f32_e32 v96, v124, v122
	v_mov_b32_e32 v102, v118
	v_mov_b32_e32 v98, v106
	v_mov_b32_e32 v103, v108
	v_mov_b32_e32 v99, v110
.LBB0_3697:
	s_or_b64 exec, exec, s[40:41]
	v_cvt_pk_bf16_f32 v100, v100, v101
	v_cvt_pk_bf16_f32 v101, v102, v103
	v_cvt_pk_bf16_f32 v102, v96, v97
	v_mov_b64_e32 v[96:97], s[14:15]
	v_mad_i64_i32 v[96:97], s[40:41], v104, s53, v[96:97]
	v_cvt_pk_bf16_f32 v103, v98, v99
	v_lshl_add_u64 v[96:97], v[146:147], 1, v[96:97]
	global_store_dwordx4 v[96:97], v[100:103], off
	v_add_u32_e32 v96, 0x80, v148
	v_ashrrev_i32_e32 v97, 31, v96
	s_and_saveexec_b64 s[40:41], s[30:31]
	s_cbranch_execz .LBB0_3699
	v_lshlrev_b64 v[98:99], 6, v[96:97]
	v_lshl_add_u64 v[102:103], v[136:137], 0, v[98:99]
	v_mov_b64_e32 v[98:99], v[212:213]
	v_mov_b64_e32 v[100:101], v[214:215]
	v_mov_b64_e32 v[102:103], v[216:217]
	v_mov_b64_e32 v[104:105], v[218:219]
	v_pk_mul_f32 v[106:107], v[92:93], v[98:99] op_sel:[1,0] op_sel_hi:[0,0]
	v_pk_mul_f32 v[114:115], v[88:89], v[100:101] op_sel:[1,0] op_sel_hi:[0,0]
	v_pk_mul_f32 v[108:109], v[92:93], v[102:103]
	v_mov_b32_e32 v98, v103
	v_mul_f32_e32 v110, v95, v99
	v_mul_f32_e32 v112, v95, v103
	v_pk_mul_f32 v[116:117], v[88:89], v[104:105]
	v_mov_b32_e32 v100, v105
	v_mul_f32_e32 v118, v91, v101
	v_mul_f32_e32 v120, v91, v105
	v_pk_fma_f32 v[92:93], v[92:93], v[102:103], v[106:107] op_sel_hi:[1,0,1]
	v_mov_b32_e32 v102, v99
	v_pk_fma_f32 v[88:89], v[88:89], v[104:105], v[114:115] op_sel_hi:[1,0,1]
	v_mov_b32_e32 v104, v101
	v_pk_fma_f32 v[110:111], v[94:95], v[98:99], v[110:111] op_sel_hi:[1,1,0] neg_lo:[0,0,1] neg_hi:[0,0,1]
	v_pk_fma_f32 v[98:99], v[90:91], v[100:101], v[118:119] op_sel_hi:[1,1,0] neg_lo:[0,0,1] neg_hi:[0,0,1]
	v_pk_fma_f32 v[100:101], v[94:95], v[102:103], v[112:113] op_sel_hi:[1,1,0]
	v_pk_fma_f32 v[102:103], v[90:91], v[104:105], v[120:121] op_sel_hi:[1,1,0]
	v_sub_f32_e32 v92, v108, v106
	v_sub_f32_e32 v88, v116, v114
	v_mov_b32_e32 v94, v110
	v_mov_b32_e32 v90, v98
	v_mov_b32_e32 v95, v100
	v_mov_b32_e32 v91, v102
.LBB0_3699:
	s_or_b64 exec, exec, s[40:41]
	v_cvt_pk_bf16_f32 v92, v92, v93
	v_cvt_pk_bf16_f32 v93, v94, v95
	v_cvt_pk_bf16_f32 v94, v88, v89
	v_mov_b64_e32 v[88:89], s[14:15]
	v_mad_i64_i32 v[88:89], s[40:41], v96, s53, v[88:89]
	v_cvt_pk_bf16_f32 v95, v90, v91
	v_lshl_add_u64 v[88:89], v[146:147], 1, v[88:89]
	global_store_dwordx4 v[88:89], v[92:95], off
	v_add_u32_e32 v88, 0x90, v148
	v_ashrrev_i32_e32 v89, 31, v88
	s_and_saveexec_b64 s[40:41], s[30:31]
	s_cbranch_execz .LBB0_3701
	v_lshlrev_b64 v[90:91], 6, v[88:89]
	v_lshl_add_u64 v[94:95], v[136:137], 0, v[90:91]
	v_mov_b64_e32 v[90:91], v[220:221]
	v_mov_b64_e32 v[92:93], v[222:223]
	v_mov_b64_e32 v[94:95], v[224:225]
	v_mov_b64_e32 v[96:97], v[226:227]
	v_pk_mul_f32 v[98:99], v[84:85], v[90:91] op_sel:[1,0] op_sel_hi:[0,0]
	v_pk_mul_f32 v[106:107], v[80:81], v[92:93] op_sel:[1,0] op_sel_hi:[0,0]
	v_pk_mul_f32 v[100:101], v[84:85], v[94:95]
	v_mov_b32_e32 v90, v95
	v_mul_f32_e32 v102, v87, v91
	v_mul_f32_e32 v104, v87, v95
	v_pk_mul_f32 v[108:109], v[80:81], v[96:97]
	v_mov_b32_e32 v92, v97
	v_mul_f32_e32 v110, v83, v93
	v_mul_f32_e32 v112, v83, v97
	v_pk_fma_f32 v[84:85], v[84:85], v[94:95], v[98:99] op_sel_hi:[1,0,1]
	v_mov_b32_e32 v94, v91
	v_pk_fma_f32 v[80:81], v[80:81], v[96:97], v[106:107] op_sel_hi:[1,0,1]
	v_mov_b32_e32 v96, v93
	v_pk_fma_f32 v[102:103], v[86:87], v[90:91], v[102:103] op_sel_hi:[1,1,0] neg_lo:[0,0,1] neg_hi:[0,0,1]
	v_pk_fma_f32 v[90:91], v[82:83], v[92:93], v[110:111] op_sel_hi:[1,1,0] neg_lo:[0,0,1] neg_hi:[0,0,1]
	v_pk_fma_f32 v[92:93], v[86:87], v[94:95], v[104:105] op_sel_hi:[1,1,0]
	v_pk_fma_f32 v[94:95], v[82:83], v[96:97], v[112:113] op_sel_hi:[1,1,0]
	v_sub_f32_e32 v84, v100, v98
	v_sub_f32_e32 v80, v108, v106
	v_mov_b32_e32 v86, v102
	v_mov_b32_e32 v82, v90
	v_mov_b32_e32 v87, v92
	v_mov_b32_e32 v83, v94
.LBB0_3701:
	s_or_b64 exec, exec, s[40:41]
	v_cvt_pk_bf16_f32 v84, v84, v85
	v_cvt_pk_bf16_f32 v85, v86, v87
	v_cvt_pk_bf16_f32 v86, v80, v81
	v_mov_b64_e32 v[80:81], s[14:15]
	v_mad_i64_i32 v[80:81], s[40:41], v88, s53, v[80:81]
	v_cvt_pk_bf16_f32 v87, v82, v83
	v_lshl_add_u64 v[80:81], v[146:147], 1, v[80:81]
	global_store_dwordx4 v[80:81], v[84:87], off
	v_add_u32_e32 v80, 0xa0, v148
	v_ashrrev_i32_e32 v81, 31, v80
	s_and_saveexec_b64 s[40:41], s[30:31]
	s_cbranch_execz .LBB0_3703
	v_lshlrev_b64 v[82:83], 6, v[80:81]
	v_lshl_add_u64 v[86:87], v[136:137], 0, v[82:83]
	v_mov_b64_e32 v[82:83], v[228:229]
	v_mov_b64_e32 v[84:85], v[230:231]
	v_mov_b64_e32 v[86:87], v[232:233]
	v_mov_b64_e32 v[88:89], v[234:235]
	v_pk_mul_f32 v[90:91], v[76:77], v[82:83] op_sel:[1,0] op_sel_hi:[0,0]
	v_pk_mul_f32 v[98:99], v[72:73], v[84:85] op_sel:[1,0] op_sel_hi:[0,0]
	v_pk_mul_f32 v[92:93], v[76:77], v[86:87]
	v_mov_b32_e32 v82, v87
	v_mul_f32_e32 v94, v79, v83
	v_mul_f32_e32 v96, v79, v87
	v_pk_mul_f32 v[100:101], v[72:73], v[88:89]
	v_mov_b32_e32 v84, v89
	v_mul_f32_e32 v102, v75, v85
	v_mul_f32_e32 v104, v75, v89
	v_pk_fma_f32 v[76:77], v[76:77], v[86:87], v[90:91] op_sel_hi:[1,0,1]
	v_mov_b32_e32 v86, v83
	v_pk_fma_f32 v[72:73], v[72:73], v[88:89], v[98:99] op_sel_hi:[1,0,1]
	v_mov_b32_e32 v88, v85
	v_pk_fma_f32 v[94:95], v[78:79], v[82:83], v[94:95] op_sel_hi:[1,1,0] neg_lo:[0,0,1] neg_hi:[0,0,1]
	v_pk_fma_f32 v[82:83], v[74:75], v[84:85], v[102:103] op_sel_hi:[1,1,0] neg_lo:[0,0,1] neg_hi:[0,0,1]
	v_pk_fma_f32 v[84:85], v[78:79], v[86:87], v[96:97] op_sel_hi:[1,1,0]
	v_pk_fma_f32 v[86:87], v[74:75], v[88:89], v[104:105] op_sel_hi:[1,1,0]
	v_sub_f32_e32 v76, v92, v90
	v_sub_f32_e32 v72, v100, v98
	v_mov_b32_e32 v78, v94
	v_mov_b32_e32 v74, v82
	v_mov_b32_e32 v79, v84
	v_mov_b32_e32 v75, v86
.LBB0_3703:
	s_or_b64 exec, exec, s[40:41]
	v_cvt_pk_bf16_f32 v76, v76, v77
	v_cvt_pk_bf16_f32 v77, v78, v79
	v_cvt_pk_bf16_f32 v78, v72, v73
	v_mov_b64_e32 v[72:73], s[14:15]
	v_mad_i64_i32 v[72:73], s[40:41], v80, s53, v[72:73]
	v_cvt_pk_bf16_f32 v79, v74, v75
	v_lshl_add_u64 v[72:73], v[146:147], 1, v[72:73]
	global_store_dwordx4 v[72:73], v[76:79], off
	v_add_u32_e32 v72, 0xb0, v148
	v_ashrrev_i32_e32 v73, 31, v72
	s_and_saveexec_b64 s[40:41], s[30:31]
	s_cbranch_execz .LBB0_3705
	v_lshlrev_b64 v[74:75], 6, v[72:73]
	v_lshl_add_u64 v[78:79], v[136:137], 0, v[74:75]
	v_mov_b64_e32 v[74:75], v[240:241]
	v_mov_b64_e32 v[76:77], v[242:243]
	v_mov_b64_e32 v[78:79], v[244:245]
	v_mov_b64_e32 v[80:81], v[246:247]
	v_pk_mul_f32 v[82:83], v[68:69], v[74:75] op_sel:[1,0] op_sel_hi:[0,0]
	v_pk_mul_f32 v[90:91], v[64:65], v[76:77] op_sel:[1,0] op_sel_hi:[0,0]
	v_pk_mul_f32 v[84:85], v[68:69], v[78:79]
	v_mov_b32_e32 v74, v79
	v_mul_f32_e32 v86, v71, v75
	v_mul_f32_e32 v88, v71, v79
	v_pk_mul_f32 v[92:93], v[64:65], v[80:81]
	v_mov_b32_e32 v76, v81
	v_mul_f32_e32 v94, v67, v77
	v_mul_f32_e32 v96, v67, v81
	v_pk_fma_f32 v[68:69], v[68:69], v[78:79], v[82:83] op_sel_hi:[1,0,1]
	v_mov_b32_e32 v78, v75
	v_pk_fma_f32 v[64:65], v[64:65], v[80:81], v[90:91] op_sel_hi:[1,0,1]
	v_mov_b32_e32 v80, v77
	v_pk_fma_f32 v[86:87], v[70:71], v[74:75], v[86:87] op_sel_hi:[1,1,0] neg_lo:[0,0,1] neg_hi:[0,0,1]
	v_pk_fma_f32 v[74:75], v[66:67], v[76:77], v[94:95] op_sel_hi:[1,1,0] neg_lo:[0,0,1] neg_hi:[0,0,1]
	v_pk_fma_f32 v[76:77], v[70:71], v[78:79], v[88:89] op_sel_hi:[1,1,0]
	v_pk_fma_f32 v[78:79], v[66:67], v[80:81], v[96:97] op_sel_hi:[1,1,0]
	v_sub_f32_e32 v68, v84, v82
	v_sub_f32_e32 v64, v92, v90
	v_mov_b32_e32 v70, v86
	v_mov_b32_e32 v66, v74
	v_mov_b32_e32 v71, v76
	v_mov_b32_e32 v67, v78

.LBB0_3706:
	s_or_b64 exec, exec, s[28:29]
	v_or_b32_e32 v64, 0x80, v146
	v_cmp_gt_i32_e32 vcc, s51, v64
	s_and_saveexec_b64 s[28:29], vcc
	s_cbranch_execz .LBB0_3724
	v_cmp_gt_i32_e32 vcc, s52, v64
	s_and_b64 s[30:31], s[8:9], vcc
	s_and_saveexec_b64 s[40:41], s[30:31]
	s_cbranch_execz .LBB0_3709
	v_lshlrev_b64 v[64:65], 6, v[148:149]
	v_lshl_add_u64 v[68:69], v[136:137], 0, v[64:65]
	v_mov_b64_e32 v[64:65], v[180:181]
	v_mov_b64_e32 v[66:67], v[182:183]
	v_mov_b64_e32 v[68:69], v[184:185]
	v_mov_b64_e32 v[70:71], v[186:187]
	v_pk_mul_f32 v[72:73], v[60:61], v[64:65] op_sel:[1,0] op_sel_hi:[0,0]
	v_pk_mul_f32 v[80:81], v[56:57], v[66:67] op_sel:[1,0] op_sel_hi:[0,0]
	v_pk_mul_f32 v[74:75], v[60:61], v[68:69]
	v_mov_b32_e32 v64, v69
	v_mul_f32_e32 v76, v63, v65
	v_mul_f32_e32 v78, v63, v69
	v_pk_mul_f32 v[82:83], v[56:57], v[70:71]
	v_mov_b32_e32 v66, v71
	v_mul_f32_e32 v84, v59, v67
	v_mul_f32_e32 v86, v59, v71
	v_pk_fma_f32 v[60:61], v[60:61], v[68:69], v[72:73] op_sel_hi:[1,0,1]
	v_mov_b32_e32 v68, v65
	v_pk_fma_f32 v[56:57], v[56:57], v[70:71], v[80:81] op_sel_hi:[1,0,1]
	v_mov_b32_e32 v70, v67
	v_pk_fma_f32 v[76:77], v[62:63], v[64:65], v[76:77] op_sel_hi:[1,1,0] neg_lo:[0,0,1] neg_hi:[0,0,1]
	v_pk_fma_f32 v[64:65], v[58:59], v[66:67], v[84:85] op_sel_hi:[1,1,0] neg_lo:[0,0,1] neg_hi:[0,0,1]
	v_pk_fma_f32 v[66:67], v[62:63], v[68:69], v[78:79] op_sel_hi:[1,1,0]
	v_pk_fma_f32 v[68:69], v[58:59], v[70:71], v[86:87] op_sel_hi:[1,1,0]
	v_sub_f32_e32 v60, v74, v72
	v_sub_f32_e32 v56, v82, v80
	v_mov_b32_e32 v62, v76
	v_mov_b32_e32 v58, v64
	v_mov_b32_e32 v63, v66
	v_mov_b32_e32 v59, v68
.LBB0_3709:
	s_or_b64 exec, exec, s[40:41]
	v_cvt_pk_bf16_f32 v60, v60, v61
	v_cvt_pk_bf16_f32 v61, v62, v63
	v_cvt_pk_bf16_f32 v62, v56, v57
	v_mov_b64_e32 v[56:57], s[14:15]
	v_mad_i64_i32 v[56:57], s[40:41], v148, s53, v[56:57]
	v_ashrrev_i32_e32 v147, 31, v146
	v_cvt_pk_bf16_f32 v63, v58, v59
	v_lshl_add_u64 v[56:57], v[146:147], 1, v[56:57]
	global_store_dwordx4 v[56:57], v[60:63], off offset:256
	v_or_b32_e32 v56, 16, v148
	v_ashrrev_i32_e32 v57, 31, v56
	s_and_saveexec_b64 s[40:41], s[30:31]
	s_cbranch_execz .LBB0_3711
	v_lshlrev_b64 v[58:59], 6, v[56:57]
	v_lshl_add_u64 v[62:63], v[136:137], 0, v[58:59]
	v_mov_b64_e32 v[58:59], v[188:189]
	v_mov_b64_e32 v[60:61], v[190:191]
	v_mov_b64_e32 v[62:63], v[192:193]
	v_mov_b64_e32 v[64:65], v[194:195]
	v_pk_mul_f32 v[66:67], v[52:53], v[58:59] op_sel:[1,0] op_sel_hi:[0,0]
	v_pk_mul_f32 v[74:75], v[48:49], v[60:61] op_sel:[1,0] op_sel_hi:[0,0]
	v_pk_mul_f32 v[68:69], v[52:53], v[62:63]
	v_mov_b32_e32 v58, v63
	v_mul_f32_e32 v70, v55, v59
	v_mul_f32_e32 v72, v55, v63
	v_pk_mul_f32 v[76:77], v[48:49], v[64:65]
	v_mov_b32_e32 v60, v65
	v_mul_f32_e32 v78, v51, v61
	v_mul_f32_e32 v80, v51, v65
	v_pk_fma_f32 v[52:53], v[52:53], v[62:63], v[66:67] op_sel_hi:[1,0,1]
	v_mov_b32_e32 v62, v59
	v_pk_fma_f32 v[48:49], v[48:49], v[64:65], v[74:75] op_sel_hi:[1,0,1]
	v_mov_b32_e32 v64, v61
	v_pk_fma_f32 v[70:71], v[54:55], v[58:59], v[70:71] op_sel_hi:[1,1,0] neg_lo:[0,0,1] neg_hi:[0,0,1]
	v_pk_fma_f32 v[58:59], v[50:51], v[60:61], v[78:79] op_sel_hi:[1,1,0] neg_lo:[0,0,1] neg_hi:[0,0,1]
	v_pk_fma_f32 v[60:61], v[54:55], v[62:63], v[72:73] op_sel_hi:[1,1,0]
	v_pk_fma_f32 v[62:63], v[50:51], v[64:65], v[80:81] op_sel_hi:[1,1,0]
	v_sub_f32_e32 v52, v68, v66
	v_sub_f32_e32 v48, v76, v74
	v_mov_b32_e32 v54, v70
	v_mov_b32_e32 v50, v58
	v_mov_b32_e32 v55, v60
	v_mov_b32_e32 v51, v62
.LBB0_3711:
	s_or_b64 exec, exec, s[40:41]
	v_cvt_pk_bf16_f32 v52, v52, v53
	v_cvt_pk_bf16_f32 v53, v54, v55
	v_cvt_pk_bf16_f32 v54, v48, v49
	v_mov_b64_e32 v[48:49], s[14:15]
	v_mad_i64_i32 v[48:49], s[40:41], v56, s53, v[48:49]
	v_cvt_pk_bf16_f32 v55, v50, v51
	v_lshl_add_u64 v[48:49], v[146:147], 1, v[48:49]
	global_store_dwordx4 v[48:49], v[52:55], off offset:256
	v_or_b32_e32 v48, 32, v148
	v_ashrrev_i32_e32 v49, 31, v48
	s_and_saveexec_b64 s[40:41], s[30:31]
	s_cbranch_execz .LBB0_3713
	v_lshlrev_b64 v[50:51], 6, v[48:49]
	v_lshl_add_u64 v[54:55], v[136:137], 0, v[50:51]
	v_mov_b64_e32 v[50:51], v[196:197]
	v_mov_b64_e32 v[52:53], v[198:199]
	v_mov_b64_e32 v[54:55], v[200:201]
	v_mov_b64_e32 v[56:57], v[202:203]
	v_pk_mul_f32 v[58:59], v[44:45], v[50:51] op_sel:[1,0] op_sel_hi:[0,0]
	v_pk_mul_f32 v[66:67], v[40:41], v[52:53] op_sel:[1,0] op_sel_hi:[0,0]
	v_pk_mul_f32 v[60:61], v[44:45], v[54:55]
	v_mov_b32_e32 v50, v55
	v_mul_f32_e32 v62, v47, v51
	v_mul_f32_e32 v64, v47, v55
	v_pk_mul_f32 v[68:69], v[40:41], v[56:57]
	v_mov_b32_e32 v52, v57
	v_mul_f32_e32 v70, v43, v53
	v_mul_f32_e32 v72, v43, v57
	v_pk_fma_f32 v[44:45], v[44:45], v[54:55], v[58:59] op_sel_hi:[1,0,1]
	v_mov_b32_e32 v54, v51
	v_pk_fma_f32 v[40:41], v[40:41], v[56:57], v[66:67] op_sel_hi:[1,0,1]
	v_mov_b32_e32 v56, v53
	v_pk_fma_f32 v[62:63], v[46:47], v[50:51], v[62:63] op_sel_hi:[1,1,0] neg_lo:[0,0,1] neg_hi:[0,0,1]
	v_pk_fma_f32 v[50:51], v[42:43], v[52:53], v[70:71] op_sel_hi:[1,1,0] neg_lo:[0,0,1] neg_hi:[0,0,1]
	v_pk_fma_f32 v[52:53], v[46:47], v[54:55], v[64:65] op_sel_hi:[1,1,0]
	v_pk_fma_f32 v[54:55], v[42:43], v[56:57], v[72:73] op_sel_hi:[1,1,0]
	v_sub_f32_e32 v44, v60, v58
	v_sub_f32_e32 v40, v68, v66
	v_mov_b32_e32 v46, v62
	v_mov_b32_e32 v42, v50
	v_mov_b32_e32 v47, v52
	v_mov_b32_e32 v43, v54
.LBB0_3713:
	s_or_b64 exec, exec, s[40:41]
	v_cvt_pk_bf16_f32 v44, v44, v45
	v_cvt_pk_bf16_f32 v45, v46, v47
	v_cvt_pk_bf16_f32 v46, v40, v41
	v_mov_b64_e32 v[40:41], s[14:15]
	v_mad_i64_i32 v[40:41], s[40:41], v48, s53, v[40:41]
	v_cvt_pk_bf16_f32 v47, v42, v43
	v_lshl_add_u64 v[40:41], v[146:147], 1, v[40:41]
	global_store_dwordx4 v[40:41], v[44:47], off offset:256
	v_or_b32_e32 v40, 48, v148
	v_ashrrev_i32_e32 v41, 31, v40
	s_and_saveexec_b64 s[40:41], s[30:31]
	s_cbranch_execz .LBB0_3715
	v_lshlrev_b64 v[42:43], 6, v[40:41]
	v_lshl_add_u64 v[46:47], v[136:137], 0, v[42:43]
	v_mov_b64_e32 v[42:43], v[204:205]
	v_mov_b64_e32 v[44:45], v[206:207]
	v_mov_b64_e32 v[46:47], v[208:209]
	v_mov_b64_e32 v[48:49], v[210:211]
	v_pk_mul_f32 v[50:51], v[36:37], v[42:43] op_sel:[1,0] op_sel_hi:[0,0]
	v_pk_mul_f32 v[58:59], v[32:33], v[44:45] op_sel:[1,0] op_sel_hi:[0,0]
	v_pk_mul_f32 v[52:53], v[36:37], v[46:47]
	v_mov_b32_e32 v42, v47
	v_mul_f32_e32 v54, v39, v43
	v_mul_f32_e32 v56, v39, v47
	v_pk_mul_f32 v[60:61], v[32:33], v[48:49]
	v_mov_b32_e32 v44, v49
	v_mul_f32_e32 v62, v35, v45
	v_mul_f32_e32 v64, v35, v49
	v_pk_fma_f32 v[36:37], v[36:37], v[46:47], v[50:51] op_sel_hi:[1,0,1]
	v_mov_b32_e32 v46, v43
	v_pk_fma_f32 v[32:33], v[32:33], v[48:49], v[58:59] op_sel_hi:[1,0,1]
	v_mov_b32_e32 v48, v45
	v_pk_fma_f32 v[54:55], v[38:39], v[42:43], v[54:55] op_sel_hi:[1,1,0] neg_lo:[0,0,1] neg_hi:[0,0,1]
	v_pk_fma_f32 v[42:43], v[34:35], v[44:45], v[62:63] op_sel_hi:[1,1,0] neg_lo:[0,0,1] neg_hi:[0,0,1]
	v_pk_fma_f32 v[44:45], v[38:39], v[46:47], v[56:57] op_sel_hi:[1,1,0]
	v_pk_fma_f32 v[46:47], v[34:35], v[48:49], v[64:65] op_sel_hi:[1,1,0]
	v_sub_f32_e32 v36, v52, v50
	v_sub_f32_e32 v32, v60, v58
	v_mov_b32_e32 v38, v54
	v_mov_b32_e32 v34, v42
	v_mov_b32_e32 v39, v44
	v_mov_b32_e32 v35, v46
.LBB0_3715:
	s_or_b64 exec, exec, s[40:41]
	v_cvt_pk_bf16_f32 v36, v36, v37
	v_cvt_pk_bf16_f32 v37, v38, v39
	v_cvt_pk_bf16_f32 v38, v32, v33
	v_mov_b64_e32 v[32:33], s[14:15]
	v_mad_i64_i32 v[32:33], s[40:41], v40, s53, v[32:33]
	v_cvt_pk_bf16_f32 v39, v34, v35
	v_lshl_add_u64 v[32:33], v[146:147], 1, v[32:33]
	global_store_dwordx4 v[32:33], v[36:39], off offset:256
	v_add_u32_e32 v32, 0x80, v148
	v_ashrrev_i32_e32 v33, 31, v32
	s_and_saveexec_b64 s[40:41], s[30:31]
	s_cbranch_execz .LBB0_3717
	v_lshlrev_b64 v[34:35], 6, v[32:33]
	v_lshl_add_u64 v[38:39], v[136:137], 0, v[34:35]
	v_mov_b64_e32 v[34:35], v[212:213]
	v_mov_b64_e32 v[36:37], v[214:215]
	v_mov_b64_e32 v[38:39], v[216:217]
	v_mov_b64_e32 v[40:41], v[218:219]
	v_pk_mul_f32 v[42:43], v[28:29], v[34:35] op_sel:[1,0] op_sel_hi:[0,0]
	v_pk_mul_f32 v[50:51], v[24:25], v[36:37] op_sel:[1,0] op_sel_hi:[0,0]
	v_pk_mul_f32 v[44:45], v[28:29], v[38:39]
	v_mov_b32_e32 v34, v39
	v_mul_f32_e32 v46, v31, v35
	v_mul_f32_e32 v48, v31, v39
	v_pk_mul_f32 v[52:53], v[24:25], v[40:41]
	v_mov_b32_e32 v36, v41
	v_mul_f32_e32 v54, v27, v37
	v_mul_f32_e32 v56, v27, v41
	v_pk_fma_f32 v[28:29], v[28:29], v[38:39], v[42:43] op_sel_hi:[1,0,1]
	v_mov_b32_e32 v38, v35
	v_pk_fma_f32 v[24:25], v[24:25], v[40:41], v[50:51] op_sel_hi:[1,0,1]
	v_mov_b32_e32 v40, v37
	v_pk_fma_f32 v[46:47], v[30:31], v[34:35], v[46:47] op_sel_hi:[1,1,0] neg_lo:[0,0,1] neg_hi:[0,0,1]
	v_pk_fma_f32 v[34:35], v[26:27], v[36:37], v[54:55] op_sel_hi:[1,1,0] neg_lo:[0,0,1] neg_hi:[0,0,1]
	v_pk_fma_f32 v[36:37], v[30:31], v[38:39], v[48:49] op_sel_hi:[1,1,0]
	v_pk_fma_f32 v[38:39], v[26:27], v[40:41], v[56:57] op_sel_hi:[1,1,0]
	v_sub_f32_e32 v28, v44, v42
	v_sub_f32_e32 v24, v52, v50
	v_mov_b32_e32 v30, v46
	v_mov_b32_e32 v26, v34
	v_mov_b32_e32 v31, v36
	v_mov_b32_e32 v27, v38
.LBB0_3717:
	s_or_b64 exec, exec, s[40:41]
	v_cvt_pk_bf16_f32 v28, v28, v29
	v_cvt_pk_bf16_f32 v29, v30, v31
	v_cvt_pk_bf16_f32 v30, v24, v25
	v_mov_b64_e32 v[24:25], s[14:15]
	v_mad_i64_i32 v[24:25], s[40:41], v32, s53, v[24:25]
	v_cvt_pk_bf16_f32 v31, v26, v27
	v_lshl_add_u64 v[24:25], v[146:147], 1, v[24:25]
	global_store_dwordx4 v[24:25], v[28:31], off offset:256
	v_add_u32_e32 v24, 0x90, v148
	v_ashrrev_i32_e32 v25, 31, v24
	s_and_saveexec_b64 s[40:41], s[30:31]
	s_cbranch_execz .LBB0_3719
	v_lshlrev_b64 v[26:27], 6, v[24:25]
	v_lshl_add_u64 v[30:31], v[136:137], 0, v[26:27]
	v_mov_b64_e32 v[26:27], v[220:221]
	v_mov_b64_e32 v[28:29], v[222:223]
	v_mov_b64_e32 v[30:31], v[224:225]
	v_mov_b64_e32 v[32:33], v[226:227]
	v_pk_mul_f32 v[34:35], v[20:21], v[26:27] op_sel:[1,0] op_sel_hi:[0,0]
	v_pk_mul_f32 v[42:43], v[16:17], v[28:29] op_sel:[1,0] op_sel_hi:[0,0]
	v_pk_mul_f32 v[36:37], v[20:21], v[30:31]
	v_mov_b32_e32 v26, v31
	v_mul_f32_e32 v38, v23, v27
	v_mul_f32_e32 v40, v23, v31
	v_pk_mul_f32 v[44:45], v[16:17], v[32:33]
	v_mov_b32_e32 v28, v33
	v_mul_f32_e32 v46, v19, v29
	v_mul_f32_e32 v48, v19, v33
	v_pk_fma_f32 v[20:21], v[20:21], v[30:31], v[34:35] op_sel_hi:[1,0,1]
	v_mov_b32_e32 v30, v27
	v_pk_fma_f32 v[16:17], v[16:17], v[32:33], v[42:43] op_sel_hi:[1,0,1]
	v_mov_b32_e32 v32, v29
	v_pk_fma_f32 v[38:39], v[22:23], v[26:27], v[38:39] op_sel_hi:[1,1,0] neg_lo:[0,0,1] neg_hi:[0,0,1]
	v_pk_fma_f32 v[26:27], v[18:19], v[28:29], v[46:47] op_sel_hi:[1,1,0] neg_lo:[0,0,1] neg_hi:[0,0,1]
	v_pk_fma_f32 v[28:29], v[22:23], v[30:31], v[40:41] op_sel_hi:[1,1,0]
	v_pk_fma_f32 v[30:31], v[18:19], v[32:33], v[48:49] op_sel_hi:[1,1,0]
	v_sub_f32_e32 v20, v36, v34
	v_sub_f32_e32 v16, v44, v42
	v_mov_b32_e32 v22, v38
	v_mov_b32_e32 v18, v26
	v_mov_b32_e32 v23, v28
	v_mov_b32_e32 v19, v30
.LBB0_3719:
	s_or_b64 exec, exec, s[40:41]
	v_cvt_pk_bf16_f32 v20, v20, v21
	v_cvt_pk_bf16_f32 v21, v22, v23
	v_cvt_pk_bf16_f32 v22, v16, v17
	v_mov_b64_e32 v[16:17], s[14:15]
	v_mad_i64_i32 v[16:17], s[40:41], v24, s53, v[16:17]
	v_cvt_pk_bf16_f32 v23, v18, v19
	v_lshl_add_u64 v[16:17], v[146:147], 1, v[16:17]
	global_store_dwordx4 v[16:17], v[20:23], off offset:256
	v_add_u32_e32 v16, 0xa0, v148
	v_ashrrev_i32_e32 v17, 31, v16
	s_and_saveexec_b64 s[40:41], s[30:31]
	s_cbranch_execz .LBB0_3721
	v_lshlrev_b64 v[18:19], 6, v[16:17]
	v_lshl_add_u64 v[22:23], v[136:137], 0, v[18:19]
	v_mov_b64_e32 v[18:19], v[228:229]
	v_mov_b64_e32 v[20:21], v[230:231]
	v_mov_b64_e32 v[22:23], v[232:233]
	v_mov_b64_e32 v[24:25], v[234:235]
	v_pk_mul_f32 v[26:27], v[12:13], v[18:19] op_sel:[1,0] op_sel_hi:[0,0]
	v_pk_mul_f32 v[34:35], v[8:9], v[20:21] op_sel:[1,0] op_sel_hi:[0,0]
	v_pk_mul_f32 v[28:29], v[12:13], v[22:23]
	v_mov_b32_e32 v18, v23
	v_mul_f32_e32 v30, v15, v19
	v_mul_f32_e32 v32, v15, v23
	v_pk_mul_f32 v[36:37], v[8:9], v[24:25]
	v_mov_b32_e32 v20, v25
	v_mul_f32_e32 v38, v11, v21
	v_mul_f32_e32 v40, v11, v25
	v_pk_fma_f32 v[12:13], v[12:13], v[22:23], v[26:27] op_sel_hi:[1,0,1]
	v_mov_b32_e32 v22, v19
	v_pk_fma_f32 v[8:9], v[8:9], v[24:25], v[34:35] op_sel_hi:[1,0,1]
	v_mov_b32_e32 v24, v21
	v_pk_fma_f32 v[30:31], v[14:15], v[18:19], v[30:31] op_sel_hi:[1,1,0] neg_lo:[0,0,1] neg_hi:[0,0,1]
	v_pk_fma_f32 v[18:19], v[10:11], v[20:21], v[38:39] op_sel_hi:[1,1,0] neg_lo:[0,0,1] neg_hi:[0,0,1]
	v_pk_fma_f32 v[20:21], v[14:15], v[22:23], v[32:33] op_sel_hi:[1,1,0]
	v_pk_fma_f32 v[22:23], v[10:11], v[24:25], v[40:41] op_sel_hi:[1,1,0]
	v_sub_f32_e32 v12, v28, v26
	v_sub_f32_e32 v8, v36, v34
	v_mov_b32_e32 v14, v30
	v_mov_b32_e32 v10, v18
	v_mov_b32_e32 v15, v20
	v_mov_b32_e32 v11, v22
.LBB0_3721:
	s_or_b64 exec, exec, s[40:41]
	v_cvt_pk_bf16_f32 v12, v12, v13
	v_cvt_pk_bf16_f32 v13, v14, v15
	v_cvt_pk_bf16_f32 v14, v8, v9
	v_mov_b64_e32 v[8:9], s[14:15]
	v_mad_i64_i32 v[8:9], s[40:41], v16, s53, v[8:9]
	v_cvt_pk_bf16_f32 v15, v10, v11
	v_lshl_add_u64 v[8:9], v[146:147], 1, v[8:9]
	global_store_dwordx4 v[8:9], v[12:15], off offset:256
	v_add_u32_e32 v8, 0xb0, v148
	v_ashrrev_i32_e32 v9, 31, v8
	s_and_saveexec_b64 s[40:41], s[30:31]
	s_cbranch_execz .LBB0_3723
	v_lshlrev_b64 v[10:11], 6, v[8:9]
	v_lshl_add_u64 v[14:15], v[136:137], 0, v[10:11]
	v_mov_b64_e32 v[10:11], v[240:241]
	v_mov_b64_e32 v[12:13], v[242:243]
	v_mov_b64_e32 v[14:15], v[244:245]
	v_mov_b64_e32 v[16:17], v[246:247]
	v_pk_mul_f32 v[18:19], v[4:5], v[10:11] op_sel:[1,0] op_sel_hi:[0,0]
	v_pk_mul_f32 v[26:27], v[0:1], v[12:13] op_sel:[1,0] op_sel_hi:[0,0]
	v_pk_mul_f32 v[20:21], v[4:5], v[14:15]
	v_mov_b32_e32 v10, v15
	v_mul_f32_e32 v22, v7, v11
	v_mul_f32_e32 v24, v7, v15
	v_pk_mul_f32 v[28:29], v[0:1], v[16:17]
	v_mov_b32_e32 v12, v17
	v_mul_f32_e32 v30, v3, v13
	v_mul_f32_e32 v32, v3, v17
	v_pk_fma_f32 v[4:5], v[4:5], v[14:15], v[18:19] op_sel_hi:[1,0,1]
	v_mov_b32_e32 v14, v11
	v_pk_fma_f32 v[0:1], v[0:1], v[16:17], v[26:27] op_sel_hi:[1,0,1]
	v_mov_b32_e32 v16, v13
	v_pk_fma_f32 v[22:23], v[6:7], v[10:11], v[22:23] op_sel_hi:[1,1,0] neg_lo:[0,0,1] neg_hi:[0,0,1]
	v_pk_fma_f32 v[10:11], v[2:3], v[12:13], v[30:31] op_sel_hi:[1,1,0] neg_lo:[0,0,1] neg_hi:[0,0,1]
	v_pk_fma_f32 v[12:13], v[6:7], v[14:15], v[24:25] op_sel_hi:[1,1,0]
	v_pk_fma_f32 v[14:15], v[2:3], v[16:17], v[32:33] op_sel_hi:[1,1,0]
	v_sub_f32_e32 v4, v20, v18
	v_sub_f32_e32 v0, v28, v26
	v_mov_b32_e32 v6, v22
	v_mov_b32_e32 v2, v10
	v_mov_b32_e32 v7, v12
	v_mov_b32_e32 v3, v14
